# RWKV scanner: in the last layer (ctx_out false) the 16 context chunks only carry the state - their unused y mat-vecs and stores are skipped
# speedup vs baseline: 1.1497x; 1.0027x over previous
; __device__ void scan_chain(PRef p, int l, int chain, ScanSm* sm) {
;     ...
; #pragma unroll 1
;     for (int c = 0; c < 144; c++) {
;       __syncthreads();
;       const ScanRec* rc0 = &sm->rec[c & 1][0];
;       LDSET(A, rc0)
; #pragma unroll 1
;       for (int i2 = 0; i2 < 8; i2++) {
;         const ScanRec* rcA = rc0 + 2 * i2;
;         const ScanRec* rcC = (i2 < 7) ? rcA + 2 : rcA + 1;
;         LDSET(B, rcA + 1)
;         SCAN_STEP(A, c * 16 + 2 * i2)
;         LDSET(A, rcC)
;         SCAN_STEP(B, c * 16 + 2 * i2 + 1)
;       }
;     }
.Lscan_rowok:
	s_waitcnt lgkmcnt(0)
	s_barrier
	ds_read2st64_b32 v[100:101], v14 offset0:1 offset1:4
	ds_read2st64_b32 v[102:103], v17 offset0:1 offset1:4
	ds_read_b32 v136, v15 offset:0
	ds_read_b32 v137, v15 offset:128
	ds_read_b32 v108, v16 offset:0
	s_cmp_lg_u32 s61, 2
	s_cbranch_scc1 .Lscan_full
	s_cmp_lt_u32 s15, 16
	s_cbranch_scc0 .Lscan_full
	s_waitcnt lgkmcnt(0)
	ds_read2st64_b32 v[104:105], v14 offset0:7 offset1:10
	ds_read2st64_b32 v[106:107], v17 offset0:7 offset1:10
	ds_read_b32 v138, v15 offset:1536
	ds_read_b32 v139, v15 offset:1664
	ds_read_b32 v109, v16 offset:1536
	v_mul_f32_dpp v120, v100, v32 row_newbcast:0 row_mask:0xf bank_mask:0xf
	v_mul_f32_dpp v121, v100, v33 row_newbcast:1 row_mask:0xf bank_mask:0xf
	v_fmac_f32_dpp v120, v100, v34 row_newbcast:2 row_mask:0xf bank_mask:0xf
	v_fmac_f32_dpp v121, v100, v35 row_newbcast:3 row_mask:0xf bank_mask:0xf
	v_fmac_f32_dpp v120, v100, v36 row_newbcast:4 row_mask:0xf bank_mask:0xf
	v_fmac_f32_dpp v121, v100, v37 row_newbcast:5 row_mask:0xf bank_mask:0xf
	v_fmac_f32_dpp v120, v100, v38 row_newbcast:6 row_mask:0xf bank_mask:0xf
	v_fmac_f32_dpp v121, v100, v39 row_newbcast:7 row_mask:0xf bank_mask:0xf
	v_fmac_f32_dpp v120, v100, v40 row_newbcast:8 row_mask:0xf bank_mask:0xf
	v_fmac_f32_dpp v121, v100, v41 row_newbcast:9 row_mask:0xf bank_mask:0xf
	v_fmac_f32_dpp v120, v100, v42 row_newbcast:10 row_mask:0xf bank_mask:0xf
	v_fmac_f32_dpp v121, v100, v43 row_newbcast:11 row_mask:0xf bank_mask:0xf
	v_fmac_f32_dpp v120, v100, v44 row_newbcast:12 row_mask:0xf bank_mask:0xf
	v_fmac_f32_dpp v121, v100, v45 row_newbcast:13 row_mask:0xf bank_mask:0xf
	v_fmac_f32_dpp v120, v100, v46 row_newbcast:14 row_mask:0xf bank_mask:0xf
	v_fmac_f32_dpp v121, v100, v47 row_newbcast:15 row_mask:0xf bank_mask:0xf
	v_fmac_f32_dpp v120, v102, v48 row_newbcast:0 row_mask:0xf bank_mask:0xf
	v_fmac_f32_dpp v121, v102, v49 row_newbcast:1 row_mask:0xf bank_mask:0xf
	v_fmac_f32_dpp v120, v102, v50 row_newbcast:2 row_mask:0xf bank_mask:0xf
	v_fmac_f32_dpp v121, v102, v51 row_newbcast:3 row_mask:0xf bank_mask:0xf
	v_fmac_f32_dpp v120, v102, v52 row_newbcast:4 row_mask:0xf bank_mask:0xf
	v_fmac_f32_dpp v121, v102, v53 row_newbcast:5 row_mask:0xf bank_mask:0xf
	v_fmac_f32_dpp v120, v102, v54 row_newbcast:6 row_mask:0xf bank_mask:0xf
	v_fmac_f32_dpp v121, v102, v55 row_newbcast:7 row_mask:0xf bank_mask:0xf
	v_fmac_f32_dpp v120, v102, v56 row_newbcast:8 row_mask:0xf bank_mask:0xf
	v_fmac_f32_dpp v121, v102, v57 row_newbcast:9 row_mask:0xf bank_mask:0xf
	v_fmac_f32_dpp v120, v102, v58 row_newbcast:10 row_mask:0xf bank_mask:0xf
	v_fmac_f32_dpp v121, v102, v59 row_newbcast:11 row_mask:0xf bank_mask:0xf
	v_fmac_f32_dpp v120, v102, v60 row_newbcast:12 row_mask:0xf bank_mask:0xf
	v_fmac_f32_dpp v121, v102, v61 row_newbcast:13 row_mask:0xf bank_mask:0xf
	v_fmac_f32_dpp v120, v102, v62 row_newbcast:14 row_mask:0xf bank_mask:0xf
	v_fmac_f32_dpp v121, v102, v63 row_newbcast:15 row_mask:0xf bank_mask:0xf
	v_add_f32_e32 v128, v120, v121
	s_nop 1
	v_permlane32_swap_b32 v129, v128
	s_nop 1
	v_add_f32_dpp v108, -v129, -v128 quad_perm:[0,1,2,3] row_mask:0xc bank_mask:0xf
	s_nop 1
	v_mfma_f32_32x32x2_f32 v[64:79], v136, v108, v[32:47]
	s_nop 15
	v_mfma_f32_32x32x2_f32 v[80:95], v137, v108, v[48:63]
	s_nop 7
	s_waitcnt lgkmcnt(0)
	ds_read2st64_b32 v[110:111], v14 offset0:13 offset1:16
	ds_read2st64_b32 v[112:113], v17 offset0:13 offset1:16
	ds_read_b32 v136, v15 offset:3072
	ds_read_b32 v137, v15 offset:3200
	ds_read_b32 v108, v16 offset:3072
	v_mul_f32_dpp v120, v104, v64 row_newbcast:0 row_mask:0xf bank_mask:0xf
	v_mul_f32_dpp v121, v104, v65 row_newbcast:1 row_mask:0xf bank_mask:0xf
	v_fmac_f32_dpp v120, v104, v66 row_newbcast:2 row_mask:0xf bank_mask:0xf
	v_fmac_f32_dpp v121, v104, v67 row_newbcast:3 row_mask:0xf bank_mask:0xf
	v_fmac_f32_dpp v120, v104, v68 row_newbcast:4 row_mask:0xf bank_mask:0xf
	v_fmac_f32_dpp v121, v104, v69 row_newbcast:5 row_mask:0xf bank_mask:0xf
	v_fmac_f32_dpp v120, v104, v70 row_newbcast:6 row_mask:0xf bank_mask:0xf
	v_fmac_f32_dpp v121, v104, v71 row_newbcast:7 row_mask:0xf bank_mask:0xf
	v_fmac_f32_dpp v120, v104, v72 row_newbcast:8 row_mask:0xf bank_mask:0xf
	v_fmac_f32_dpp v121, v104, v73 row_newbcast:9 row_mask:0xf bank_mask:0xf
	v_fmac_f32_dpp v120, v104, v74 row_newbcast:10 row_mask:0xf bank_mask:0xf
	v_fmac_f32_dpp v121, v104, v75 row_newbcast:11 row_mask:0xf bank_mask:0xf
	v_fmac_f32_dpp v120, v104, v76 row_newbcast:12 row_mask:0xf bank_mask:0xf
	v_fmac_f32_dpp v121, v104, v77 row_newbcast:13 row_mask:0xf bank_mask:0xf
	v_fmac_f32_dpp v120, v104, v78 row_newbcast:14 row_mask:0xf bank_mask:0xf
	v_fmac_f32_dpp v121, v104, v79 row_newbcast:15 row_mask:0xf bank_mask:0xf
	v_fmac_f32_dpp v120, v106, v80 row_newbcast:0 row_mask:0xf bank_mask:0xf
	v_fmac_f32_dpp v121, v106, v81 row_newbcast:1 row_mask:0xf bank_mask:0xf
	v_fmac_f32_dpp v120, v106, v82 row_newbcast:2 row_mask:0xf bank_mask:0xf
	v_fmac_f32_dpp v121, v106, v83 row_newbcast:3 row_mask:0xf bank_mask:0xf
	v_fmac_f32_dpp v120, v106, v84 row_newbcast:4 row_mask:0xf bank_mask:0xf
	v_fmac_f32_dpp v121, v106, v85 row_newbcast:5 row_mask:0xf bank_mask:0xf
	v_fmac_f32_dpp v120, v106, v86 row_newbcast:6 row_mask:0xf bank_mask:0xf
	v_fmac_f32_dpp v121, v106, v87 row_newbcast:7 row_mask:0xf bank_mask:0xf
	v_fmac_f32_dpp v120, v106, v88 row_newbcast:8 row_mask:0xf bank_mask:0xf
	v_fmac_f32_dpp v121, v106, v89 row_newbcast:9 row_mask:0xf bank_mask:0xf
	v_fmac_f32_dpp v120, v106, v90 row_newbcast:10 row_mask:0xf bank_mask:0xf
	v_fmac_f32_dpp v121, v106, v91 row_newbcast:11 row_mask:0xf bank_mask:0xf
	v_fmac_f32_dpp v120, v106, v92 row_newbcast:12 row_mask:0xf bank_mask:0xf
	v_fmac_f32_dpp v121, v106, v93 row_newbcast:13 row_mask:0xf bank_mask:0xf
	v_fmac_f32_dpp v120, v106, v94 row_newbcast:14 row_mask:0xf bank_mask:0xf
	v_fmac_f32_dpp v121, v106, v95 row_newbcast:15 row_mask:0xf bank_mask:0xf
	v_add_f32_e32 v128, v120, v121
	s_nop 1
	v_permlane32_swap_b32 v129, v128
	s_nop 1
	v_add_f32_dpp v109, -v129, -v128 quad_perm:[0,1,2,3] row_mask:0xc bank_mask:0xf
	s_nop 1
	v_mfma_f32_32x32x2_f32 v[32:47], v138, v109, v[64:79]
	s_nop 15
	v_mfma_f32_32x32x2_f32 v[48:63], v139, v109, v[80:95]
	s_nop 7
	s_waitcnt lgkmcnt(0)
	ds_read2st64_b32 v[114:115], v14 offset0:19 offset1:22
	ds_read2st64_b32 v[116:117], v17 offset0:19 offset1:22
	ds_read_b32 v138, v15 offset:4608
	ds_read_b32 v139, v15 offset:4736
	ds_read_b32 v109, v16 offset:4608
	v_mul_f32_dpp v120, v110, v32 row_newbcast:0 row_mask:0xf bank_mask:0xf
	v_mul_f32_dpp v121, v110, v33 row_newbcast:1 row_mask:0xf bank_mask:0xf
	v_fmac_f32_dpp v120, v110, v34 row_newbcast:2 row_mask:0xf bank_mask:0xf
	v_fmac_f32_dpp v121, v110, v35 row_newbcast:3 row_mask:0xf bank_mask:0xf
	v_fmac_f32_dpp v120, v110, v36 row_newbcast:4 row_mask:0xf bank_mask:0xf
	v_fmac_f32_dpp v121, v110, v37 row_newbcast:5 row_mask:0xf bank_mask:0xf
	v_fmac_f32_dpp v120, v110, v38 row_newbcast:6 row_mask:0xf bank_mask:0xf
	v_fmac_f32_dpp v121, v110, v39 row_newbcast:7 row_mask:0xf bank_mask:0xf
	v_fmac_f32_dpp v120, v110, v40 row_newbcast:8 row_mask:0xf bank_mask:0xf
	v_fmac_f32_dpp v121, v110, v41 row_newbcast:9 row_mask:0xf bank_mask:0xf
	v_fmac_f32_dpp v120, v110, v42 row_newbcast:10 row_mask:0xf bank_mask:0xf
	v_fmac_f32_dpp v121, v110, v43 row_newbcast:11 row_mask:0xf bank_mask:0xf
	v_fmac_f32_dpp v120, v110, v44 row_newbcast:12 row_mask:0xf bank_mask:0xf
	v_fmac_f32_dpp v121, v110, v45 row_newbcast:13 row_mask:0xf bank_mask:0xf
	v_fmac_f32_dpp v120, v110, v46 row_newbcast:14 row_mask:0xf bank_mask:0xf
	v_fmac_f32_dpp v121, v110, v47 row_newbcast:15 row_mask:0xf bank_mask:0xf
	v_fmac_f32_dpp v120, v112, v48 row_newbcast:0 row_mask:0xf bank_mask:0xf
	v_fmac_f32_dpp v121, v112, v49 row_newbcast:1 row_mask:0xf bank_mask:0xf
	v_fmac_f32_dpp v120, v112, v50 row_newbcast:2 row_mask:0xf bank_mask:0xf
	v_fmac_f32_dpp v121, v112, v51 row_newbcast:3 row_mask:0xf bank_mask:0xf
	v_fmac_f32_dpp v120, v112, v52 row_newbcast:4 row_mask:0xf bank_mask:0xf
	v_fmac_f32_dpp v121, v112, v53 row_newbcast:5 row_mask:0xf bank_mask:0xf
	v_fmac_f32_dpp v120, v112, v54 row_newbcast:6 row_mask:0xf bank_mask:0xf
	v_fmac_f32_dpp v121, v112, v55 row_newbcast:7 row_mask:0xf bank_mask:0xf
	v_fmac_f32_dpp v120, v112, v56 row_newbcast:8 row_mask:0xf bank_mask:0xf
	v_fmac_f32_dpp v121, v112, v57 row_newbcast:9 row_mask:0xf bank_mask:0xf
	v_fmac_f32_dpp v120, v112, v58 row_newbcast:10 row_mask:0xf bank_mask:0xf
	v_fmac_f32_dpp v121, v112, v59 row_newbcast:11 row_mask:0xf bank_mask:0xf
	v_fmac_f32_dpp v120, v112, v60 row_newbcast:12 row_mask:0xf bank_mask:0xf
	v_fmac_f32_dpp v121, v112, v61 row_newbcast:13 row_mask:0xf bank_mask:0xf
	v_fmac_f32_dpp v120, v112, v62 row_newbcast:14 row_mask:0xf bank_mask:0xf
	v_fmac_f32_dpp v121, v112, v63 row_newbcast:15 row_mask:0xf bank_mask:0xf
	v_add_f32_e32 v128, v120, v121
	s_nop 1
	v_permlane32_swap_b32 v129, v128
	s_nop 1
	v_add_f32_dpp v108, -v129, -v128 quad_perm:[0,1,2,3] row_mask:0xc bank_mask:0xf
	s_nop 1
	v_mfma_f32_32x32x2_f32 v[64:79], v136, v108, v[32:47]
	s_nop 15
	v_mfma_f32_32x32x2_f32 v[80:95], v137, v108, v[48:63]
	s_nop 7
	s_waitcnt lgkmcnt(0)
	ds_read2st64_b32 v[100:101], v14 offset0:25 offset1:28
	ds_read2st64_b32 v[102:103], v17 offset0:25 offset1:28
	ds_read_b32 v136, v15 offset:6144
	ds_read_b32 v137, v15 offset:6272
	ds_read_b32 v108, v16 offset:6144
	v_mul_f32_dpp v120, v114, v64 row_newbcast:0 row_mask:0xf bank_mask:0xf
	v_mul_f32_dpp v121, v114, v65 row_newbcast:1 row_mask:0xf bank_mask:0xf
	v_fmac_f32_dpp v120, v114, v66 row_newbcast:2 row_mask:0xf bank_mask:0xf
	v_fmac_f32_dpp v121, v114, v67 row_newbcast:3 row_mask:0xf bank_mask:0xf
	v_fmac_f32_dpp v120, v114, v68 row_newbcast:4 row_mask:0xf bank_mask:0xf
	v_fmac_f32_dpp v121, v114, v69 row_newbcast:5 row_mask:0xf bank_mask:0xf
	v_fmac_f32_dpp v120, v114, v70 row_newbcast:6 row_mask:0xf bank_mask:0xf
	v_fmac_f32_dpp v121, v114, v71 row_newbcast:7 row_mask:0xf bank_mask:0xf
	v_fmac_f32_dpp v120, v114, v72 row_newbcast:8 row_mask:0xf bank_mask:0xf
	v_fmac_f32_dpp v121, v114, v73 row_newbcast:9 row_mask:0xf bank_mask:0xf
	v_fmac_f32_dpp v120, v114, v74 row_newbcast:10 row_mask:0xf bank_mask:0xf
	v_fmac_f32_dpp v121, v114, v75 row_newbcast:11 row_mask:0xf bank_mask:0xf
	v_fmac_f32_dpp v120, v114, v76 row_newbcast:12 row_mask:0xf bank_mask:0xf
	v_fmac_f32_dpp v121, v114, v77 row_newbcast:13 row_mask:0xf bank_mask:0xf
	v_fmac_f32_dpp v120, v114, v78 row_newbcast:14 row_mask:0xf bank_mask:0xf
	v_fmac_f32_dpp v121, v114, v79 row_newbcast:15 row_mask:0xf bank_mask:0xf
	v_fmac_f32_dpp v120, v116, v80 row_newbcast:0 row_mask:0xf bank_mask:0xf
	v_fmac_f32_dpp v121, v116, v81 row_newbcast:1 row_mask:0xf bank_mask:0xf
	v_fmac_f32_dpp v120, v116, v82 row_newbcast:2 row_mask:0xf bank_mask:0xf
	v_fmac_f32_dpp v121, v116, v83 row_newbcast:3 row_mask:0xf bank_mask:0xf
	v_fmac_f32_dpp v120, v116, v84 row_newbcast:4 row_mask:0xf bank_mask:0xf
	v_fmac_f32_dpp v121, v116, v85 row_newbcast:5 row_mask:0xf bank_mask:0xf
	v_fmac_f32_dpp v120, v116, v86 row_newbcast:6 row_mask:0xf bank_mask:0xf
	v_fmac_f32_dpp v121, v116, v87 row_newbcast:7 row_mask:0xf bank_mask:0xf
	v_fmac_f32_dpp v120, v116, v88 row_newbcast:8 row_mask:0xf bank_mask:0xf
	v_fmac_f32_dpp v121, v116, v89 row_newbcast:9 row_mask:0xf bank_mask:0xf
	v_fmac_f32_dpp v120, v116, v90 row_newbcast:10 row_mask:0xf bank_mask:0xf
	v_fmac_f32_dpp v121, v116, v91 row_newbcast:11 row_mask:0xf bank_mask:0xf
	v_fmac_f32_dpp v120, v116, v92 row_newbcast:12 row_mask:0xf bank_mask:0xf
	v_fmac_f32_dpp v121, v116, v93 row_newbcast:13 row_mask:0xf bank_mask:0xf
	v_fmac_f32_dpp v120, v116, v94 row_newbcast:14 row_mask:0xf bank_mask:0xf
	v_fmac_f32_dpp v121, v116, v95 row_newbcast:15 row_mask:0xf bank_mask:0xf
	v_add_f32_e32 v128, v120, v121
	s_nop 1
	v_permlane32_swap_b32 v129, v128
	s_nop 1
	v_add_f32_dpp v109, -v129, -v128 quad_perm:[0,1,2,3] row_mask:0xc bank_mask:0xf
	s_nop 1
	v_mfma_f32_32x32x2_f32 v[32:47], v138, v109, v[64:79]
	s_nop 15
	v_mfma_f32_32x32x2_f32 v[48:63], v139, v109, v[80:95]
	s_nop 7
	s_waitcnt lgkmcnt(0)
	ds_read2st64_b32 v[104:105], v14 offset0:31 offset1:34
	ds_read2st64_b32 v[106:107], v17 offset0:31 offset1:34
	ds_read_b32 v138, v15 offset:7680
	ds_read_b32 v139, v15 offset:7808
	ds_read_b32 v109, v16 offset:7680
	v_mul_f32_dpp v120, v100, v32 row_newbcast:0 row_mask:0xf bank_mask:0xf
	v_mul_f32_dpp v121, v100, v33 row_newbcast:1 row_mask:0xf bank_mask:0xf
	v_fmac_f32_dpp v120, v100, v34 row_newbcast:2 row_mask:0xf bank_mask:0xf
	v_fmac_f32_dpp v121, v100, v35 row_newbcast:3 row_mask:0xf bank_mask:0xf
	v_fmac_f32_dpp v120, v100, v36 row_newbcast:4 row_mask:0xf bank_mask:0xf
	v_fmac_f32_dpp v121, v100, v37 row_newbcast:5 row_mask:0xf bank_mask:0xf
	v_fmac_f32_dpp v120, v100, v38 row_newbcast:6 row_mask:0xf bank_mask:0xf
	v_fmac_f32_dpp v121, v100, v39 row_newbcast:7 row_mask:0xf bank_mask:0xf
	v_fmac_f32_dpp v120, v100, v40 row_newbcast:8 row_mask:0xf bank_mask:0xf
	v_fmac_f32_dpp v121, v100, v41 row_newbcast:9 row_mask:0xf bank_mask:0xf
	v_fmac_f32_dpp v120, v100, v42 row_newbcast:10 row_mask:0xf bank_mask:0xf
	v_fmac_f32_dpp v121, v100, v43 row_newbcast:11 row_mask:0xf bank_mask:0xf
	v_fmac_f32_dpp v120, v100, v44 row_newbcast:12 row_mask:0xf bank_mask:0xf
	v_fmac_f32_dpp v121, v100, v45 row_newbcast:13 row_mask:0xf bank_mask:0xf
	v_fmac_f32_dpp v120, v100, v46 row_newbcast:14 row_mask:0xf bank_mask:0xf
	v_fmac_f32_dpp v121, v100, v47 row_newbcast:15 row_mask:0xf bank_mask:0xf
	v_fmac_f32_dpp v120, v102, v48 row_newbcast:0 row_mask:0xf bank_mask:0xf
	v_fmac_f32_dpp v121, v102, v49 row_newbcast:1 row_mask:0xf bank_mask:0xf
	v_fmac_f32_dpp v120, v102, v50 row_newbcast:2 row_mask:0xf bank_mask:0xf
	v_fmac_f32_dpp v121, v102, v51 row_newbcast:3 row_mask:0xf bank_mask:0xf
	v_fmac_f32_dpp v120, v102, v52 row_newbcast:4 row_mask:0xf bank_mask:0xf
	v_fmac_f32_dpp v121, v102, v53 row_newbcast:5 row_mask:0xf bank_mask:0xf
	v_fmac_f32_dpp v120, v102, v54 row_newbcast:6 row_mask:0xf bank_mask:0xf
	v_fmac_f32_dpp v121, v102, v55 row_newbcast:7 row_mask:0xf bank_mask:0xf
	v_fmac_f32_dpp v120, v102, v56 row_newbcast:8 row_mask:0xf bank_mask:0xf
	v_fmac_f32_dpp v121, v102, v57 row_newbcast:9 row_mask:0xf bank_mask:0xf
	v_fmac_f32_dpp v120, v102, v58 row_newbcast:10 row_mask:0xf bank_mask:0xf
	v_fmac_f32_dpp v121, v102, v59 row_newbcast:11 row_mask:0xf bank_mask:0xf
	v_fmac_f32_dpp v120, v102, v60 row_newbcast:12 row_mask:0xf bank_mask:0xf
	v_fmac_f32_dpp v121, v102, v61 row_newbcast:13 row_mask:0xf bank_mask:0xf
	v_fmac_f32_dpp v120, v102, v62 row_newbcast:14 row_mask:0xf bank_mask:0xf
	v_fmac_f32_dpp v121, v102, v63 row_newbcast:15 row_mask:0xf bank_mask:0xf
	v_add_f32_e32 v128, v120, v121
	s_nop 1
	v_permlane32_swap_b32 v129, v128
	s_nop 1
	v_add_f32_dpp v108, -v129, -v128 quad_perm:[0,1,2,3] row_mask:0xc bank_mask:0xf
	s_nop 1
	v_mfma_f32_32x32x2_f32 v[64:79], v136, v108, v[32:47]
	s_nop 15
	v_mfma_f32_32x32x2_f32 v[80:95], v137, v108, v[48:63]
	s_nop 7
	s_waitcnt lgkmcnt(0)
	ds_read2st64_b32 v[110:111], v14 offset0:37 offset1:40
	ds_read2st64_b32 v[112:113], v17 offset0:37 offset1:40
	ds_read_b32 v136, v15 offset:9216
	ds_read_b32 v137, v15 offset:9344
	ds_read_b32 v108, v16 offset:9216
	v_mul_f32_dpp v120, v104, v64 row_newbcast:0 row_mask:0xf bank_mask:0xf
	v_mul_f32_dpp v121, v104, v65 row_newbcast:1 row_mask:0xf bank_mask:0xf
	v_fmac_f32_dpp v120, v104, v66 row_newbcast:2 row_mask:0xf bank_mask:0xf
	v_fmac_f32_dpp v121, v104, v67 row_newbcast:3 row_mask:0xf bank_mask:0xf
	v_fmac_f32_dpp v120, v104, v68 row_newbcast:4 row_mask:0xf bank_mask:0xf
	v_fmac_f32_dpp v121, v104, v69 row_newbcast:5 row_mask:0xf bank_mask:0xf
	v_fmac_f32_dpp v120, v104, v70 row_newbcast:6 row_mask:0xf bank_mask:0xf
	v_fmac_f32_dpp v121, v104, v71 row_newbcast:7 row_mask:0xf bank_mask:0xf
	v_fmac_f32_dpp v120, v104, v72 row_newbcast:8 row_mask:0xf bank_mask:0xf
	v_fmac_f32_dpp v121, v104, v73 row_newbcast:9 row_mask:0xf bank_mask:0xf
	v_fmac_f32_dpp v120, v104, v74 row_newbcast:10 row_mask:0xf bank_mask:0xf
	v_fmac_f32_dpp v121, v104, v75 row_newbcast:11 row_mask:0xf bank_mask:0xf
	v_fmac_f32_dpp v120, v104, v76 row_newbcast:12 row_mask:0xf bank_mask:0xf
	v_fmac_f32_dpp v121, v104, v77 row_newbcast:13 row_mask:0xf bank_mask:0xf
	v_fmac_f32_dpp v120, v104, v78 row_newbcast:14 row_mask:0xf bank_mask:0xf
	v_fmac_f32_dpp v121, v104, v79 row_newbcast:15 row_mask:0xf bank_mask:0xf
	v_fmac_f32_dpp v120, v106, v80 row_newbcast:0 row_mask:0xf bank_mask:0xf
	v_fmac_f32_dpp v121, v106, v81 row_newbcast:1 row_mask:0xf bank_mask:0xf
	v_fmac_f32_dpp v120, v106, v82 row_newbcast:2 row_mask:0xf bank_mask:0xf
	v_fmac_f32_dpp v121, v106, v83 row_newbcast:3 row_mask:0xf bank_mask:0xf
	v_fmac_f32_dpp v120, v106, v84 row_newbcast:4 row_mask:0xf bank_mask:0xf
	v_fmac_f32_dpp v121, v106, v85 row_newbcast:5 row_mask:0xf bank_mask:0xf
	v_fmac_f32_dpp v120, v106, v86 row_newbcast:6 row_mask:0xf bank_mask:0xf
	v_fmac_f32_dpp v121, v106, v87 row_newbcast:7 row_mask:0xf bank_mask:0xf
	v_fmac_f32_dpp v120, v106, v88 row_newbcast:8 row_mask:0xf bank_mask:0xf
	v_fmac_f32_dpp v121, v106, v89 row_newbcast:9 row_mask:0xf bank_mask:0xf
	v_fmac_f32_dpp v120, v106, v90 row_newbcast:10 row_mask:0xf bank_mask:0xf
	v_fmac_f32_dpp v121, v106, v91 row_newbcast:11 row_mask:0xf bank_mask:0xf
	v_fmac_f32_dpp v120, v106, v92 row_newbcast:12 row_mask:0xf bank_mask:0xf
	v_fmac_f32_dpp v121, v106, v93 row_newbcast:13 row_mask:0xf bank_mask:0xf
	v_fmac_f32_dpp v120, v106, v94 row_newbcast:14 row_mask:0xf bank_mask:0xf
	v_fmac_f32_dpp v121, v106, v95 row_newbcast:15 row_mask:0xf bank_mask:0xf
	v_add_f32_e32 v128, v120, v121
	s_nop 1
	v_permlane32_swap_b32 v129, v128
	s_nop 1
	v_add_f32_dpp v109, -v129, -v128 quad_perm:[0,1,2,3] row_mask:0xc bank_mask:0xf
	s_nop 1
	v_mfma_f32_32x32x2_f32 v[32:47], v138, v109, v[64:79]
	s_nop 15
	v_mfma_f32_32x32x2_f32 v[48:63], v139, v109, v[80:95]
	s_nop 7
	s_waitcnt lgkmcnt(0)
	ds_read2st64_b32 v[114:115], v14 offset0:43 offset1:46
	ds_read2st64_b32 v[116:117], v17 offset0:43 offset1:46
	ds_read_b32 v138, v15 offset:10752
	ds_read_b32 v139, v15 offset:10880
	ds_read_b32 v109, v16 offset:10752
	ds_read_b32 v118, v14 offset:10752
	ds_read_b32 v119, v14 offset:10880
	v_mul_f32_dpp v120, v110, v32 row_newbcast:0 row_mask:0xf bank_mask:0xf
	v_mul_f32_dpp v121, v110, v33 row_newbcast:1 row_mask:0xf bank_mask:0xf
	v_fmac_f32_dpp v120, v110, v34 row_newbcast:2 row_mask:0xf bank_mask:0xf
	v_fmac_f32_dpp v121, v110, v35 row_newbcast:3 row_mask:0xf bank_mask:0xf
	v_fmac_f32_dpp v120, v110, v36 row_newbcast:4 row_mask:0xf bank_mask:0xf
	v_fmac_f32_dpp v121, v110, v37 row_newbcast:5 row_mask:0xf bank_mask:0xf
	v_fmac_f32_dpp v120, v110, v38 row_newbcast:6 row_mask:0xf bank_mask:0xf
	v_fmac_f32_dpp v121, v110, v39 row_newbcast:7 row_mask:0xf bank_mask:0xf
	v_fmac_f32_dpp v120, v110, v40 row_newbcast:8 row_mask:0xf bank_mask:0xf
	v_fmac_f32_dpp v121, v110, v41 row_newbcast:9 row_mask:0xf bank_mask:0xf
	v_fmac_f32_dpp v120, v110, v42 row_newbcast:10 row_mask:0xf bank_mask:0xf
	v_fmac_f32_dpp v121, v110, v43 row_newbcast:11 row_mask:0xf bank_mask:0xf
	v_fmac_f32_dpp v120, v110, v44 row_newbcast:12 row_mask:0xf bank_mask:0xf
	v_fmac_f32_dpp v121, v110, v45 row_newbcast:13 row_mask:0xf bank_mask:0xf
	v_fmac_f32_dpp v120, v110, v46 row_newbcast:14 row_mask:0xf bank_mask:0xf
	v_fmac_f32_dpp v121, v110, v47 row_newbcast:15 row_mask:0xf bank_mask:0xf
	v_fmac_f32_dpp v120, v112, v48 row_newbcast:0 row_mask:0xf bank_mask:0xf
	v_fmac_f32_dpp v121, v112, v49 row_newbcast:1 row_mask:0xf bank_mask:0xf
	v_fmac_f32_dpp v120, v112, v50 row_newbcast:2 row_mask:0xf bank_mask:0xf
	v_fmac_f32_dpp v121, v112, v51 row_newbcast:3 row_mask:0xf bank_mask:0xf
	v_fmac_f32_dpp v120, v112, v52 row_newbcast:4 row_mask:0xf bank_mask:0xf
	v_fmac_f32_dpp v121, v112, v53 row_newbcast:5 row_mask:0xf bank_mask:0xf
	v_fmac_f32_dpp v120, v112, v54 row_newbcast:6 row_mask:0xf bank_mask:0xf
	v_fmac_f32_dpp v121, v112, v55 row_newbcast:7 row_mask:0xf bank_mask:0xf
	v_fmac_f32_dpp v120, v112, v56 row_newbcast:8 row_mask:0xf bank_mask:0xf
	v_fmac_f32_dpp v121, v112, v57 row_newbcast:9 row_mask:0xf bank_mask:0xf
	v_fmac_f32_dpp v120, v112, v58 row_newbcast:10 row_mask:0xf bank_mask:0xf
	v_fmac_f32_dpp v121, v112, v59 row_newbcast:11 row_mask:0xf bank_mask:0xf
	v_fmac_f32_dpp v120, v112, v60 row_newbcast:12 row_mask:0xf bank_mask:0xf
	v_fmac_f32_dpp v121, v112, v61 row_newbcast:13 row_mask:0xf bank_mask:0xf
	v_fmac_f32_dpp v120, v112, v62 row_newbcast:14 row_mask:0xf bank_mask:0xf
	v_fmac_f32_dpp v121, v112, v63 row_newbcast:15 row_mask:0xf bank_mask:0xf
	v_add_f32_e32 v128, v120, v121
	s_nop 1
	v_permlane32_swap_b32 v129, v128
	s_nop 1
	v_add_f32_dpp v108, -v129, -v128 quad_perm:[0,1,2,3] row_mask:0xc bank_mask:0xf
	s_nop 1
	v_mfma_f32_32x32x2_f32 v[64:79], v136, v108, v[32:47]
	s_nop 15
	v_mfma_f32_32x32x2_f32 v[80:95], v137, v108, v[48:63]
	s_nop 7
	s_waitcnt lgkmcnt(0)
	ds_read2st64_b32 v[100:101], v14 offset0:49 offset1:52
	ds_read2st64_b32 v[102:103], v17 offset0:49 offset1:52
	ds_read_b32 v136, v15 offset:12288
	ds_read_b32 v137, v15 offset:12416
	ds_read_b32 v108, v16 offset:12288
	v_mul_f32_dpp v120, v114, v64 row_newbcast:0 row_mask:0xf bank_mask:0xf
	v_mul_f32_dpp v121, v114, v65 row_newbcast:1 row_mask:0xf bank_mask:0xf
	v_fmac_f32_dpp v120, v114, v66 row_newbcast:2 row_mask:0xf bank_mask:0xf
	v_fmac_f32_dpp v121, v114, v67 row_newbcast:3 row_mask:0xf bank_mask:0xf
	v_fmac_f32_dpp v120, v114, v68 row_newbcast:4 row_mask:0xf bank_mask:0xf
	v_fmac_f32_dpp v121, v114, v69 row_newbcast:5 row_mask:0xf bank_mask:0xf
	v_fmac_f32_dpp v120, v114, v70 row_newbcast:6 row_mask:0xf bank_mask:0xf
	v_fmac_f32_dpp v121, v114, v71 row_newbcast:7 row_mask:0xf bank_mask:0xf
	v_fmac_f32_dpp v120, v114, v72 row_newbcast:8 row_mask:0xf bank_mask:0xf
	v_fmac_f32_dpp v121, v114, v73 row_newbcast:9 row_mask:0xf bank_mask:0xf
	v_fmac_f32_dpp v120, v114, v74 row_newbcast:10 row_mask:0xf bank_mask:0xf
	v_fmac_f32_dpp v121, v114, v75 row_newbcast:11 row_mask:0xf bank_mask:0xf
	v_fmac_f32_dpp v120, v114, v76 row_newbcast:12 row_mask:0xf bank_mask:0xf
	v_fmac_f32_dpp v121, v114, v77 row_newbcast:13 row_mask:0xf bank_mask:0xf
	v_fmac_f32_dpp v120, v114, v78 row_newbcast:14 row_mask:0xf bank_mask:0xf
	v_fmac_f32_dpp v121, v114, v79 row_newbcast:15 row_mask:0xf bank_mask:0xf
	v_fmac_f32_dpp v120, v116, v80 row_newbcast:0 row_mask:0xf bank_mask:0xf
	v_fmac_f32_dpp v121, v116, v81 row_newbcast:1 row_mask:0xf bank_mask:0xf
	v_fmac_f32_dpp v120, v116, v82 row_newbcast:2 row_mask:0xf bank_mask:0xf
	v_fmac_f32_dpp v121, v116, v83 row_newbcast:3 row_mask:0xf bank_mask:0xf
	v_fmac_f32_dpp v120, v116, v84 row_newbcast:4 row_mask:0xf bank_mask:0xf
	v_fmac_f32_dpp v121, v116, v85 row_newbcast:5 row_mask:0xf bank_mask:0xf
	v_fmac_f32_dpp v120, v116, v86 row_newbcast:6 row_mask:0xf bank_mask:0xf
	v_fmac_f32_dpp v121, v116, v87 row_newbcast:7 row_mask:0xf bank_mask:0xf
	v_fmac_f32_dpp v120, v116, v88 row_newbcast:8 row_mask:0xf bank_mask:0xf
	v_fmac_f32_dpp v121, v116, v89 row_newbcast:9 row_mask:0xf bank_mask:0xf
	v_fmac_f32_dpp v120, v116, v90 row_newbcast:10 row_mask:0xf bank_mask:0xf
	v_fmac_f32_dpp v121, v116, v91 row_newbcast:11 row_mask:0xf bank_mask:0xf
	v_fmac_f32_dpp v120, v116, v92 row_newbcast:12 row_mask:0xf bank_mask:0xf
	v_fmac_f32_dpp v121, v116, v93 row_newbcast:13 row_mask:0xf bank_mask:0xf
	v_fmac_f32_dpp v120, v116, v94 row_newbcast:14 row_mask:0xf bank_mask:0xf
	v_fmac_f32_dpp v121, v116, v95 row_newbcast:15 row_mask:0xf bank_mask:0xf
	v_add_f32_e32 v128, v120, v121
	s_nop 1
	v_permlane32_swap_b32 v129, v128
	s_nop 1
	v_add_f32_dpp v109, -v129, -v128 quad_perm:[0,1,2,3] row_mask:0xc bank_mask:0xf
	s_nop 1
	v_mfma_f32_32x32x2_f32 v[32:47], v138, v109, v[64:79]
	s_nop 15
	v_mfma_f32_32x32x2_f32 v[48:63], v139, v109, v[80:95]
	s_nop 7
	s_nop 7
	s_nop 7
	v_mul_f32_dpp v32, v118, v32 row_newbcast:0 row_mask:0xf bank_mask:0xf
	v_mul_f32_dpp v33, v118, v33 row_newbcast:1 row_mask:0xf bank_mask:0xf
	v_mul_f32_dpp v34, v118, v34 row_newbcast:2 row_mask:0xf bank_mask:0xf
	v_mul_f32_dpp v35, v118, v35 row_newbcast:3 row_mask:0xf bank_mask:0xf
	v_mul_f32_dpp v36, v118, v36 row_newbcast:4 row_mask:0xf bank_mask:0xf
	v_mul_f32_dpp v37, v118, v37 row_newbcast:5 row_mask:0xf bank_mask:0xf
	v_mul_f32_dpp v38, v118, v38 row_newbcast:6 row_mask:0xf bank_mask:0xf
	v_mul_f32_dpp v39, v118, v39 row_newbcast:7 row_mask:0xf bank_mask:0xf
	v_mul_f32_dpp v40, v118, v40 row_newbcast:8 row_mask:0xf bank_mask:0xf
	v_mul_f32_dpp v41, v118, v41 row_newbcast:9 row_mask:0xf bank_mask:0xf
	v_mul_f32_dpp v42, v118, v42 row_newbcast:10 row_mask:0xf bank_mask:0xf
	v_mul_f32_dpp v43, v118, v43 row_newbcast:11 row_mask:0xf bank_mask:0xf
	v_mul_f32_dpp v44, v118, v44 row_newbcast:12 row_mask:0xf bank_mask:0xf
	v_mul_f32_dpp v45, v118, v45 row_newbcast:13 row_mask:0xf bank_mask:0xf
	v_mul_f32_dpp v46, v118, v46 row_newbcast:14 row_mask:0xf bank_mask:0xf
	v_mul_f32_dpp v47, v118, v47 row_newbcast:15 row_mask:0xf bank_mask:0xf
	v_mul_f32_dpp v48, v119, v48 row_newbcast:0 row_mask:0xf bank_mask:0xf
	v_mul_f32_dpp v49, v119, v49 row_newbcast:1 row_mask:0xf bank_mask:0xf
	v_mul_f32_dpp v50, v119, v50 row_newbcast:2 row_mask:0xf bank_mask:0xf
	v_mul_f32_dpp v51, v119, v51 row_newbcast:3 row_mask:0xf bank_mask:0xf
	v_mul_f32_dpp v52, v119, v52 row_newbcast:4 row_mask:0xf bank_mask:0xf
	v_mul_f32_dpp v53, v119, v53 row_newbcast:5 row_mask:0xf bank_mask:0xf
	v_mul_f32_dpp v54, v119, v54 row_newbcast:6 row_mask:0xf bank_mask:0xf
	v_mul_f32_dpp v55, v119, v55 row_newbcast:7 row_mask:0xf bank_mask:0xf
	v_mul_f32_dpp v56, v119, v56 row_newbcast:8 row_mask:0xf bank_mask:0xf
	v_mul_f32_dpp v57, v119, v57 row_newbcast:9 row_mask:0xf bank_mask:0xf
	v_mul_f32_dpp v58, v119, v58 row_newbcast:10 row_mask:0xf bank_mask:0xf
	v_mul_f32_dpp v59, v119, v59 row_newbcast:11 row_mask:0xf bank_mask:0xf
	v_mul_f32_dpp v60, v119, v60 row_newbcast:12 row_mask:0xf bank_mask:0xf
	v_mul_f32_dpp v61, v119, v61 row_newbcast:13 row_mask:0xf bank_mask:0xf
	v_mul_f32_dpp v62, v119, v62 row_newbcast:14 row_mask:0xf bank_mask:0xf
	v_mul_f32_dpp v63, v119, v63 row_newbcast:15 row_mask:0xf bank_mask:0xf
	s_waitcnt lgkmcnt(0)
	ds_read2st64_b32 v[104:105], v14 offset0:55 offset1:58
	ds_read2st64_b32 v[106:107], v17 offset0:55 offset1:58
	ds_read_b32 v138, v15 offset:13824
	ds_read_b32 v139, v15 offset:13952
	ds_read_b32 v109, v16 offset:13824
	v_mul_f32_dpp v120, v100, v32 row_newbcast:0 row_mask:0xf bank_mask:0xf
	v_mul_f32_dpp v121, v100, v33 row_newbcast:1 row_mask:0xf bank_mask:0xf
	v_fmac_f32_dpp v120, v100, v34 row_newbcast:2 row_mask:0xf bank_mask:0xf
	v_fmac_f32_dpp v121, v100, v35 row_newbcast:3 row_mask:0xf bank_mask:0xf
	v_fmac_f32_dpp v120, v100, v36 row_newbcast:4 row_mask:0xf bank_mask:0xf
	v_fmac_f32_dpp v121, v100, v37 row_newbcast:5 row_mask:0xf bank_mask:0xf
	v_fmac_f32_dpp v120, v100, v38 row_newbcast:6 row_mask:0xf bank_mask:0xf
	v_fmac_f32_dpp v121, v100, v39 row_newbcast:7 row_mask:0xf bank_mask:0xf
	v_fmac_f32_dpp v120, v100, v40 row_newbcast:8 row_mask:0xf bank_mask:0xf
	v_fmac_f32_dpp v121, v100, v41 row_newbcast:9 row_mask:0xf bank_mask:0xf
	v_fmac_f32_dpp v120, v100, v42 row_newbcast:10 row_mask:0xf bank_mask:0xf
	v_fmac_f32_dpp v121, v100, v43 row_newbcast:11 row_mask:0xf bank_mask:0xf
	v_fmac_f32_dpp v120, v100, v44 row_newbcast:12 row_mask:0xf bank_mask:0xf
	v_fmac_f32_dpp v121, v100, v45 row_newbcast:13 row_mask:0xf bank_mask:0xf
	v_fmac_f32_dpp v120, v100, v46 row_newbcast:14 row_mask:0xf bank_mask:0xf
	v_fmac_f32_dpp v121, v100, v47 row_newbcast:15 row_mask:0xf bank_mask:0xf
	v_fmac_f32_dpp v120, v102, v48 row_newbcast:0 row_mask:0xf bank_mask:0xf
	v_fmac_f32_dpp v121, v102, v49 row_newbcast:1 row_mask:0xf bank_mask:0xf
	v_fmac_f32_dpp v120, v102, v50 row_newbcast:2 row_mask:0xf bank_mask:0xf
	v_fmac_f32_dpp v121, v102, v51 row_newbcast:3 row_mask:0xf bank_mask:0xf
	v_fmac_f32_dpp v120, v102, v52 row_newbcast:4 row_mask:0xf bank_mask:0xf
	v_fmac_f32_dpp v121, v102, v53 row_newbcast:5 row_mask:0xf bank_mask:0xf
	v_fmac_f32_dpp v120, v102, v54 row_newbcast:6 row_mask:0xf bank_mask:0xf
	v_fmac_f32_dpp v121, v102, v55 row_newbcast:7 row_mask:0xf bank_mask:0xf
	v_fmac_f32_dpp v120, v102, v56 row_newbcast:8 row_mask:0xf bank_mask:0xf
	v_fmac_f32_dpp v121, v102, v57 row_newbcast:9 row_mask:0xf bank_mask:0xf
	v_fmac_f32_dpp v120, v102, v58 row_newbcast:10 row_mask:0xf bank_mask:0xf
	v_fmac_f32_dpp v121, v102, v59 row_newbcast:11 row_mask:0xf bank_mask:0xf
	v_fmac_f32_dpp v120, v102, v60 row_newbcast:12 row_mask:0xf bank_mask:0xf
	v_fmac_f32_dpp v121, v102, v61 row_newbcast:13 row_mask:0xf bank_mask:0xf
	v_fmac_f32_dpp v120, v102, v62 row_newbcast:14 row_mask:0xf bank_mask:0xf
	v_fmac_f32_dpp v121, v102, v63 row_newbcast:15 row_mask:0xf bank_mask:0xf
	v_add_f32_e32 v128, v120, v121
	s_nop 1
	v_permlane32_swap_b32 v129, v128
	s_nop 1
	v_add_f32_dpp v108, -v129, -v128 quad_perm:[0,1,2,3] row_mask:0xc bank_mask:0xf
	s_nop 1
	v_mfma_f32_32x32x2_f32 v[64:79], v136, v108, v[32:47]
	s_nop 15
	v_mfma_f32_32x32x2_f32 v[80:95], v137, v108, v[48:63]
	s_nop 7
	s_waitcnt lgkmcnt(0)
	ds_read2st64_b32 v[110:111], v14 offset0:61 offset1:64
	ds_read2st64_b32 v[112:113], v17 offset0:61 offset1:64
	ds_read_b32 v136, v15 offset:15360
	ds_read_b32 v137, v15 offset:15488
	ds_read_b32 v108, v16 offset:15360
	v_mul_f32_dpp v120, v104, v64 row_newbcast:0 row_mask:0xf bank_mask:0xf
	v_mul_f32_dpp v121, v104, v65 row_newbcast:1 row_mask:0xf bank_mask:0xf
	v_fmac_f32_dpp v120, v104, v66 row_newbcast:2 row_mask:0xf bank_mask:0xf
	v_fmac_f32_dpp v121, v104, v67 row_newbcast:3 row_mask:0xf bank_mask:0xf
	v_fmac_f32_dpp v120, v104, v68 row_newbcast:4 row_mask:0xf bank_mask:0xf
	v_fmac_f32_dpp v121, v104, v69 row_newbcast:5 row_mask:0xf bank_mask:0xf
	v_fmac_f32_dpp v120, v104, v70 row_newbcast:6 row_mask:0xf bank_mask:0xf
	v_fmac_f32_dpp v121, v104, v71 row_newbcast:7 row_mask:0xf bank_mask:0xf
	v_fmac_f32_dpp v120, v104, v72 row_newbcast:8 row_mask:0xf bank_mask:0xf
	v_fmac_f32_dpp v121, v104, v73 row_newbcast:9 row_mask:0xf bank_mask:0xf
	v_fmac_f32_dpp v120, v104, v74 row_newbcast:10 row_mask:0xf bank_mask:0xf
	v_fmac_f32_dpp v121, v104, v75 row_newbcast:11 row_mask:0xf bank_mask:0xf
	v_fmac_f32_dpp v120, v104, v76 row_newbcast:12 row_mask:0xf bank_mask:0xf
	v_fmac_f32_dpp v121, v104, v77 row_newbcast:13 row_mask:0xf bank_mask:0xf
	v_fmac_f32_dpp v120, v104, v78 row_newbcast:14 row_mask:0xf bank_mask:0xf
	v_fmac_f32_dpp v121, v104, v79 row_newbcast:15 row_mask:0xf bank_mask:0xf
	v_fmac_f32_dpp v120, v106, v80 row_newbcast:0 row_mask:0xf bank_mask:0xf
	v_fmac_f32_dpp v121, v106, v81 row_newbcast:1 row_mask:0xf bank_mask:0xf
	v_fmac_f32_dpp v120, v106, v82 row_newbcast:2 row_mask:0xf bank_mask:0xf
	v_fmac_f32_dpp v121, v106, v83 row_newbcast:3 row_mask:0xf bank_mask:0xf
	v_fmac_f32_dpp v120, v106, v84 row_newbcast:4 row_mask:0xf bank_mask:0xf
	v_fmac_f32_dpp v121, v106, v85 row_newbcast:5 row_mask:0xf bank_mask:0xf
	v_fmac_f32_dpp v120, v106, v86 row_newbcast:6 row_mask:0xf bank_mask:0xf
	v_fmac_f32_dpp v121, v106, v87 row_newbcast:7 row_mask:0xf bank_mask:0xf
	v_fmac_f32_dpp v120, v106, v88 row_newbcast:8 row_mask:0xf bank_mask:0xf
	v_fmac_f32_dpp v121, v106, v89 row_newbcast:9 row_mask:0xf bank_mask:0xf
	v_fmac_f32_dpp v120, v106, v90 row_newbcast:10 row_mask:0xf bank_mask:0xf
	v_fmac_f32_dpp v121, v106, v91 row_newbcast:11 row_mask:0xf bank_mask:0xf
	v_fmac_f32_dpp v120, v106, v92 row_newbcast:12 row_mask:0xf bank_mask:0xf
	v_fmac_f32_dpp v121, v106, v93 row_newbcast:13 row_mask:0xf bank_mask:0xf
	v_fmac_f32_dpp v120, v106, v94 row_newbcast:14 row_mask:0xf bank_mask:0xf
	v_fmac_f32_dpp v121, v106, v95 row_newbcast:15 row_mask:0xf bank_mask:0xf
	v_add_f32_e32 v128, v120, v121
	s_nop 1
	v_permlane32_swap_b32 v129, v128
	s_nop 1
	v_add_f32_dpp v109, -v129, -v128 quad_perm:[0,1,2,3] row_mask:0xc bank_mask:0xf
	s_nop 1
	v_mfma_f32_32x32x2_f32 v[32:47], v138, v109, v[64:79]
	s_nop 15
	v_mfma_f32_32x32x2_f32 v[48:63], v139, v109, v[80:95]
	s_nop 7
	s_waitcnt lgkmcnt(0)
	ds_read2st64_b32 v[114:115], v14 offset0:67 offset1:70
	ds_read2st64_b32 v[116:117], v17 offset0:67 offset1:70
	ds_read_b32 v138, v15 offset:16896
	ds_read_b32 v139, v15 offset:17024
	ds_read_b32 v109, v16 offset:16896
	v_mul_f32_dpp v120, v110, v32 row_newbcast:0 row_mask:0xf bank_mask:0xf
	v_mul_f32_dpp v121, v110, v33 row_newbcast:1 row_mask:0xf bank_mask:0xf
	v_fmac_f32_dpp v120, v110, v34 row_newbcast:2 row_mask:0xf bank_mask:0xf
	v_fmac_f32_dpp v121, v110, v35 row_newbcast:3 row_mask:0xf bank_mask:0xf
	v_fmac_f32_dpp v120, v110, v36 row_newbcast:4 row_mask:0xf bank_mask:0xf
	v_fmac_f32_dpp v121, v110, v37 row_newbcast:5 row_mask:0xf bank_mask:0xf
	v_fmac_f32_dpp v120, v110, v38 row_newbcast:6 row_mask:0xf bank_mask:0xf
	v_fmac_f32_dpp v121, v110, v39 row_newbcast:7 row_mask:0xf bank_mask:0xf
	v_fmac_f32_dpp v120, v110, v40 row_newbcast:8 row_mask:0xf bank_mask:0xf
	v_fmac_f32_dpp v121, v110, v41 row_newbcast:9 row_mask:0xf bank_mask:0xf
	v_fmac_f32_dpp v120, v110, v42 row_newbcast:10 row_mask:0xf bank_mask:0xf
	v_fmac_f32_dpp v121, v110, v43 row_newbcast:11 row_mask:0xf bank_mask:0xf
	v_fmac_f32_dpp v120, v110, v44 row_newbcast:12 row_mask:0xf bank_mask:0xf
	v_fmac_f32_dpp v121, v110, v45 row_newbcast:13 row_mask:0xf bank_mask:0xf
	v_fmac_f32_dpp v120, v110, v46 row_newbcast:14 row_mask:0xf bank_mask:0xf
	v_fmac_f32_dpp v121, v110, v47 row_newbcast:15 row_mask:0xf bank_mask:0xf
	v_fmac_f32_dpp v120, v112, v48 row_newbcast:0 row_mask:0xf bank_mask:0xf
	v_fmac_f32_dpp v121, v112, v49 row_newbcast:1 row_mask:0xf bank_mask:0xf
	v_fmac_f32_dpp v120, v112, v50 row_newbcast:2 row_mask:0xf bank_mask:0xf
	v_fmac_f32_dpp v121, v112, v51 row_newbcast:3 row_mask:0xf bank_mask:0xf
	v_fmac_f32_dpp v120, v112, v52 row_newbcast:4 row_mask:0xf bank_mask:0xf
	v_fmac_f32_dpp v121, v112, v53 row_newbcast:5 row_mask:0xf bank_mask:0xf
	v_fmac_f32_dpp v120, v112, v54 row_newbcast:6 row_mask:0xf bank_mask:0xf
	v_fmac_f32_dpp v121, v112, v55 row_newbcast:7 row_mask:0xf bank_mask:0xf
	v_fmac_f32_dpp v120, v112, v56 row_newbcast:8 row_mask:0xf bank_mask:0xf
	v_fmac_f32_dpp v121, v112, v57 row_newbcast:9 row_mask:0xf bank_mask:0xf
	v_fmac_f32_dpp v120, v112, v58 row_newbcast:10 row_mask:0xf bank_mask:0xf
	v_fmac_f32_dpp v121, v112, v59 row_newbcast:11 row_mask:0xf bank_mask:0xf
	v_fmac_f32_dpp v120, v112, v60 row_newbcast:12 row_mask:0xf bank_mask:0xf
	v_fmac_f32_dpp v121, v112, v61 row_newbcast:13 row_mask:0xf bank_mask:0xf
	v_fmac_f32_dpp v120, v112, v62 row_newbcast:14 row_mask:0xf bank_mask:0xf
	v_fmac_f32_dpp v121, v112, v63 row_newbcast:15 row_mask:0xf bank_mask:0xf
	v_add_f32_e32 v128, v120, v121
	s_nop 1
	v_permlane32_swap_b32 v129, v128
	s_nop 1
	v_add_f32_dpp v108, -v129, -v128 quad_perm:[0,1,2,3] row_mask:0xc bank_mask:0xf
	s_nop 1
	v_mfma_f32_32x32x2_f32 v[64:79], v136, v108, v[32:47]
	s_nop 15
	v_mfma_f32_32x32x2_f32 v[80:95], v137, v108, v[48:63]
	s_nop 7
	s_waitcnt lgkmcnt(0)
	ds_read2st64_b32 v[100:101], v14 offset0:73 offset1:76
	ds_read2st64_b32 v[102:103], v17 offset0:73 offset1:76
	ds_read_b32 v136, v15 offset:18432
	ds_read_b32 v137, v15 offset:18560
	ds_read_b32 v108, v16 offset:18432
	v_mul_f32_dpp v120, v114, v64 row_newbcast:0 row_mask:0xf bank_mask:0xf
	v_mul_f32_dpp v121, v114, v65 row_newbcast:1 row_mask:0xf bank_mask:0xf
	v_fmac_f32_dpp v120, v114, v66 row_newbcast:2 row_mask:0xf bank_mask:0xf
	v_fmac_f32_dpp v121, v114, v67 row_newbcast:3 row_mask:0xf bank_mask:0xf
	v_fmac_f32_dpp v120, v114, v68 row_newbcast:4 row_mask:0xf bank_mask:0xf
	v_fmac_f32_dpp v121, v114, v69 row_newbcast:5 row_mask:0xf bank_mask:0xf
	v_fmac_f32_dpp v120, v114, v70 row_newbcast:6 row_mask:0xf bank_mask:0xf
	v_fmac_f32_dpp v121, v114, v71 row_newbcast:7 row_mask:0xf bank_mask:0xf
	v_fmac_f32_dpp v120, v114, v72 row_newbcast:8 row_mask:0xf bank_mask:0xf
	v_fmac_f32_dpp v121, v114, v73 row_newbcast:9 row_mask:0xf bank_mask:0xf
	v_fmac_f32_dpp v120, v114, v74 row_newbcast:10 row_mask:0xf bank_mask:0xf
	v_fmac_f32_dpp v121, v114, v75 row_newbcast:11 row_mask:0xf bank_mask:0xf
	v_fmac_f32_dpp v120, v114, v76 row_newbcast:12 row_mask:0xf bank_mask:0xf
	v_fmac_f32_dpp v121, v114, v77 row_newbcast:13 row_mask:0xf bank_mask:0xf
	v_fmac_f32_dpp v120, v114, v78 row_newbcast:14 row_mask:0xf bank_mask:0xf
	v_fmac_f32_dpp v121, v114, v79 row_newbcast:15 row_mask:0xf bank_mask:0xf
	v_fmac_f32_dpp v120, v116, v80 row_newbcast:0 row_mask:0xf bank_mask:0xf
	v_fmac_f32_dpp v121, v116, v81 row_newbcast:1 row_mask:0xf bank_mask:0xf
	v_fmac_f32_dpp v120, v116, v82 row_newbcast:2 row_mask:0xf bank_mask:0xf
	v_fmac_f32_dpp v121, v116, v83 row_newbcast:3 row_mask:0xf bank_mask:0xf
	v_fmac_f32_dpp v120, v116, v84 row_newbcast:4 row_mask:0xf bank_mask:0xf
	v_fmac_f32_dpp v121, v116, v85 row_newbcast:5 row_mask:0xf bank_mask:0xf
	v_fmac_f32_dpp v120, v116, v86 row_newbcast:6 row_mask:0xf bank_mask:0xf
	v_fmac_f32_dpp v121, v116, v87 row_newbcast:7 row_mask:0xf bank_mask:0xf
	v_fmac_f32_dpp v120, v116, v88 row_newbcast:8 row_mask:0xf bank_mask:0xf
	v_fmac_f32_dpp v121, v116, v89 row_newbcast:9 row_mask:0xf bank_mask:0xf
	v_fmac_f32_dpp v120, v116, v90 row_newbcast:10 row_mask:0xf bank_mask:0xf
	v_fmac_f32_dpp v121, v116, v91 row_newbcast:11 row_mask:0xf bank_mask:0xf
	v_fmac_f32_dpp v120, v116, v92 row_newbcast:12 row_mask:0xf bank_mask:0xf
	v_fmac_f32_dpp v121, v116, v93 row_newbcast:13 row_mask:0xf bank_mask:0xf
	v_fmac_f32_dpp v120, v116, v94 row_newbcast:14 row_mask:0xf bank_mask:0xf
	v_fmac_f32_dpp v121, v116, v95 row_newbcast:15 row_mask:0xf bank_mask:0xf
	v_add_f32_e32 v128, v120, v121
	s_nop 1
	v_permlane32_swap_b32 v129, v128
	s_nop 1
	v_add_f32_dpp v109, -v129, -v128 quad_perm:[0,1,2,3] row_mask:0xc bank_mask:0xf
	s_nop 1
	v_mfma_f32_32x32x2_f32 v[32:47], v138, v109, v[64:79]
	s_nop 15
	v_mfma_f32_32x32x2_f32 v[48:63], v139, v109, v[80:95]
	s_nop 7
	s_waitcnt lgkmcnt(0)
	ds_read2st64_b32 v[104:105], v14 offset0:79 offset1:82
	ds_read2st64_b32 v[106:107], v17 offset0:79 offset1:82
	ds_read_b32 v138, v15 offset:19968
	ds_read_b32 v139, v15 offset:20096
	ds_read_b32 v109, v16 offset:19968
	v_mul_f32_dpp v120, v100, v32 row_newbcast:0 row_mask:0xf bank_mask:0xf
	v_mul_f32_dpp v121, v100, v33 row_newbcast:1 row_mask:0xf bank_mask:0xf
	v_fmac_f32_dpp v120, v100, v34 row_newbcast:2 row_mask:0xf bank_mask:0xf
	v_fmac_f32_dpp v121, v100, v35 row_newbcast:3 row_mask:0xf bank_mask:0xf
	v_fmac_f32_dpp v120, v100, v36 row_newbcast:4 row_mask:0xf bank_mask:0xf
	v_fmac_f32_dpp v121, v100, v37 row_newbcast:5 row_mask:0xf bank_mask:0xf
	v_fmac_f32_dpp v120, v100, v38 row_newbcast:6 row_mask:0xf bank_mask:0xf
	v_fmac_f32_dpp v121, v100, v39 row_newbcast:7 row_mask:0xf bank_mask:0xf
	v_fmac_f32_dpp v120, v100, v40 row_newbcast:8 row_mask:0xf bank_mask:0xf
	v_fmac_f32_dpp v121, v100, v41 row_newbcast:9 row_mask:0xf bank_mask:0xf
	v_fmac_f32_dpp v120, v100, v42 row_newbcast:10 row_mask:0xf bank_mask:0xf
	v_fmac_f32_dpp v121, v100, v43 row_newbcast:11 row_mask:0xf bank_mask:0xf
	v_fmac_f32_dpp v120, v100, v44 row_newbcast:12 row_mask:0xf bank_mask:0xf
	v_fmac_f32_dpp v121, v100, v45 row_newbcast:13 row_mask:0xf bank_mask:0xf
	v_fmac_f32_dpp v120, v100, v46 row_newbcast:14 row_mask:0xf bank_mask:0xf
	v_fmac_f32_dpp v121, v100, v47 row_newbcast:15 row_mask:0xf bank_mask:0xf
	v_fmac_f32_dpp v120, v102, v48 row_newbcast:0 row_mask:0xf bank_mask:0xf
	v_fmac_f32_dpp v121, v102, v49 row_newbcast:1 row_mask:0xf bank_mask:0xf
	v_fmac_f32_dpp v120, v102, v50 row_newbcast:2 row_mask:0xf bank_mask:0xf
	v_fmac_f32_dpp v121, v102, v51 row_newbcast:3 row_mask:0xf bank_mask:0xf
	v_fmac_f32_dpp v120, v102, v52 row_newbcast:4 row_mask:0xf bank_mask:0xf
	v_fmac_f32_dpp v121, v102, v53 row_newbcast:5 row_mask:0xf bank_mask:0xf
	v_fmac_f32_dpp v120, v102, v54 row_newbcast:6 row_mask:0xf bank_mask:0xf
	v_fmac_f32_dpp v121, v102, v55 row_newbcast:7 row_mask:0xf bank_mask:0xf
	v_fmac_f32_dpp v120, v102, v56 row_newbcast:8 row_mask:0xf bank_mask:0xf
	v_fmac_f32_dpp v121, v102, v57 row_newbcast:9 row_mask:0xf bank_mask:0xf
	v_fmac_f32_dpp v120, v102, v58 row_newbcast:10 row_mask:0xf bank_mask:0xf
	v_fmac_f32_dpp v121, v102, v59 row_newbcast:11 row_mask:0xf bank_mask:0xf
	v_fmac_f32_dpp v120, v102, v60 row_newbcast:12 row_mask:0xf bank_mask:0xf
	v_fmac_f32_dpp v121, v102, v61 row_newbcast:13 row_mask:0xf bank_mask:0xf
	v_fmac_f32_dpp v120, v102, v62 row_newbcast:14 row_mask:0xf bank_mask:0xf
	v_fmac_f32_dpp v121, v102, v63 row_newbcast:15 row_mask:0xf bank_mask:0xf
	v_add_f32_e32 v128, v120, v121
	s_nop 1
	v_permlane32_swap_b32 v129, v128
	s_nop 1
	v_add_f32_dpp v108, -v129, -v128 quad_perm:[0,1,2,3] row_mask:0xc bank_mask:0xf
	s_nop 1
	v_mfma_f32_32x32x2_f32 v[64:79], v136, v108, v[32:47]
	s_nop 15
	v_mfma_f32_32x32x2_f32 v[80:95], v137, v108, v[48:63]
	s_nop 7
	s_waitcnt lgkmcnt(0)
	ds_read2st64_b32 v[110:111], v14 offset0:85 offset1:88
	ds_read2st64_b32 v[112:113], v17 offset0:85 offset1:88
	ds_read_b32 v136, v15 offset:21504
	ds_read_b32 v137, v15 offset:21632
	ds_read_b32 v108, v16 offset:21504
	v_mul_f32_dpp v120, v104, v64 row_newbcast:0 row_mask:0xf bank_mask:0xf
	v_mul_f32_dpp v121, v104, v65 row_newbcast:1 row_mask:0xf bank_mask:0xf
	v_fmac_f32_dpp v120, v104, v66 row_newbcast:2 row_mask:0xf bank_mask:0xf
	v_fmac_f32_dpp v121, v104, v67 row_newbcast:3 row_mask:0xf bank_mask:0xf
	v_fmac_f32_dpp v120, v104, v68 row_newbcast:4 row_mask:0xf bank_mask:0xf
	v_fmac_f32_dpp v121, v104, v69 row_newbcast:5 row_mask:0xf bank_mask:0xf
	v_fmac_f32_dpp v120, v104, v70 row_newbcast:6 row_mask:0xf bank_mask:0xf
	v_fmac_f32_dpp v121, v104, v71 row_newbcast:7 row_mask:0xf bank_mask:0xf
	v_fmac_f32_dpp v120, v104, v72 row_newbcast:8 row_mask:0xf bank_mask:0xf
	v_fmac_f32_dpp v121, v104, v73 row_newbcast:9 row_mask:0xf bank_mask:0xf
	v_fmac_f32_dpp v120, v104, v74 row_newbcast:10 row_mask:0xf bank_mask:0xf
	v_fmac_f32_dpp v121, v104, v75 row_newbcast:11 row_mask:0xf bank_mask:0xf
	v_fmac_f32_dpp v120, v104, v76 row_newbcast:12 row_mask:0xf bank_mask:0xf
	v_fmac_f32_dpp v121, v104, v77 row_newbcast:13 row_mask:0xf bank_mask:0xf
	v_fmac_f32_dpp v120, v104, v78 row_newbcast:14 row_mask:0xf bank_mask:0xf
	v_fmac_f32_dpp v121, v104, v79 row_newbcast:15 row_mask:0xf bank_mask:0xf
	v_fmac_f32_dpp v120, v106, v80 row_newbcast:0 row_mask:0xf bank_mask:0xf
	v_fmac_f32_dpp v121, v106, v81 row_newbcast:1 row_mask:0xf bank_mask:0xf
	v_fmac_f32_dpp v120, v106, v82 row_newbcast:2 row_mask:0xf bank_mask:0xf
	v_fmac_f32_dpp v121, v106, v83 row_newbcast:3 row_mask:0xf bank_mask:0xf
	v_fmac_f32_dpp v120, v106, v84 row_newbcast:4 row_mask:0xf bank_mask:0xf
	v_fmac_f32_dpp v121, v106, v85 row_newbcast:5 row_mask:0xf bank_mask:0xf
	v_fmac_f32_dpp v120, v106, v86 row_newbcast:6 row_mask:0xf bank_mask:0xf
	v_fmac_f32_dpp v121, v106, v87 row_newbcast:7 row_mask:0xf bank_mask:0xf
	v_fmac_f32_dpp v120, v106, v88 row_newbcast:8 row_mask:0xf bank_mask:0xf
	v_fmac_f32_dpp v121, v106, v89 row_newbcast:9 row_mask:0xf bank_mask:0xf
	v_fmac_f32_dpp v120, v106, v90 row_newbcast:10 row_mask:0xf bank_mask:0xf
	v_fmac_f32_dpp v121, v106, v91 row_newbcast:11 row_mask:0xf bank_mask:0xf
	v_fmac_f32_dpp v120, v106, v92 row_newbcast:12 row_mask:0xf bank_mask:0xf
	v_fmac_f32_dpp v121, v106, v93 row_newbcast:13 row_mask:0xf bank_mask:0xf
	v_fmac_f32_dpp v120, v106, v94 row_newbcast:14 row_mask:0xf bank_mask:0xf
	v_fmac_f32_dpp v121, v106, v95 row_newbcast:15 row_mask:0xf bank_mask:0xf
	v_add_f32_e32 v128, v120, v121
	s_nop 1
	v_permlane32_swap_b32 v129, v128
	s_nop 1
	v_add_f32_dpp v109, -v129, -v128 quad_perm:[0,1,2,3] row_mask:0xc bank_mask:0xf
	s_nop 1
	v_mfma_f32_32x32x2_f32 v[32:47], v138, v109, v[64:79]
	s_nop 15
	v_mfma_f32_32x32x2_f32 v[48:63], v139, v109, v[80:95]
	s_nop 7
	s_waitcnt lgkmcnt(0)
	ds_read2st64_b32 v[114:115], v14 offset0:91 offset1:94
	ds_read2st64_b32 v[116:117], v17 offset0:91 offset1:94
	ds_read_b32 v138, v15 offset:23040
	ds_read_b32 v139, v15 offset:23168
	ds_read_b32 v109, v16 offset:23040
	ds_read_b32 v118, v14 offset:23040
	ds_read_b32 v119, v14 offset:23168
	v_mul_f32_dpp v120, v110, v32 row_newbcast:0 row_mask:0xf bank_mask:0xf
	v_mul_f32_dpp v121, v110, v33 row_newbcast:1 row_mask:0xf bank_mask:0xf
	v_fmac_f32_dpp v120, v110, v34 row_newbcast:2 row_mask:0xf bank_mask:0xf
	v_fmac_f32_dpp v121, v110, v35 row_newbcast:3 row_mask:0xf bank_mask:0xf
	v_fmac_f32_dpp v120, v110, v36 row_newbcast:4 row_mask:0xf bank_mask:0xf
	v_fmac_f32_dpp v121, v110, v37 row_newbcast:5 row_mask:0xf bank_mask:0xf
	v_fmac_f32_dpp v120, v110, v38 row_newbcast:6 row_mask:0xf bank_mask:0xf
	v_fmac_f32_dpp v121, v110, v39 row_newbcast:7 row_mask:0xf bank_mask:0xf
	v_fmac_f32_dpp v120, v110, v40 row_newbcast:8 row_mask:0xf bank_mask:0xf
	v_fmac_f32_dpp v121, v110, v41 row_newbcast:9 row_mask:0xf bank_mask:0xf
	v_fmac_f32_dpp v120, v110, v42 row_newbcast:10 row_mask:0xf bank_mask:0xf
	v_fmac_f32_dpp v121, v110, v43 row_newbcast:11 row_mask:0xf bank_mask:0xf
	v_fmac_f32_dpp v120, v110, v44 row_newbcast:12 row_mask:0xf bank_mask:0xf
	v_fmac_f32_dpp v121, v110, v45 row_newbcast:13 row_mask:0xf bank_mask:0xf
	v_fmac_f32_dpp v120, v110, v46 row_newbcast:14 row_mask:0xf bank_mask:0xf
	v_fmac_f32_dpp v121, v110, v47 row_newbcast:15 row_mask:0xf bank_mask:0xf
	v_fmac_f32_dpp v120, v112, v48 row_newbcast:0 row_mask:0xf bank_mask:0xf
	v_fmac_f32_dpp v121, v112, v49 row_newbcast:1 row_mask:0xf bank_mask:0xf
	v_fmac_f32_dpp v120, v112, v50 row_newbcast:2 row_mask:0xf bank_mask:0xf
	v_fmac_f32_dpp v121, v112, v51 row_newbcast:3 row_mask:0xf bank_mask:0xf
	v_fmac_f32_dpp v120, v112, v52 row_newbcast:4 row_mask:0xf bank_mask:0xf
	v_fmac_f32_dpp v121, v112, v53 row_newbcast:5 row_mask:0xf bank_mask:0xf
	v_fmac_f32_dpp v120, v112, v54 row_newbcast:6 row_mask:0xf bank_mask:0xf
	v_fmac_f32_dpp v121, v112, v55 row_newbcast:7 row_mask:0xf bank_mask:0xf
	v_fmac_f32_dpp v120, v112, v56 row_newbcast:8 row_mask:0xf bank_mask:0xf
	v_fmac_f32_dpp v121, v112, v57 row_newbcast:9 row_mask:0xf bank_mask:0xf
	v_fmac_f32_dpp v120, v112, v58 row_newbcast:10 row_mask:0xf bank_mask:0xf
	v_fmac_f32_dpp v121, v112, v59 row_newbcast:11 row_mask:0xf bank_mask:0xf
	v_fmac_f32_dpp v120, v112, v60 row_newbcast:12 row_mask:0xf bank_mask:0xf
	v_fmac_f32_dpp v121, v112, v61 row_newbcast:13 row_mask:0xf bank_mask:0xf
	v_fmac_f32_dpp v120, v112, v62 row_newbcast:14 row_mask:0xf bank_mask:0xf
	v_fmac_f32_dpp v121, v112, v63 row_newbcast:15 row_mask:0xf bank_mask:0xf
	v_add_f32_e32 v128, v120, v121
	s_nop 1
	v_permlane32_swap_b32 v129, v128
	s_nop 1
	v_add_f32_dpp v108, -v129, -v128 quad_perm:[0,1,2,3] row_mask:0xc bank_mask:0xf
	s_nop 1
	v_mfma_f32_32x32x2_f32 v[64:79], v136, v108, v[32:47]
	s_nop 15
	v_mfma_f32_32x32x2_f32 v[80:95], v137, v108, v[48:63]
	s_nop 7
	s_waitcnt lgkmcnt(0)
	v_mul_f32_dpp v120, v114, v64 row_newbcast:0 row_mask:0xf bank_mask:0xf
	v_mul_f32_dpp v121, v114, v65 row_newbcast:1 row_mask:0xf bank_mask:0xf
	v_fmac_f32_dpp v120, v114, v66 row_newbcast:2 row_mask:0xf bank_mask:0xf
	v_fmac_f32_dpp v121, v114, v67 row_newbcast:3 row_mask:0xf bank_mask:0xf
	v_fmac_f32_dpp v120, v114, v68 row_newbcast:4 row_mask:0xf bank_mask:0xf
	v_fmac_f32_dpp v121, v114, v69 row_newbcast:5 row_mask:0xf bank_mask:0xf
	v_fmac_f32_dpp v120, v114, v70 row_newbcast:6 row_mask:0xf bank_mask:0xf
	v_fmac_f32_dpp v121, v114, v71 row_newbcast:7 row_mask:0xf bank_mask:0xf
	v_fmac_f32_dpp v120, v114, v72 row_newbcast:8 row_mask:0xf bank_mask:0xf
	v_fmac_f32_dpp v121, v114, v73 row_newbcast:9 row_mask:0xf bank_mask:0xf
	v_fmac_f32_dpp v120, v114, v74 row_newbcast:10 row_mask:0xf bank_mask:0xf
	v_fmac_f32_dpp v121, v114, v75 row_newbcast:11 row_mask:0xf bank_mask:0xf
	v_fmac_f32_dpp v120, v114, v76 row_newbcast:12 row_mask:0xf bank_mask:0xf
	v_fmac_f32_dpp v121, v114, v77 row_newbcast:13 row_mask:0xf bank_mask:0xf
	v_fmac_f32_dpp v120, v114, v78 row_newbcast:14 row_mask:0xf bank_mask:0xf
	v_fmac_f32_dpp v121, v114, v79 row_newbcast:15 row_mask:0xf bank_mask:0xf
	v_fmac_f32_dpp v120, v116, v80 row_newbcast:0 row_mask:0xf bank_mask:0xf
	v_fmac_f32_dpp v121, v116, v81 row_newbcast:1 row_mask:0xf bank_mask:0xf
	v_fmac_f32_dpp v120, v116, v82 row_newbcast:2 row_mask:0xf bank_mask:0xf
	v_fmac_f32_dpp v121, v116, v83 row_newbcast:3 row_mask:0xf bank_mask:0xf
	v_fmac_f32_dpp v120, v116, v84 row_newbcast:4 row_mask:0xf bank_mask:0xf
	v_fmac_f32_dpp v121, v116, v85 row_newbcast:5 row_mask:0xf bank_mask:0xf
	v_fmac_f32_dpp v120, v116, v86 row_newbcast:6 row_mask:0xf bank_mask:0xf
	v_fmac_f32_dpp v121, v116, v87 row_newbcast:7 row_mask:0xf bank_mask:0xf
	v_fmac_f32_dpp v120, v116, v88 row_newbcast:8 row_mask:0xf bank_mask:0xf
	v_fmac_f32_dpp v121, v116, v89 row_newbcast:9 row_mask:0xf bank_mask:0xf
	v_fmac_f32_dpp v120, v116, v90 row_newbcast:10 row_mask:0xf bank_mask:0xf
	v_fmac_f32_dpp v121, v116, v91 row_newbcast:11 row_mask:0xf bank_mask:0xf
	v_fmac_f32_dpp v120, v116, v92 row_newbcast:12 row_mask:0xf bank_mask:0xf
	v_fmac_f32_dpp v121, v116, v93 row_newbcast:13 row_mask:0xf bank_mask:0xf
	v_fmac_f32_dpp v120, v116, v94 row_newbcast:14 row_mask:0xf bank_mask:0xf
	v_fmac_f32_dpp v121, v116, v95 row_newbcast:15 row_mask:0xf bank_mask:0xf
	v_add_f32_e32 v128, v120, v121
	s_nop 1
	v_permlane32_swap_b32 v129, v128
	s_nop 1
	v_add_f32_dpp v109, -v129, -v128 quad_perm:[0,1,2,3] row_mask:0xc bank_mask:0xf
	s_nop 1
	v_mfma_f32_32x32x2_f32 v[32:47], v138, v109, v[64:79]
	s_nop 15
	v_mfma_f32_32x32x2_f32 v[48:63], v139, v109, v[80:95]
	s_nop 7
	s_nop 7
	s_nop 7
	v_mul_f32_dpp v32, v118, v32 row_newbcast:0 row_mask:0xf bank_mask:0xf
	v_mul_f32_dpp v33, v118, v33 row_newbcast:1 row_mask:0xf bank_mask:0xf
	v_mul_f32_dpp v34, v118, v34 row_newbcast:2 row_mask:0xf bank_mask:0xf
	v_mul_f32_dpp v35, v118, v35 row_newbcast:3 row_mask:0xf bank_mask:0xf
	v_mul_f32_dpp v36, v118, v36 row_newbcast:4 row_mask:0xf bank_mask:0xf
	v_mul_f32_dpp v37, v118, v37 row_newbcast:5 row_mask:0xf bank_mask:0xf
	v_mul_f32_dpp v38, v118, v38 row_newbcast:6 row_mask:0xf bank_mask:0xf
	v_mul_f32_dpp v39, v118, v39 row_newbcast:7 row_mask:0xf bank_mask:0xf
	v_mul_f32_dpp v40, v118, v40 row_newbcast:8 row_mask:0xf bank_mask:0xf
	v_mul_f32_dpp v41, v118, v41 row_newbcast:9 row_mask:0xf bank_mask:0xf
	v_mul_f32_dpp v42, v118, v42 row_newbcast:10 row_mask:0xf bank_mask:0xf
	v_mul_f32_dpp v43, v118, v43 row_newbcast:11 row_mask:0xf bank_mask:0xf
	v_mul_f32_dpp v44, v118, v44 row_newbcast:12 row_mask:0xf bank_mask:0xf
	v_mul_f32_dpp v45, v118, v45 row_newbcast:13 row_mask:0xf bank_mask:0xf
	v_mul_f32_dpp v46, v118, v46 row_newbcast:14 row_mask:0xf bank_mask:0xf
	v_mul_f32_dpp v47, v118, v47 row_newbcast:15 row_mask:0xf bank_mask:0xf
	v_mul_f32_dpp v48, v119, v48 row_newbcast:0 row_mask:0xf bank_mask:0xf
	v_mul_f32_dpp v49, v119, v49 row_newbcast:1 row_mask:0xf bank_mask:0xf
	v_mul_f32_dpp v50, v119, v50 row_newbcast:2 row_mask:0xf bank_mask:0xf
	v_mul_f32_dpp v51, v119, v51 row_newbcast:3 row_mask:0xf bank_mask:0xf
	v_mul_f32_dpp v52, v119, v52 row_newbcast:4 row_mask:0xf bank_mask:0xf
	v_mul_f32_dpp v53, v119, v53 row_newbcast:5 row_mask:0xf bank_mask:0xf
	v_mul_f32_dpp v54, v119, v54 row_newbcast:6 row_mask:0xf bank_mask:0xf
	v_mul_f32_dpp v55, v119, v55 row_newbcast:7 row_mask:0xf bank_mask:0xf
	v_mul_f32_dpp v56, v119, v56 row_newbcast:8 row_mask:0xf bank_mask:0xf
	v_mul_f32_dpp v57, v119, v57 row_newbcast:9 row_mask:0xf bank_mask:0xf
	v_mul_f32_dpp v58, v119, v58 row_newbcast:10 row_mask:0xf bank_mask:0xf
	v_mul_f32_dpp v59, v119, v59 row_newbcast:11 row_mask:0xf bank_mask:0xf
	v_mul_f32_dpp v60, v119, v60 row_newbcast:12 row_mask:0xf bank_mask:0xf
	v_mul_f32_dpp v61, v119, v61 row_newbcast:13 row_mask:0xf bank_mask:0xf
	v_mul_f32_dpp v62, v119, v62 row_newbcast:14 row_mask:0xf bank_mask:0xf
	v_mul_f32_dpp v63, v119, v63 row_newbcast:15 row_mask:0xf bank_mask:0xf
	s_branch .Lscan_tail
.Lscan_full:
	s_waitcnt lgkmcnt(0)
	ds_read2st64_b32 v[104:105], v14 offset0:7 offset1:10
	ds_read2st64_b32 v[106:107], v17 offset0:7 offset1:10
	ds_read_b32 v138, v15 offset:1536
	ds_read_b32 v139, v15 offset:1664
	ds_read_b32 v109, v16 offset:1536
	v_mul_f32_dpp v120, v100, v32 row_newbcast:0 row_mask:0xf bank_mask:0xf
	v_mul_f32_dpp v121, v100, v33 row_newbcast:1 row_mask:0xf bank_mask:0xf
	v_fmac_f32_dpp v120, v100, v34 row_newbcast:2 row_mask:0xf bank_mask:0xf
	v_fmac_f32_dpp v121, v100, v35 row_newbcast:3 row_mask:0xf bank_mask:0xf
	v_fmac_f32_dpp v120, v100, v36 row_newbcast:4 row_mask:0xf bank_mask:0xf
	v_fmac_f32_dpp v121, v100, v37 row_newbcast:5 row_mask:0xf bank_mask:0xf
	v_fmac_f32_dpp v120, v100, v38 row_newbcast:6 row_mask:0xf bank_mask:0xf
	v_fmac_f32_dpp v121, v100, v39 row_newbcast:7 row_mask:0xf bank_mask:0xf
	v_fmac_f32_dpp v120, v100, v40 row_newbcast:8 row_mask:0xf bank_mask:0xf
	v_fmac_f32_dpp v121, v100, v41 row_newbcast:9 row_mask:0xf bank_mask:0xf
	v_fmac_f32_dpp v120, v100, v42 row_newbcast:10 row_mask:0xf bank_mask:0xf
	v_fmac_f32_dpp v121, v100, v43 row_newbcast:11 row_mask:0xf bank_mask:0xf
	v_fmac_f32_dpp v120, v100, v44 row_newbcast:12 row_mask:0xf bank_mask:0xf
	v_fmac_f32_dpp v121, v100, v45 row_newbcast:13 row_mask:0xf bank_mask:0xf
	v_fmac_f32_dpp v120, v100, v46 row_newbcast:14 row_mask:0xf bank_mask:0xf
	v_fmac_f32_dpp v121, v100, v47 row_newbcast:15 row_mask:0xf bank_mask:0xf
	v_fmac_f32_dpp v120, v102, v48 row_newbcast:0 row_mask:0xf bank_mask:0xf
	v_fmac_f32_dpp v121, v102, v49 row_newbcast:1 row_mask:0xf bank_mask:0xf
	v_fmac_f32_dpp v120, v102, v50 row_newbcast:2 row_mask:0xf bank_mask:0xf
	v_fmac_f32_dpp v121, v102, v51 row_newbcast:3 row_mask:0xf bank_mask:0xf
	v_fmac_f32_dpp v120, v102, v52 row_newbcast:4 row_mask:0xf bank_mask:0xf
	v_fmac_f32_dpp v121, v102, v53 row_newbcast:5 row_mask:0xf bank_mask:0xf
	v_fmac_f32_dpp v120, v102, v54 row_newbcast:6 row_mask:0xf bank_mask:0xf
	v_fmac_f32_dpp v121, v102, v55 row_newbcast:7 row_mask:0xf bank_mask:0xf
	v_fmac_f32_dpp v120, v102, v56 row_newbcast:8 row_mask:0xf bank_mask:0xf
	v_fmac_f32_dpp v121, v102, v57 row_newbcast:9 row_mask:0xf bank_mask:0xf
	v_fmac_f32_dpp v120, v102, v58 row_newbcast:10 row_mask:0xf bank_mask:0xf
	v_fmac_f32_dpp v121, v102, v59 row_newbcast:11 row_mask:0xf bank_mask:0xf
	v_fmac_f32_dpp v120, v102, v60 row_newbcast:12 row_mask:0xf bank_mask:0xf
	v_fmac_f32_dpp v121, v102, v61 row_newbcast:13 row_mask:0xf bank_mask:0xf
	v_fmac_f32_dpp v120, v102, v62 row_newbcast:14 row_mask:0xf bank_mask:0xf
	v_fmac_f32_dpp v121, v102, v63 row_newbcast:15 row_mask:0xf bank_mask:0xf
	v_add_f32_e32 v128, v120, v121
	s_nop 1
	v_permlane32_swap_b32 v129, v128
	s_nop 1
	v_add_f32_dpp v108, -v129, -v128 quad_perm:[0,1,2,3] row_mask:0xc bank_mask:0xf
	s_nop 1
	v_mfma_f32_32x32x2_f32 v[64:79], v136, v108, v[32:47]
	s_nop 15
	v_mfma_f32_32x32x2_f32 v[80:95], v137, v108, v[48:63]
	s_nop 7
	s_waitcnt lgkmcnt(0)
	ds_read2st64_b32 v[110:111], v14 offset0:13 offset1:16
	ds_read2st64_b32 v[112:113], v17 offset0:13 offset1:16
	ds_read_b32 v136, v15 offset:3072
	ds_read_b32 v137, v15 offset:3200
	ds_read_b32 v108, v16 offset:3072
	v_mul_f32_dpp v120, v104, v64 row_newbcast:0 row_mask:0xf bank_mask:0xf
	v_mul_f32_dpp v121, v104, v65 row_newbcast:1 row_mask:0xf bank_mask:0xf
	v_fmac_f32_dpp v120, v104, v66 row_newbcast:2 row_mask:0xf bank_mask:0xf
	v_fmac_f32_dpp v121, v104, v67 row_newbcast:3 row_mask:0xf bank_mask:0xf
	v_fmac_f32_dpp v120, v104, v68 row_newbcast:4 row_mask:0xf bank_mask:0xf
	v_fmac_f32_dpp v121, v104, v69 row_newbcast:5 row_mask:0xf bank_mask:0xf
	v_fmac_f32_dpp v120, v104, v70 row_newbcast:6 row_mask:0xf bank_mask:0xf
	v_fmac_f32_dpp v121, v104, v71 row_newbcast:7 row_mask:0xf bank_mask:0xf
	v_fmac_f32_dpp v120, v104, v72 row_newbcast:8 row_mask:0xf bank_mask:0xf
	v_fmac_f32_dpp v121, v104, v73 row_newbcast:9 row_mask:0xf bank_mask:0xf
	v_fmac_f32_dpp v120, v104, v74 row_newbcast:10 row_mask:0xf bank_mask:0xf
	v_fmac_f32_dpp v121, v104, v75 row_newbcast:11 row_mask:0xf bank_mask:0xf
	v_fmac_f32_dpp v120, v104, v76 row_newbcast:12 row_mask:0xf bank_mask:0xf
	v_fmac_f32_dpp v121, v104, v77 row_newbcast:13 row_mask:0xf bank_mask:0xf
	v_fmac_f32_dpp v120, v104, v78 row_newbcast:14 row_mask:0xf bank_mask:0xf
	v_fmac_f32_dpp v121, v104, v79 row_newbcast:15 row_mask:0xf bank_mask:0xf
	v_fmac_f32_dpp v120, v106, v80 row_newbcast:0 row_mask:0xf bank_mask:0xf
	v_fmac_f32_dpp v121, v106, v81 row_newbcast:1 row_mask:0xf bank_mask:0xf
	v_fmac_f32_dpp v120, v106, v82 row_newbcast:2 row_mask:0xf bank_mask:0xf
	v_fmac_f32_dpp v121, v106, v83 row_newbcast:3 row_mask:0xf bank_mask:0xf
	v_fmac_f32_dpp v120, v106, v84 row_newbcast:4 row_mask:0xf bank_mask:0xf
	v_fmac_f32_dpp v121, v106, v85 row_newbcast:5 row_mask:0xf bank_mask:0xf
	v_fmac_f32_dpp v120, v106, v86 row_newbcast:6 row_mask:0xf bank_mask:0xf
	v_fmac_f32_dpp v121, v106, v87 row_newbcast:7 row_mask:0xf bank_mask:0xf
	v_fmac_f32_dpp v120, v106, v88 row_newbcast:8 row_mask:0xf bank_mask:0xf
	v_fmac_f32_dpp v121, v106, v89 row_newbcast:9 row_mask:0xf bank_mask:0xf
	v_fmac_f32_dpp v120, v106, v90 row_newbcast:10 row_mask:0xf bank_mask:0xf
	v_fmac_f32_dpp v121, v106, v91 row_newbcast:11 row_mask:0xf bank_mask:0xf
	v_fmac_f32_dpp v120, v106, v92 row_newbcast:12 row_mask:0xf bank_mask:0xf
	v_fmac_f32_dpp v121, v106, v93 row_newbcast:13 row_mask:0xf bank_mask:0xf
	v_fmac_f32_dpp v120, v106, v94 row_newbcast:14 row_mask:0xf bank_mask:0xf
	v_fmac_f32_dpp v121, v106, v95 row_newbcast:15 row_mask:0xf bank_mask:0xf
	v_add_f32_e32 v128, v120, v121
	v_mul_f32_dpp v124, v101, v64 row_newbcast:0 row_mask:0xf bank_mask:0xf
	v_mul_f32_dpp v125, v101, v65 row_newbcast:1 row_mask:0xf bank_mask:0xf
	v_permlane32_swap_b32 v129, v128
	v_fmac_f32_dpp v124, v101, v66 row_newbcast:2 row_mask:0xf bank_mask:0xf
	v_fmac_f32_dpp v125, v101, v67 row_newbcast:3 row_mask:0xf bank_mask:0xf
	v_add_f32_dpp v109, -v129, -v128 quad_perm:[0,1,2,3] row_mask:0xc bank_mask:0xf
	v_fmac_f32_dpp v124, v101, v68 row_newbcast:4 row_mask:0xf bank_mask:0xf
	v_fmac_f32_dpp v125, v101, v69 row_newbcast:5 row_mask:0xf bank_mask:0xf
	v_mfma_f32_32x32x2_f32 v[32:47], v138, v109, v[64:79]
	v_fmac_f32_dpp v124, v101, v70 row_newbcast:6 row_mask:0xf bank_mask:0xf
	v_fmac_f32_dpp v125, v101, v71 row_newbcast:7 row_mask:0xf bank_mask:0xf
	v_fmac_f32_dpp v124, v101, v72 row_newbcast:8 row_mask:0xf bank_mask:0xf
	v_fmac_f32_dpp v125, v101, v73 row_newbcast:9 row_mask:0xf bank_mask:0xf
	v_fmac_f32_dpp v124, v101, v74 row_newbcast:10 row_mask:0xf bank_mask:0xf
	v_fmac_f32_dpp v125, v101, v75 row_newbcast:11 row_mask:0xf bank_mask:0xf
	v_fmac_f32_dpp v124, v101, v76 row_newbcast:12 row_mask:0xf bank_mask:0xf
	v_fmac_f32_dpp v125, v101, v77 row_newbcast:13 row_mask:0xf bank_mask:0xf
	v_fmac_f32_dpp v124, v101, v78 row_newbcast:14 row_mask:0xf bank_mask:0xf
	v_fmac_f32_dpp v125, v101, v79 row_newbcast:15 row_mask:0xf bank_mask:0xf
	v_fmac_f32_dpp v124, v103, v80 row_newbcast:0 row_mask:0xf bank_mask:0xf
	v_fmac_f32_dpp v125, v103, v81 row_newbcast:1 row_mask:0xf bank_mask:0xf
	v_fmac_f32_dpp v124, v103, v82 row_newbcast:2 row_mask:0xf bank_mask:0xf
	v_fmac_f32_dpp v125, v103, v83 row_newbcast:3 row_mask:0xf bank_mask:0xf
	v_mfma_f32_32x32x2_f32 v[48:63], v139, v109, v[80:95]
	v_fmac_f32_dpp v124, v103, v84 row_newbcast:4 row_mask:0xf bank_mask:0xf
	v_fmac_f32_dpp v125, v103, v85 row_newbcast:5 row_mask:0xf bank_mask:0xf
	v_fmac_f32_dpp v124, v103, v86 row_newbcast:6 row_mask:0xf bank_mask:0xf
	v_fmac_f32_dpp v125, v103, v87 row_newbcast:7 row_mask:0xf bank_mask:0xf
	v_fmac_f32_dpp v124, v103, v88 row_newbcast:8 row_mask:0xf bank_mask:0xf
	v_fmac_f32_dpp v125, v103, v89 row_newbcast:9 row_mask:0xf bank_mask:0xf
	v_fmac_f32_dpp v124, v103, v90 row_newbcast:10 row_mask:0xf bank_mask:0xf
	v_fmac_f32_dpp v125, v103, v91 row_newbcast:11 row_mask:0xf bank_mask:0xf
	v_fmac_f32_dpp v124, v103, v92 row_newbcast:12 row_mask:0xf bank_mask:0xf
	v_fmac_f32_dpp v125, v103, v93 row_newbcast:13 row_mask:0xf bank_mask:0xf
	v_fmac_f32_dpp v124, v103, v94 row_newbcast:14 row_mask:0xf bank_mask:0xf
	v_fmac_f32_dpp v125, v103, v95 row_newbcast:15 row_mask:0xf bank_mask:0xf
	v_add_f32_e32 v130, v124, v125
	s_waitcnt lgkmcnt(0)
	ds_read2st64_b32 v[114:115], v14 offset0:19 offset1:22
	ds_read2st64_b32 v[116:117], v17 offset0:19 offset1:22
	ds_read_b32 v138, v15 offset:4608
	ds_read_b32 v139, v15 offset:4736
	ds_read_b32 v109, v16 offset:4608
	v_mul_f32_dpp v120, v110, v32 row_newbcast:0 row_mask:0xf bank_mask:0xf
	v_mul_f32_dpp v121, v110, v33 row_newbcast:1 row_mask:0xf bank_mask:0xf
	v_fmac_f32_dpp v120, v110, v34 row_newbcast:2 row_mask:0xf bank_mask:0xf
	v_fmac_f32_dpp v121, v110, v35 row_newbcast:3 row_mask:0xf bank_mask:0xf
	v_fmac_f32_dpp v120, v110, v36 row_newbcast:4 row_mask:0xf bank_mask:0xf
	v_fmac_f32_dpp v121, v110, v37 row_newbcast:5 row_mask:0xf bank_mask:0xf
	v_fmac_f32_dpp v120, v110, v38 row_newbcast:6 row_mask:0xf bank_mask:0xf
	v_fmac_f32_dpp v121, v110, v39 row_newbcast:7 row_mask:0xf bank_mask:0xf
	v_fmac_f32_dpp v120, v110, v40 row_newbcast:8 row_mask:0xf bank_mask:0xf
	v_fmac_f32_dpp v121, v110, v41 row_newbcast:9 row_mask:0xf bank_mask:0xf
	v_fmac_f32_dpp v120, v110, v42 row_newbcast:10 row_mask:0xf bank_mask:0xf
	v_fmac_f32_dpp v121, v110, v43 row_newbcast:11 row_mask:0xf bank_mask:0xf
	v_fmac_f32_dpp v120, v110, v44 row_newbcast:12 row_mask:0xf bank_mask:0xf
	v_fmac_f32_dpp v121, v110, v45 row_newbcast:13 row_mask:0xf bank_mask:0xf
	v_fmac_f32_dpp v120, v110, v46 row_newbcast:14 row_mask:0xf bank_mask:0xf
	v_fmac_f32_dpp v121, v110, v47 row_newbcast:15 row_mask:0xf bank_mask:0xf
	v_fmac_f32_dpp v120, v112, v48 row_newbcast:0 row_mask:0xf bank_mask:0xf
	v_fmac_f32_dpp v121, v112, v49 row_newbcast:1 row_mask:0xf bank_mask:0xf
	v_fmac_f32_dpp v120, v112, v50 row_newbcast:2 row_mask:0xf bank_mask:0xf
	v_fmac_f32_dpp v121, v112, v51 row_newbcast:3 row_mask:0xf bank_mask:0xf
	v_fmac_f32_dpp v120, v112, v52 row_newbcast:4 row_mask:0xf bank_mask:0xf
	v_fmac_f32_dpp v121, v112, v53 row_newbcast:5 row_mask:0xf bank_mask:0xf
	v_fmac_f32_dpp v120, v112, v54 row_newbcast:6 row_mask:0xf bank_mask:0xf
	v_fmac_f32_dpp v121, v112, v55 row_newbcast:7 row_mask:0xf bank_mask:0xf
	v_fmac_f32_dpp v120, v112, v56 row_newbcast:8 row_mask:0xf bank_mask:0xf
	v_fmac_f32_dpp v121, v112, v57 row_newbcast:9 row_mask:0xf bank_mask:0xf
	v_fmac_f32_dpp v120, v112, v58 row_newbcast:10 row_mask:0xf bank_mask:0xf
	v_fmac_f32_dpp v121, v112, v59 row_newbcast:11 row_mask:0xf bank_mask:0xf
	v_fmac_f32_dpp v120, v112, v60 row_newbcast:12 row_mask:0xf bank_mask:0xf
	v_fmac_f32_dpp v121, v112, v61 row_newbcast:13 row_mask:0xf bank_mask:0xf
	v_fmac_f32_dpp v120, v112, v62 row_newbcast:14 row_mask:0xf bank_mask:0xf
	v_fmac_f32_dpp v121, v112, v63 row_newbcast:15 row_mask:0xf bank_mask:0xf
	v_add_f32_e32 v128, v120, v121
	v_mul_f32_dpp v124, v105, v32 row_newbcast:0 row_mask:0xf bank_mask:0xf
	v_mul_f32_dpp v125, v105, v33 row_newbcast:1 row_mask:0xf bank_mask:0xf
	v_permlane32_swap_b32 v129, v128
	v_fmac_f32_dpp v124, v105, v34 row_newbcast:2 row_mask:0xf bank_mask:0xf
	v_fmac_f32_dpp v125, v105, v35 row_newbcast:3 row_mask:0xf bank_mask:0xf
	v_add_f32_dpp v108, -v129, -v128 quad_perm:[0,1,2,3] row_mask:0xc bank_mask:0xf
	v_fmac_f32_dpp v124, v105, v36 row_newbcast:4 row_mask:0xf bank_mask:0xf
	v_fmac_f32_dpp v125, v105, v37 row_newbcast:5 row_mask:0xf bank_mask:0xf
	v_mfma_f32_32x32x2_f32 v[64:79], v136, v108, v[32:47]
	v_fmac_f32_dpp v124, v105, v38 row_newbcast:6 row_mask:0xf bank_mask:0xf
	v_fmac_f32_dpp v125, v105, v39 row_newbcast:7 row_mask:0xf bank_mask:0xf
	v_fmac_f32_dpp v124, v105, v40 row_newbcast:8 row_mask:0xf bank_mask:0xf
	v_fmac_f32_dpp v125, v105, v41 row_newbcast:9 row_mask:0xf bank_mask:0xf
	v_fmac_f32_dpp v124, v105, v42 row_newbcast:10 row_mask:0xf bank_mask:0xf
	v_fmac_f32_dpp v125, v105, v43 row_newbcast:11 row_mask:0xf bank_mask:0xf
	v_fmac_f32_dpp v124, v105, v44 row_newbcast:12 row_mask:0xf bank_mask:0xf
	v_fmac_f32_dpp v125, v105, v45 row_newbcast:13 row_mask:0xf bank_mask:0xf
	v_fmac_f32_dpp v124, v105, v46 row_newbcast:14 row_mask:0xf bank_mask:0xf
	v_fmac_f32_dpp v125, v105, v47 row_newbcast:15 row_mask:0xf bank_mask:0xf
	v_fmac_f32_dpp v124, v107, v48 row_newbcast:0 row_mask:0xf bank_mask:0xf
	v_fmac_f32_dpp v125, v107, v49 row_newbcast:1 row_mask:0xf bank_mask:0xf
	v_fmac_f32_dpp v124, v107, v50 row_newbcast:2 row_mask:0xf bank_mask:0xf
	v_fmac_f32_dpp v125, v107, v51 row_newbcast:3 row_mask:0xf bank_mask:0xf
	v_mfma_f32_32x32x2_f32 v[80:95], v137, v108, v[48:63]
	v_fmac_f32_dpp v124, v107, v52 row_newbcast:4 row_mask:0xf bank_mask:0xf
	v_fmac_f32_dpp v125, v107, v53 row_newbcast:5 row_mask:0xf bank_mask:0xf
	v_fmac_f32_dpp v124, v107, v54 row_newbcast:6 row_mask:0xf bank_mask:0xf
	v_fmac_f32_dpp v125, v107, v55 row_newbcast:7 row_mask:0xf bank_mask:0xf
	v_fmac_f32_dpp v124, v107, v56 row_newbcast:8 row_mask:0xf bank_mask:0xf
	v_fmac_f32_dpp v125, v107, v57 row_newbcast:9 row_mask:0xf bank_mask:0xf
	v_fmac_f32_dpp v124, v107, v58 row_newbcast:10 row_mask:0xf bank_mask:0xf
	v_fmac_f32_dpp v125, v107, v59 row_newbcast:11 row_mask:0xf bank_mask:0xf
	v_fmac_f32_dpp v124, v107, v60 row_newbcast:12 row_mask:0xf bank_mask:0xf
	v_fmac_f32_dpp v125, v107, v61 row_newbcast:13 row_mask:0xf bank_mask:0xf
	v_fmac_f32_dpp v124, v107, v62 row_newbcast:14 row_mask:0xf bank_mask:0xf
	v_fmac_f32_dpp v125, v107, v63 row_newbcast:15 row_mask:0xf bank_mask:0xf
	v_add_f32_e32 v131, v124, v125
	s_nop 1
	v_permlane32_swap_b32 v130, v131
	v_add_f32_e32 v133, v130, v131
	v_cvt_pk_bf16_f32 v133, v133, v133
	global_store_short v13, v133, s[16:17]
	s_add_u32 s16, s16, s20
	s_addc_u32 s17, s17, s21
	s_waitcnt lgkmcnt(0)
	ds_read2st64_b32 v[100:101], v14 offset0:25 offset1:28
	ds_read2st64_b32 v[102:103], v17 offset0:25 offset1:28
	ds_read_b32 v136, v15 offset:6144
	ds_read_b32 v137, v15 offset:6272
	ds_read_b32 v108, v16 offset:6144
	v_mul_f32_dpp v120, v114, v64 row_newbcast:0 row_mask:0xf bank_mask:0xf
	v_mul_f32_dpp v121, v114, v65 row_newbcast:1 row_mask:0xf bank_mask:0xf
	v_fmac_f32_dpp v120, v114, v66 row_newbcast:2 row_mask:0xf bank_mask:0xf
	v_fmac_f32_dpp v121, v114, v67 row_newbcast:3 row_mask:0xf bank_mask:0xf
	v_fmac_f32_dpp v120, v114, v68 row_newbcast:4 row_mask:0xf bank_mask:0xf
	v_fmac_f32_dpp v121, v114, v69 row_newbcast:5 row_mask:0xf bank_mask:0xf
	v_fmac_f32_dpp v120, v114, v70 row_newbcast:6 row_mask:0xf bank_mask:0xf
	v_fmac_f32_dpp v121, v114, v71 row_newbcast:7 row_mask:0xf bank_mask:0xf
	v_fmac_f32_dpp v120, v114, v72 row_newbcast:8 row_mask:0xf bank_mask:0xf
	v_fmac_f32_dpp v121, v114, v73 row_newbcast:9 row_mask:0xf bank_mask:0xf
	v_fmac_f32_dpp v120, v114, v74 row_newbcast:10 row_mask:0xf bank_mask:0xf
	v_fmac_f32_dpp v121, v114, v75 row_newbcast:11 row_mask:0xf bank_mask:0xf
	v_fmac_f32_dpp v120, v114, v76 row_newbcast:12 row_mask:0xf bank_mask:0xf
	v_fmac_f32_dpp v121, v114, v77 row_newbcast:13 row_mask:0xf bank_mask:0xf
	v_fmac_f32_dpp v120, v114, v78 row_newbcast:14 row_mask:0xf bank_mask:0xf
	v_fmac_f32_dpp v121, v114, v79 row_newbcast:15 row_mask:0xf bank_mask:0xf
	v_fmac_f32_dpp v120, v116, v80 row_newbcast:0 row_mask:0xf bank_mask:0xf
	v_fmac_f32_dpp v121, v116, v81 row_newbcast:1 row_mask:0xf bank_mask:0xf
	v_fmac_f32_dpp v120, v116, v82 row_newbcast:2 row_mask:0xf bank_mask:0xf
	v_fmac_f32_dpp v121, v116, v83 row_newbcast:3 row_mask:0xf bank_mask:0xf
	v_fmac_f32_dpp v120, v116, v84 row_newbcast:4 row_mask:0xf bank_mask:0xf
	v_fmac_f32_dpp v121, v116, v85 row_newbcast:5 row_mask:0xf bank_mask:0xf
	v_fmac_f32_dpp v120, v116, v86 row_newbcast:6 row_mask:0xf bank_mask:0xf
	v_fmac_f32_dpp v121, v116, v87 row_newbcast:7 row_mask:0xf bank_mask:0xf
	v_fmac_f32_dpp v120, v116, v88 row_newbcast:8 row_mask:0xf bank_mask:0xf
	v_fmac_f32_dpp v121, v116, v89 row_newbcast:9 row_mask:0xf bank_mask:0xf
	v_fmac_f32_dpp v120, v116, v90 row_newbcast:10 row_mask:0xf bank_mask:0xf
	v_fmac_f32_dpp v121, v116, v91 row_newbcast:11 row_mask:0xf bank_mask:0xf
	v_fmac_f32_dpp v120, v116, v92 row_newbcast:12 row_mask:0xf bank_mask:0xf
	v_fmac_f32_dpp v121, v116, v93 row_newbcast:13 row_mask:0xf bank_mask:0xf
	v_fmac_f32_dpp v120, v116, v94 row_newbcast:14 row_mask:0xf bank_mask:0xf
	v_fmac_f32_dpp v121, v116, v95 row_newbcast:15 row_mask:0xf bank_mask:0xf
	v_add_f32_e32 v128, v120, v121
	v_mul_f32_dpp v124, v111, v64 row_newbcast:0 row_mask:0xf bank_mask:0xf
	v_mul_f32_dpp v125, v111, v65 row_newbcast:1 row_mask:0xf bank_mask:0xf
	v_permlane32_swap_b32 v129, v128
	v_fmac_f32_dpp v124, v111, v66 row_newbcast:2 row_mask:0xf bank_mask:0xf
	v_fmac_f32_dpp v125, v111, v67 row_newbcast:3 row_mask:0xf bank_mask:0xf
	v_add_f32_dpp v109, -v129, -v128 quad_perm:[0,1,2,3] row_mask:0xc bank_mask:0xf
	v_fmac_f32_dpp v124, v111, v68 row_newbcast:4 row_mask:0xf bank_mask:0xf
	v_fmac_f32_dpp v125, v111, v69 row_newbcast:5 row_mask:0xf bank_mask:0xf
	v_mfma_f32_32x32x2_f32 v[32:47], v138, v109, v[64:79]
	v_fmac_f32_dpp v124, v111, v70 row_newbcast:6 row_mask:0xf bank_mask:0xf
	v_fmac_f32_dpp v125, v111, v71 row_newbcast:7 row_mask:0xf bank_mask:0xf
	v_fmac_f32_dpp v124, v111, v72 row_newbcast:8 row_mask:0xf bank_mask:0xf
	v_fmac_f32_dpp v125, v111, v73 row_newbcast:9 row_mask:0xf bank_mask:0xf
	v_fmac_f32_dpp v124, v111, v74 row_newbcast:10 row_mask:0xf bank_mask:0xf
	v_fmac_f32_dpp v125, v111, v75 row_newbcast:11 row_mask:0xf bank_mask:0xf
	v_fmac_f32_dpp v124, v111, v76 row_newbcast:12 row_mask:0xf bank_mask:0xf
	v_fmac_f32_dpp v125, v111, v77 row_newbcast:13 row_mask:0xf bank_mask:0xf
	v_fmac_f32_dpp v124, v111, v78 row_newbcast:14 row_mask:0xf bank_mask:0xf
	v_fmac_f32_dpp v125, v111, v79 row_newbcast:15 row_mask:0xf bank_mask:0xf
	v_fmac_f32_dpp v124, v113, v80 row_newbcast:0 row_mask:0xf bank_mask:0xf
	v_fmac_f32_dpp v125, v113, v81 row_newbcast:1 row_mask:0xf bank_mask:0xf
	v_fmac_f32_dpp v124, v113, v82 row_newbcast:2 row_mask:0xf bank_mask:0xf
	v_fmac_f32_dpp v125, v113, v83 row_newbcast:3 row_mask:0xf bank_mask:0xf
	v_mfma_f32_32x32x2_f32 v[48:63], v139, v109, v[80:95]
	v_fmac_f32_dpp v124, v113, v84 row_newbcast:4 row_mask:0xf bank_mask:0xf
	v_fmac_f32_dpp v125, v113, v85 row_newbcast:5 row_mask:0xf bank_mask:0xf
	v_fmac_f32_dpp v124, v113, v86 row_newbcast:6 row_mask:0xf bank_mask:0xf
	v_fmac_f32_dpp v125, v113, v87 row_newbcast:7 row_mask:0xf bank_mask:0xf
	v_fmac_f32_dpp v124, v113, v88 row_newbcast:8 row_mask:0xf bank_mask:0xf
	v_fmac_f32_dpp v125, v113, v89 row_newbcast:9 row_mask:0xf bank_mask:0xf
	v_fmac_f32_dpp v124, v113, v90 row_newbcast:10 row_mask:0xf bank_mask:0xf
	v_fmac_f32_dpp v125, v113, v91 row_newbcast:11 row_mask:0xf bank_mask:0xf
	v_fmac_f32_dpp v124, v113, v92 row_newbcast:12 row_mask:0xf bank_mask:0xf
	v_fmac_f32_dpp v125, v113, v93 row_newbcast:13 row_mask:0xf bank_mask:0xf
	v_fmac_f32_dpp v124, v113, v94 row_newbcast:14 row_mask:0xf bank_mask:0xf
	v_fmac_f32_dpp v125, v113, v95 row_newbcast:15 row_mask:0xf bank_mask:0xf
	v_add_f32_e32 v130, v124, v125
	s_waitcnt lgkmcnt(0)
	ds_read2st64_b32 v[104:105], v14 offset0:31 offset1:34
	ds_read2st64_b32 v[106:107], v17 offset0:31 offset1:34
	ds_read_b32 v138, v15 offset:7680
	ds_read_b32 v139, v15 offset:7808
	ds_read_b32 v109, v16 offset:7680
	v_mul_f32_dpp v120, v100, v32 row_newbcast:0 row_mask:0xf bank_mask:0xf
	v_mul_f32_dpp v121, v100, v33 row_newbcast:1 row_mask:0xf bank_mask:0xf
	v_fmac_f32_dpp v120, v100, v34 row_newbcast:2 row_mask:0xf bank_mask:0xf
	v_fmac_f32_dpp v121, v100, v35 row_newbcast:3 row_mask:0xf bank_mask:0xf
	v_fmac_f32_dpp v120, v100, v36 row_newbcast:4 row_mask:0xf bank_mask:0xf
	v_fmac_f32_dpp v121, v100, v37 row_newbcast:5 row_mask:0xf bank_mask:0xf
	v_fmac_f32_dpp v120, v100, v38 row_newbcast:6 row_mask:0xf bank_mask:0xf
	v_fmac_f32_dpp v121, v100, v39 row_newbcast:7 row_mask:0xf bank_mask:0xf
	v_fmac_f32_dpp v120, v100, v40 row_newbcast:8 row_mask:0xf bank_mask:0xf
	v_fmac_f32_dpp v121, v100, v41 row_newbcast:9 row_mask:0xf bank_mask:0xf
	v_fmac_f32_dpp v120, v100, v42 row_newbcast:10 row_mask:0xf bank_mask:0xf
	v_fmac_f32_dpp v121, v100, v43 row_newbcast:11 row_mask:0xf bank_mask:0xf
	v_fmac_f32_dpp v120, v100, v44 row_newbcast:12 row_mask:0xf bank_mask:0xf
	v_fmac_f32_dpp v121, v100, v45 row_newbcast:13 row_mask:0xf bank_mask:0xf
	v_fmac_f32_dpp v120, v100, v46 row_newbcast:14 row_mask:0xf bank_mask:0xf
	v_fmac_f32_dpp v121, v100, v47 row_newbcast:15 row_mask:0xf bank_mask:0xf
	v_fmac_f32_dpp v120, v102, v48 row_newbcast:0 row_mask:0xf bank_mask:0xf
	v_fmac_f32_dpp v121, v102, v49 row_newbcast:1 row_mask:0xf bank_mask:0xf
	v_fmac_f32_dpp v120, v102, v50 row_newbcast:2 row_mask:0xf bank_mask:0xf
	v_fmac_f32_dpp v121, v102, v51 row_newbcast:3 row_mask:0xf bank_mask:0xf
	v_fmac_f32_dpp v120, v102, v52 row_newbcast:4 row_mask:0xf bank_mask:0xf
	v_fmac_f32_dpp v121, v102, v53 row_newbcast:5 row_mask:0xf bank_mask:0xf
	v_fmac_f32_dpp v120, v102, v54 row_newbcast:6 row_mask:0xf bank_mask:0xf
	v_fmac_f32_dpp v121, v102, v55 row_newbcast:7 row_mask:0xf bank_mask:0xf
	v_fmac_f32_dpp v120, v102, v56 row_newbcast:8 row_mask:0xf bank_mask:0xf
	v_fmac_f32_dpp v121, v102, v57 row_newbcast:9 row_mask:0xf bank_mask:0xf
	v_fmac_f32_dpp v120, v102, v58 row_newbcast:10 row_mask:0xf bank_mask:0xf
	v_fmac_f32_dpp v121, v102, v59 row_newbcast:11 row_mask:0xf bank_mask:0xf
	v_fmac_f32_dpp v120, v102, v60 row_newbcast:12 row_mask:0xf bank_mask:0xf
	v_fmac_f32_dpp v121, v102, v61 row_newbcast:13 row_mask:0xf bank_mask:0xf
	v_fmac_f32_dpp v120, v102, v62 row_newbcast:14 row_mask:0xf bank_mask:0xf
	v_fmac_f32_dpp v121, v102, v63 row_newbcast:15 row_mask:0xf bank_mask:0xf
	v_add_f32_e32 v128, v120, v121
	v_mul_f32_dpp v124, v115, v32 row_newbcast:0 row_mask:0xf bank_mask:0xf
	v_mul_f32_dpp v125, v115, v33 row_newbcast:1 row_mask:0xf bank_mask:0xf
	v_permlane32_swap_b32 v129, v128
	v_fmac_f32_dpp v124, v115, v34 row_newbcast:2 row_mask:0xf bank_mask:0xf
	v_fmac_f32_dpp v125, v115, v35 row_newbcast:3 row_mask:0xf bank_mask:0xf
	v_add_f32_dpp v108, -v129, -v128 quad_perm:[0,1,2,3] row_mask:0xc bank_mask:0xf
	v_fmac_f32_dpp v124, v115, v36 row_newbcast:4 row_mask:0xf bank_mask:0xf
	v_fmac_f32_dpp v125, v115, v37 row_newbcast:5 row_mask:0xf bank_mask:0xf
	v_mfma_f32_32x32x2_f32 v[64:79], v136, v108, v[32:47]
	v_fmac_f32_dpp v124, v115, v38 row_newbcast:6 row_mask:0xf bank_mask:0xf
	v_fmac_f32_dpp v125, v115, v39 row_newbcast:7 row_mask:0xf bank_mask:0xf
	v_fmac_f32_dpp v124, v115, v40 row_newbcast:8 row_mask:0xf bank_mask:0xf
	v_fmac_f32_dpp v125, v115, v41 row_newbcast:9 row_mask:0xf bank_mask:0xf
	v_fmac_f32_dpp v124, v115, v42 row_newbcast:10 row_mask:0xf bank_mask:0xf
	v_fmac_f32_dpp v125, v115, v43 row_newbcast:11 row_mask:0xf bank_mask:0xf
	v_fmac_f32_dpp v124, v115, v44 row_newbcast:12 row_mask:0xf bank_mask:0xf
	v_fmac_f32_dpp v125, v115, v45 row_newbcast:13 row_mask:0xf bank_mask:0xf
	v_fmac_f32_dpp v124, v115, v46 row_newbcast:14 row_mask:0xf bank_mask:0xf
	v_fmac_f32_dpp v125, v115, v47 row_newbcast:15 row_mask:0xf bank_mask:0xf
	v_fmac_f32_dpp v124, v117, v48 row_newbcast:0 row_mask:0xf bank_mask:0xf
	v_fmac_f32_dpp v125, v117, v49 row_newbcast:1 row_mask:0xf bank_mask:0xf
	v_fmac_f32_dpp v124, v117, v50 row_newbcast:2 row_mask:0xf bank_mask:0xf
	v_fmac_f32_dpp v125, v117, v51 row_newbcast:3 row_mask:0xf bank_mask:0xf
	v_mfma_f32_32x32x2_f32 v[80:95], v137, v108, v[48:63]
	v_fmac_f32_dpp v124, v117, v52 row_newbcast:4 row_mask:0xf bank_mask:0xf
	v_fmac_f32_dpp v125, v117, v53 row_newbcast:5 row_mask:0xf bank_mask:0xf
	v_fmac_f32_dpp v124, v117, v54 row_newbcast:6 row_mask:0xf bank_mask:0xf
	v_fmac_f32_dpp v125, v117, v55 row_newbcast:7 row_mask:0xf bank_mask:0xf
	v_fmac_f32_dpp v124, v117, v56 row_newbcast:8 row_mask:0xf bank_mask:0xf
	v_fmac_f32_dpp v125, v117, v57 row_newbcast:9 row_mask:0xf bank_mask:0xf
	v_fmac_f32_dpp v124, v117, v58 row_newbcast:10 row_mask:0xf bank_mask:0xf
	v_fmac_f32_dpp v125, v117, v59 row_newbcast:11 row_mask:0xf bank_mask:0xf
	v_fmac_f32_dpp v124, v117, v60 row_newbcast:12 row_mask:0xf bank_mask:0xf
	v_fmac_f32_dpp v125, v117, v61 row_newbcast:13 row_mask:0xf bank_mask:0xf
	v_fmac_f32_dpp v124, v117, v62 row_newbcast:14 row_mask:0xf bank_mask:0xf
	v_fmac_f32_dpp v125, v117, v63 row_newbcast:15 row_mask:0xf bank_mask:0xf
	v_add_f32_e32 v131, v124, v125
	s_nop 1
	v_permlane32_swap_b32 v130, v131
	v_add_f32_e32 v133, v130, v131
	v_cvt_pk_bf16_f32 v133, v133, v133
	global_store_short v13, v133, s[16:17]
	s_add_u32 s16, s16, s20
	s_addc_u32 s17, s17, s21
	s_waitcnt lgkmcnt(0)
	ds_read2st64_b32 v[110:111], v14 offset0:37 offset1:40
	ds_read2st64_b32 v[112:113], v17 offset0:37 offset1:40
	ds_read_b32 v136, v15 offset:9216
	ds_read_b32 v137, v15 offset:9344
	ds_read_b32 v108, v16 offset:9216
	v_mul_f32_dpp v120, v104, v64 row_newbcast:0 row_mask:0xf bank_mask:0xf
	v_mul_f32_dpp v121, v104, v65 row_newbcast:1 row_mask:0xf bank_mask:0xf
	v_fmac_f32_dpp v120, v104, v66 row_newbcast:2 row_mask:0xf bank_mask:0xf
	v_fmac_f32_dpp v121, v104, v67 row_newbcast:3 row_mask:0xf bank_mask:0xf
	v_fmac_f32_dpp v120, v104, v68 row_newbcast:4 row_mask:0xf bank_mask:0xf
	v_fmac_f32_dpp v121, v104, v69 row_newbcast:5 row_mask:0xf bank_mask:0xf
	v_fmac_f32_dpp v120, v104, v70 row_newbcast:6 row_mask:0xf bank_mask:0xf
	v_fmac_f32_dpp v121, v104, v71 row_newbcast:7 row_mask:0xf bank_mask:0xf
	v_fmac_f32_dpp v120, v104, v72 row_newbcast:8 row_mask:0xf bank_mask:0xf
	v_fmac_f32_dpp v121, v104, v73 row_newbcast:9 row_mask:0xf bank_mask:0xf
	v_fmac_f32_dpp v120, v104, v74 row_newbcast:10 row_mask:0xf bank_mask:0xf
	v_fmac_f32_dpp v121, v104, v75 row_newbcast:11 row_mask:0xf bank_mask:0xf
	v_fmac_f32_dpp v120, v104, v76 row_newbcast:12 row_mask:0xf bank_mask:0xf
	v_fmac_f32_dpp v121, v104, v77 row_newbcast:13 row_mask:0xf bank_mask:0xf
	v_fmac_f32_dpp v120, v104, v78 row_newbcast:14 row_mask:0xf bank_mask:0xf
	v_fmac_f32_dpp v121, v104, v79 row_newbcast:15 row_mask:0xf bank_mask:0xf
	v_fmac_f32_dpp v120, v106, v80 row_newbcast:0 row_mask:0xf bank_mask:0xf
	v_fmac_f32_dpp v121, v106, v81 row_newbcast:1 row_mask:0xf bank_mask:0xf
	v_fmac_f32_dpp v120, v106, v82 row_newbcast:2 row_mask:0xf bank_mask:0xf
	v_fmac_f32_dpp v121, v106, v83 row_newbcast:3 row_mask:0xf bank_mask:0xf
	v_fmac_f32_dpp v120, v106, v84 row_newbcast:4 row_mask:0xf bank_mask:0xf
	v_fmac_f32_dpp v121, v106, v85 row_newbcast:5 row_mask:0xf bank_mask:0xf
	v_fmac_f32_dpp v120, v106, v86 row_newbcast:6 row_mask:0xf bank_mask:0xf
	v_fmac_f32_dpp v121, v106, v87 row_newbcast:7 row_mask:0xf bank_mask:0xf
	v_fmac_f32_dpp v120, v106, v88 row_newbcast:8 row_mask:0xf bank_mask:0xf
	v_fmac_f32_dpp v121, v106, v89 row_newbcast:9 row_mask:0xf bank_mask:0xf
	v_fmac_f32_dpp v120, v106, v90 row_newbcast:10 row_mask:0xf bank_mask:0xf
	v_fmac_f32_dpp v121, v106, v91 row_newbcast:11 row_mask:0xf bank_mask:0xf
	v_fmac_f32_dpp v120, v106, v92 row_newbcast:12 row_mask:0xf bank_mask:0xf
	v_fmac_f32_dpp v121, v106, v93 row_newbcast:13 row_mask:0xf bank_mask:0xf
	v_fmac_f32_dpp v120, v106, v94 row_newbcast:14 row_mask:0xf bank_mask:0xf
	v_fmac_f32_dpp v121, v106, v95 row_newbcast:15 row_mask:0xf bank_mask:0xf
	v_add_f32_e32 v128, v120, v121
	v_mul_f32_dpp v124, v101, v64 row_newbcast:0 row_mask:0xf bank_mask:0xf
	v_mul_f32_dpp v125, v101, v65 row_newbcast:1 row_mask:0xf bank_mask:0xf
	v_permlane32_swap_b32 v129, v128
	v_fmac_f32_dpp v124, v101, v66 row_newbcast:2 row_mask:0xf bank_mask:0xf
	v_fmac_f32_dpp v125, v101, v67 row_newbcast:3 row_mask:0xf bank_mask:0xf
	v_add_f32_dpp v109, -v129, -v128 quad_perm:[0,1,2,3] row_mask:0xc bank_mask:0xf
	v_fmac_f32_dpp v124, v101, v68 row_newbcast:4 row_mask:0xf bank_mask:0xf
	v_fmac_f32_dpp v125, v101, v69 row_newbcast:5 row_mask:0xf bank_mask:0xf
	v_mfma_f32_32x32x2_f32 v[32:47], v138, v109, v[64:79]
	v_fmac_f32_dpp v124, v101, v70 row_newbcast:6 row_mask:0xf bank_mask:0xf
	v_fmac_f32_dpp v125, v101, v71 row_newbcast:7 row_mask:0xf bank_mask:0xf
	v_fmac_f32_dpp v124, v101, v72 row_newbcast:8 row_mask:0xf bank_mask:0xf
	v_fmac_f32_dpp v125, v101, v73 row_newbcast:9 row_mask:0xf bank_mask:0xf
	v_fmac_f32_dpp v124, v101, v74 row_newbcast:10 row_mask:0xf bank_mask:0xf
	v_fmac_f32_dpp v125, v101, v75 row_newbcast:11 row_mask:0xf bank_mask:0xf
	v_fmac_f32_dpp v124, v101, v76 row_newbcast:12 row_mask:0xf bank_mask:0xf
	v_fmac_f32_dpp v125, v101, v77 row_newbcast:13 row_mask:0xf bank_mask:0xf
	v_fmac_f32_dpp v124, v101, v78 row_newbcast:14 row_mask:0xf bank_mask:0xf
	v_fmac_f32_dpp v125, v101, v79 row_newbcast:15 row_mask:0xf bank_mask:0xf
	v_fmac_f32_dpp v124, v103, v80 row_newbcast:0 row_mask:0xf bank_mask:0xf
	v_fmac_f32_dpp v125, v103, v81 row_newbcast:1 row_mask:0xf bank_mask:0xf
	v_fmac_f32_dpp v124, v103, v82 row_newbcast:2 row_mask:0xf bank_mask:0xf
	v_fmac_f32_dpp v125, v103, v83 row_newbcast:3 row_mask:0xf bank_mask:0xf
	v_mfma_f32_32x32x2_f32 v[48:63], v139, v109, v[80:95]
	v_fmac_f32_dpp v124, v103, v84 row_newbcast:4 row_mask:0xf bank_mask:0xf
	v_fmac_f32_dpp v125, v103, v85 row_newbcast:5 row_mask:0xf bank_mask:0xf
	v_fmac_f32_dpp v124, v103, v86 row_newbcast:6 row_mask:0xf bank_mask:0xf
	v_fmac_f32_dpp v125, v103, v87 row_newbcast:7 row_mask:0xf bank_mask:0xf
	v_fmac_f32_dpp v124, v103, v88 row_newbcast:8 row_mask:0xf bank_mask:0xf
	v_fmac_f32_dpp v125, v103, v89 row_newbcast:9 row_mask:0xf bank_mask:0xf
	v_fmac_f32_dpp v124, v103, v90 row_newbcast:10 row_mask:0xf bank_mask:0xf
	v_fmac_f32_dpp v125, v103, v91 row_newbcast:11 row_mask:0xf bank_mask:0xf
	v_fmac_f32_dpp v124, v103, v92 row_newbcast:12 row_mask:0xf bank_mask:0xf
	v_fmac_f32_dpp v125, v103, v93 row_newbcast:13 row_mask:0xf bank_mask:0xf
	v_fmac_f32_dpp v124, v103, v94 row_newbcast:14 row_mask:0xf bank_mask:0xf
	v_fmac_f32_dpp v125, v103, v95 row_newbcast:15 row_mask:0xf bank_mask:0xf
	v_add_f32_e32 v130, v124, v125
	s_waitcnt lgkmcnt(0)
	ds_read2st64_b32 v[114:115], v14 offset0:43 offset1:46
	ds_read2st64_b32 v[116:117], v17 offset0:43 offset1:46
	ds_read_b32 v138, v15 offset:10752
	ds_read_b32 v139, v15 offset:10880
	ds_read_b32 v109, v16 offset:10752
	ds_read_b32 v118, v14 offset:10752
	ds_read_b32 v119, v14 offset:10880
	v_mul_f32_dpp v120, v110, v32 row_newbcast:0 row_mask:0xf bank_mask:0xf
	v_mul_f32_dpp v121, v110, v33 row_newbcast:1 row_mask:0xf bank_mask:0xf
	v_fmac_f32_dpp v120, v110, v34 row_newbcast:2 row_mask:0xf bank_mask:0xf
	v_fmac_f32_dpp v121, v110, v35 row_newbcast:3 row_mask:0xf bank_mask:0xf
	v_fmac_f32_dpp v120, v110, v36 row_newbcast:4 row_mask:0xf bank_mask:0xf
	v_fmac_f32_dpp v121, v110, v37 row_newbcast:5 row_mask:0xf bank_mask:0xf
	v_fmac_f32_dpp v120, v110, v38 row_newbcast:6 row_mask:0xf bank_mask:0xf
	v_fmac_f32_dpp v121, v110, v39 row_newbcast:7 row_mask:0xf bank_mask:0xf
	v_fmac_f32_dpp v120, v110, v40 row_newbcast:8 row_mask:0xf bank_mask:0xf
	v_fmac_f32_dpp v121, v110, v41 row_newbcast:9 row_mask:0xf bank_mask:0xf
	v_fmac_f32_dpp v120, v110, v42 row_newbcast:10 row_mask:0xf bank_mask:0xf
	v_fmac_f32_dpp v121, v110, v43 row_newbcast:11 row_mask:0xf bank_mask:0xf
	v_fmac_f32_dpp v120, v110, v44 row_newbcast:12 row_mask:0xf bank_mask:0xf
	v_fmac_f32_dpp v121, v110, v45 row_newbcast:13 row_mask:0xf bank_mask:0xf
	v_fmac_f32_dpp v120, v110, v46 row_newbcast:14 row_mask:0xf bank_mask:0xf
	v_fmac_f32_dpp v121, v110, v47 row_newbcast:15 row_mask:0xf bank_mask:0xf
	v_fmac_f32_dpp v120, v112, v48 row_newbcast:0 row_mask:0xf bank_mask:0xf
	v_fmac_f32_dpp v121, v112, v49 row_newbcast:1 row_mask:0xf bank_mask:0xf
	v_fmac_f32_dpp v120, v112, v50 row_newbcast:2 row_mask:0xf bank_mask:0xf
	v_fmac_f32_dpp v121, v112, v51 row_newbcast:3 row_mask:0xf bank_mask:0xf
	v_fmac_f32_dpp v120, v112, v52 row_newbcast:4 row_mask:0xf bank_mask:0xf
	v_fmac_f32_dpp v121, v112, v53 row_newbcast:5 row_mask:0xf bank_mask:0xf
	v_fmac_f32_dpp v120, v112, v54 row_newbcast:6 row_mask:0xf bank_mask:0xf
	v_fmac_f32_dpp v121, v112, v55 row_newbcast:7 row_mask:0xf bank_mask:0xf
	v_fmac_f32_dpp v120, v112, v56 row_newbcast:8 row_mask:0xf bank_mask:0xf
	v_fmac_f32_dpp v121, v112, v57 row_newbcast:9 row_mask:0xf bank_mask:0xf
	v_fmac_f32_dpp v120, v112, v58 row_newbcast:10 row_mask:0xf bank_mask:0xf
	v_fmac_f32_dpp v121, v112, v59 row_newbcast:11 row_mask:0xf bank_mask:0xf
	v_fmac_f32_dpp v120, v112, v60 row_newbcast:12 row_mask:0xf bank_mask:0xf
	v_fmac_f32_dpp v121, v112, v61 row_newbcast:13 row_mask:0xf bank_mask:0xf
	v_fmac_f32_dpp v120, v112, v62 row_newbcast:14 row_mask:0xf bank_mask:0xf
	v_fmac_f32_dpp v121, v112, v63 row_newbcast:15 row_mask:0xf bank_mask:0xf
	v_add_f32_e32 v128, v120, v121
	v_mul_f32_dpp v124, v105, v32 row_newbcast:0 row_mask:0xf bank_mask:0xf
	v_mul_f32_dpp v125, v105, v33 row_newbcast:1 row_mask:0xf bank_mask:0xf
	v_permlane32_swap_b32 v129, v128
	v_fmac_f32_dpp v124, v105, v34 row_newbcast:2 row_mask:0xf bank_mask:0xf
	v_fmac_f32_dpp v125, v105, v35 row_newbcast:3 row_mask:0xf bank_mask:0xf
	v_add_f32_dpp v108, -v129, -v128 quad_perm:[0,1,2,3] row_mask:0xc bank_mask:0xf
	v_fmac_f32_dpp v124, v105, v36 row_newbcast:4 row_mask:0xf bank_mask:0xf
	v_fmac_f32_dpp v125, v105, v37 row_newbcast:5 row_mask:0xf bank_mask:0xf
	v_mfma_f32_32x32x2_f32 v[64:79], v136, v108, v[32:47]
	v_fmac_f32_dpp v124, v105, v38 row_newbcast:6 row_mask:0xf bank_mask:0xf
	v_fmac_f32_dpp v125, v105, v39 row_newbcast:7 row_mask:0xf bank_mask:0xf
	v_fmac_f32_dpp v124, v105, v40 row_newbcast:8 row_mask:0xf bank_mask:0xf
	v_fmac_f32_dpp v125, v105, v41 row_newbcast:9 row_mask:0xf bank_mask:0xf
	v_fmac_f32_dpp v124, v105, v42 row_newbcast:10 row_mask:0xf bank_mask:0xf
	v_fmac_f32_dpp v125, v105, v43 row_newbcast:11 row_mask:0xf bank_mask:0xf
	v_fmac_f32_dpp v124, v105, v44 row_newbcast:12 row_mask:0xf bank_mask:0xf
	v_fmac_f32_dpp v125, v105, v45 row_newbcast:13 row_mask:0xf bank_mask:0xf
	v_fmac_f32_dpp v124, v105, v46 row_newbcast:14 row_mask:0xf bank_mask:0xf
	v_fmac_f32_dpp v125, v105, v47 row_newbcast:15 row_mask:0xf bank_mask:0xf
	v_fmac_f32_dpp v124, v107, v48 row_newbcast:0 row_mask:0xf bank_mask:0xf
	v_fmac_f32_dpp v125, v107, v49 row_newbcast:1 row_mask:0xf bank_mask:0xf
	v_fmac_f32_dpp v124, v107, v50 row_newbcast:2 row_mask:0xf bank_mask:0xf
	v_fmac_f32_dpp v125, v107, v51 row_newbcast:3 row_mask:0xf bank_mask:0xf
	v_mfma_f32_32x32x2_f32 v[80:95], v137, v108, v[48:63]
	v_fmac_f32_dpp v124, v107, v52 row_newbcast:4 row_mask:0xf bank_mask:0xf
	v_fmac_f32_dpp v125, v107, v53 row_newbcast:5 row_mask:0xf bank_mask:0xf
	v_fmac_f32_dpp v124, v107, v54 row_newbcast:6 row_mask:0xf bank_mask:0xf
	v_fmac_f32_dpp v125, v107, v55 row_newbcast:7 row_mask:0xf bank_mask:0xf
	v_fmac_f32_dpp v124, v107, v56 row_newbcast:8 row_mask:0xf bank_mask:0xf
	v_fmac_f32_dpp v125, v107, v57 row_newbcast:9 row_mask:0xf bank_mask:0xf
	v_fmac_f32_dpp v124, v107, v58 row_newbcast:10 row_mask:0xf bank_mask:0xf
	v_fmac_f32_dpp v125, v107, v59 row_newbcast:11 row_mask:0xf bank_mask:0xf
	v_fmac_f32_dpp v124, v107, v60 row_newbcast:12 row_mask:0xf bank_mask:0xf
	v_fmac_f32_dpp v125, v107, v61 row_newbcast:13 row_mask:0xf bank_mask:0xf
	v_fmac_f32_dpp v124, v107, v62 row_newbcast:14 row_mask:0xf bank_mask:0xf
	v_fmac_f32_dpp v125, v107, v63 row_newbcast:15 row_mask:0xf bank_mask:0xf
	v_add_f32_e32 v131, v124, v125
	s_nop 1
	v_permlane32_swap_b32 v130, v131
	v_add_f32_e32 v133, v130, v131
	v_cvt_pk_bf16_f32 v133, v133, v133
	global_store_short v13, v133, s[16:17]
	s_add_u32 s16, s16, s20
	s_addc_u32 s17, s17, s21
	s_waitcnt lgkmcnt(0)
	ds_read2st64_b32 v[100:101], v14 offset0:49 offset1:52
	ds_read2st64_b32 v[102:103], v17 offset0:49 offset1:52
	ds_read_b32 v136, v15 offset:12288
	ds_read_b32 v137, v15 offset:12416
	ds_read_b32 v108, v16 offset:12288
	v_mul_f32_dpp v120, v114, v64 row_newbcast:0 row_mask:0xf bank_mask:0xf
	v_mul_f32_dpp v121, v114, v65 row_newbcast:1 row_mask:0xf bank_mask:0xf
	v_fmac_f32_dpp v120, v114, v66 row_newbcast:2 row_mask:0xf bank_mask:0xf
	v_fmac_f32_dpp v121, v114, v67 row_newbcast:3 row_mask:0xf bank_mask:0xf
	v_fmac_f32_dpp v120, v114, v68 row_newbcast:4 row_mask:0xf bank_mask:0xf
	v_fmac_f32_dpp v121, v114, v69 row_newbcast:5 row_mask:0xf bank_mask:0xf
	v_fmac_f32_dpp v120, v114, v70 row_newbcast:6 row_mask:0xf bank_mask:0xf
	v_fmac_f32_dpp v121, v114, v71 row_newbcast:7 row_mask:0xf bank_mask:0xf
	v_fmac_f32_dpp v120, v114, v72 row_newbcast:8 row_mask:0xf bank_mask:0xf
	v_fmac_f32_dpp v121, v114, v73 row_newbcast:9 row_mask:0xf bank_mask:0xf
	v_fmac_f32_dpp v120, v114, v74 row_newbcast:10 row_mask:0xf bank_mask:0xf
	v_fmac_f32_dpp v121, v114, v75 row_newbcast:11 row_mask:0xf bank_mask:0xf
	v_fmac_f32_dpp v120, v114, v76 row_newbcast:12 row_mask:0xf bank_mask:0xf
	v_fmac_f32_dpp v121, v114, v77 row_newbcast:13 row_mask:0xf bank_mask:0xf
	v_fmac_f32_dpp v120, v114, v78 row_newbcast:14 row_mask:0xf bank_mask:0xf
	v_fmac_f32_dpp v121, v114, v79 row_newbcast:15 row_mask:0xf bank_mask:0xf
	v_fmac_f32_dpp v120, v116, v80 row_newbcast:0 row_mask:0xf bank_mask:0xf
	v_fmac_f32_dpp v121, v116, v81 row_newbcast:1 row_mask:0xf bank_mask:0xf
	v_fmac_f32_dpp v120, v116, v82 row_newbcast:2 row_mask:0xf bank_mask:0xf
	v_fmac_f32_dpp v121, v116, v83 row_newbcast:3 row_mask:0xf bank_mask:0xf
	v_fmac_f32_dpp v120, v116, v84 row_newbcast:4 row_mask:0xf bank_mask:0xf
	v_fmac_f32_dpp v121, v116, v85 row_newbcast:5 row_mask:0xf bank_mask:0xf
	v_fmac_f32_dpp v120, v116, v86 row_newbcast:6 row_mask:0xf bank_mask:0xf
	v_fmac_f32_dpp v121, v116, v87 row_newbcast:7 row_mask:0xf bank_mask:0xf
	v_fmac_f32_dpp v120, v116, v88 row_newbcast:8 row_mask:0xf bank_mask:0xf
	v_fmac_f32_dpp v121, v116, v89 row_newbcast:9 row_mask:0xf bank_mask:0xf
	v_fmac_f32_dpp v120, v116, v90 row_newbcast:10 row_mask:0xf bank_mask:0xf
	v_fmac_f32_dpp v121, v116, v91 row_newbcast:11 row_mask:0xf bank_mask:0xf
	v_fmac_f32_dpp v120, v116, v92 row_newbcast:12 row_mask:0xf bank_mask:0xf
	v_fmac_f32_dpp v121, v116, v93 row_newbcast:13 row_mask:0xf bank_mask:0xf
	v_fmac_f32_dpp v120, v116, v94 row_newbcast:14 row_mask:0xf bank_mask:0xf
	v_fmac_f32_dpp v121, v116, v95 row_newbcast:15 row_mask:0xf bank_mask:0xf
	v_add_f32_e32 v128, v120, v121
	v_mul_f32_dpp v124, v111, v64 row_newbcast:0 row_mask:0xf bank_mask:0xf
	v_mul_f32_dpp v125, v111, v65 row_newbcast:1 row_mask:0xf bank_mask:0xf
	v_permlane32_swap_b32 v129, v128
	v_fmac_f32_dpp v124, v111, v66 row_newbcast:2 row_mask:0xf bank_mask:0xf
	v_fmac_f32_dpp v125, v111, v67 row_newbcast:3 row_mask:0xf bank_mask:0xf
	v_add_f32_dpp v109, -v129, -v128 quad_perm:[0,1,2,3] row_mask:0xc bank_mask:0xf
	v_fmac_f32_dpp v124, v111, v68 row_newbcast:4 row_mask:0xf bank_mask:0xf
	v_fmac_f32_dpp v125, v111, v69 row_newbcast:5 row_mask:0xf bank_mask:0xf
	v_mfma_f32_32x32x2_f32 v[32:47], v138, v109, v[64:79]
	v_fmac_f32_dpp v124, v111, v70 row_newbcast:6 row_mask:0xf bank_mask:0xf
	v_fmac_f32_dpp v125, v111, v71 row_newbcast:7 row_mask:0xf bank_mask:0xf
	v_fmac_f32_dpp v124, v111, v72 row_newbcast:8 row_mask:0xf bank_mask:0xf
	v_fmac_f32_dpp v125, v111, v73 row_newbcast:9 row_mask:0xf bank_mask:0xf
	v_fmac_f32_dpp v124, v111, v74 row_newbcast:10 row_mask:0xf bank_mask:0xf
	v_fmac_f32_dpp v125, v111, v75 row_newbcast:11 row_mask:0xf bank_mask:0xf
	v_fmac_f32_dpp v124, v111, v76 row_newbcast:12 row_mask:0xf bank_mask:0xf
	v_fmac_f32_dpp v125, v111, v77 row_newbcast:13 row_mask:0xf bank_mask:0xf
	v_fmac_f32_dpp v124, v111, v78 row_newbcast:14 row_mask:0xf bank_mask:0xf
	v_fmac_f32_dpp v125, v111, v79 row_newbcast:15 row_mask:0xf bank_mask:0xf
	v_fmac_f32_dpp v124, v113, v80 row_newbcast:0 row_mask:0xf bank_mask:0xf
	v_fmac_f32_dpp v125, v113, v81 row_newbcast:1 row_mask:0xf bank_mask:0xf
	v_fmac_f32_dpp v124, v113, v82 row_newbcast:2 row_mask:0xf bank_mask:0xf
	v_fmac_f32_dpp v125, v113, v83 row_newbcast:3 row_mask:0xf bank_mask:0xf
	v_mfma_f32_32x32x2_f32 v[48:63], v139, v109, v[80:95]
	v_fmac_f32_dpp v124, v113, v84 row_newbcast:4 row_mask:0xf bank_mask:0xf
	v_fmac_f32_dpp v125, v113, v85 row_newbcast:5 row_mask:0xf bank_mask:0xf
	v_fmac_f32_dpp v124, v113, v86 row_newbcast:6 row_mask:0xf bank_mask:0xf
	v_fmac_f32_dpp v125, v113, v87 row_newbcast:7 row_mask:0xf bank_mask:0xf
	v_fmac_f32_dpp v124, v113, v88 row_newbcast:8 row_mask:0xf bank_mask:0xf
	v_fmac_f32_dpp v125, v113, v89 row_newbcast:9 row_mask:0xf bank_mask:0xf
	v_fmac_f32_dpp v124, v113, v90 row_newbcast:10 row_mask:0xf bank_mask:0xf
	v_fmac_f32_dpp v125, v113, v91 row_newbcast:11 row_mask:0xf bank_mask:0xf
	v_fmac_f32_dpp v124, v113, v92 row_newbcast:12 row_mask:0xf bank_mask:0xf
	v_fmac_f32_dpp v125, v113, v93 row_newbcast:13 row_mask:0xf bank_mask:0xf
	v_fmac_f32_dpp v124, v113, v94 row_newbcast:14 row_mask:0xf bank_mask:0xf
	v_fmac_f32_dpp v125, v113, v95 row_newbcast:15 row_mask:0xf bank_mask:0xf
	v_add_f32_e32 v130, v124, v125
	v_mul_f32_dpp v124, v115, v32 row_newbcast:0 row_mask:0xf bank_mask:0xf
	v_mul_f32_dpp v125, v115, v33 row_newbcast:1 row_mask:0xf bank_mask:0xf
	v_fmac_f32_dpp v124, v115, v34 row_newbcast:2 row_mask:0xf bank_mask:0xf
	v_fmac_f32_dpp v125, v115, v35 row_newbcast:3 row_mask:0xf bank_mask:0xf
	v_fmac_f32_dpp v124, v115, v36 row_newbcast:4 row_mask:0xf bank_mask:0xf
	v_fmac_f32_dpp v125, v115, v37 row_newbcast:5 row_mask:0xf bank_mask:0xf
	v_fmac_f32_dpp v124, v115, v38 row_newbcast:6 row_mask:0xf bank_mask:0xf
	v_fmac_f32_dpp v125, v115, v39 row_newbcast:7 row_mask:0xf bank_mask:0xf
	v_fmac_f32_dpp v124, v115, v40 row_newbcast:8 row_mask:0xf bank_mask:0xf
	v_fmac_f32_dpp v125, v115, v41 row_newbcast:9 row_mask:0xf bank_mask:0xf
	v_fmac_f32_dpp v124, v115, v42 row_newbcast:10 row_mask:0xf bank_mask:0xf
	v_fmac_f32_dpp v125, v115, v43 row_newbcast:11 row_mask:0xf bank_mask:0xf
	v_fmac_f32_dpp v124, v115, v44 row_newbcast:12 row_mask:0xf bank_mask:0xf
	v_fmac_f32_dpp v125, v115, v45 row_newbcast:13 row_mask:0xf bank_mask:0xf
	v_fmac_f32_dpp v124, v115, v46 row_newbcast:14 row_mask:0xf bank_mask:0xf
	v_fmac_f32_dpp v125, v115, v47 row_newbcast:15 row_mask:0xf bank_mask:0xf
	v_fmac_f32_dpp v124, v117, v48 row_newbcast:0 row_mask:0xf bank_mask:0xf
	v_fmac_f32_dpp v125, v117, v49 row_newbcast:1 row_mask:0xf bank_mask:0xf
	v_fmac_f32_dpp v124, v117, v50 row_newbcast:2 row_mask:0xf bank_mask:0xf
	v_fmac_f32_dpp v125, v117, v51 row_newbcast:3 row_mask:0xf bank_mask:0xf
	v_fmac_f32_dpp v124, v117, v52 row_newbcast:4 row_mask:0xf bank_mask:0xf
	v_fmac_f32_dpp v125, v117, v53 row_newbcast:5 row_mask:0xf bank_mask:0xf
	v_fmac_f32_dpp v124, v117, v54 row_newbcast:6 row_mask:0xf bank_mask:0xf
	v_fmac_f32_dpp v125, v117, v55 row_newbcast:7 row_mask:0xf bank_mask:0xf
	v_fmac_f32_dpp v124, v117, v56 row_newbcast:8 row_mask:0xf bank_mask:0xf
	v_fmac_f32_dpp v125, v117, v57 row_newbcast:9 row_mask:0xf bank_mask:0xf
	v_fmac_f32_dpp v124, v117, v58 row_newbcast:10 row_mask:0xf bank_mask:0xf
	v_fmac_f32_dpp v125, v117, v59 row_newbcast:11 row_mask:0xf bank_mask:0xf
	v_fmac_f32_dpp v124, v117, v60 row_newbcast:12 row_mask:0xf bank_mask:0xf
	v_fmac_f32_dpp v125, v117, v61 row_newbcast:13 row_mask:0xf bank_mask:0xf
	v_fmac_f32_dpp v124, v117, v62 row_newbcast:14 row_mask:0xf bank_mask:0xf
	v_fmac_f32_dpp v125, v117, v63 row_newbcast:15 row_mask:0xf bank_mask:0xf
	v_add_f32_e32 v131, v124, v125
	v_mul_f32_dpp v32, v118, v32 row_newbcast:0 row_mask:0xf bank_mask:0xf
	v_mul_f32_dpp v33, v118, v33 row_newbcast:1 row_mask:0xf bank_mask:0xf
	v_mul_f32_dpp v34, v118, v34 row_newbcast:2 row_mask:0xf bank_mask:0xf
	v_mul_f32_dpp v35, v118, v35 row_newbcast:3 row_mask:0xf bank_mask:0xf
	v_mul_f32_dpp v36, v118, v36 row_newbcast:4 row_mask:0xf bank_mask:0xf
	v_mul_f32_dpp v37, v118, v37 row_newbcast:5 row_mask:0xf bank_mask:0xf
	v_mul_f32_dpp v38, v118, v38 row_newbcast:6 row_mask:0xf bank_mask:0xf
	v_mul_f32_dpp v39, v118, v39 row_newbcast:7 row_mask:0xf bank_mask:0xf
	v_mul_f32_dpp v40, v118, v40 row_newbcast:8 row_mask:0xf bank_mask:0xf
	v_mul_f32_dpp v41, v118, v41 row_newbcast:9 row_mask:0xf bank_mask:0xf
	v_mul_f32_dpp v42, v118, v42 row_newbcast:10 row_mask:0xf bank_mask:0xf
	v_mul_f32_dpp v43, v118, v43 row_newbcast:11 row_mask:0xf bank_mask:0xf
	v_mul_f32_dpp v44, v118, v44 row_newbcast:12 row_mask:0xf bank_mask:0xf
	v_mul_f32_dpp v45, v118, v45 row_newbcast:13 row_mask:0xf bank_mask:0xf
	v_mul_f32_dpp v46, v118, v46 row_newbcast:14 row_mask:0xf bank_mask:0xf
	v_mul_f32_dpp v47, v118, v47 row_newbcast:15 row_mask:0xf bank_mask:0xf
	v_mul_f32_dpp v48, v119, v48 row_newbcast:0 row_mask:0xf bank_mask:0xf
	v_mul_f32_dpp v49, v119, v49 row_newbcast:1 row_mask:0xf bank_mask:0xf
	v_mul_f32_dpp v50, v119, v50 row_newbcast:2 row_mask:0xf bank_mask:0xf
	v_mul_f32_dpp v51, v119, v51 row_newbcast:3 row_mask:0xf bank_mask:0xf
	v_mul_f32_dpp v52, v119, v52 row_newbcast:4 row_mask:0xf bank_mask:0xf
	v_mul_f32_dpp v53, v119, v53 row_newbcast:5 row_mask:0xf bank_mask:0xf
	v_mul_f32_dpp v54, v119, v54 row_newbcast:6 row_mask:0xf bank_mask:0xf
	v_mul_f32_dpp v55, v119, v55 row_newbcast:7 row_mask:0xf bank_mask:0xf
	v_mul_f32_dpp v56, v119, v56 row_newbcast:8 row_mask:0xf bank_mask:0xf
	v_mul_f32_dpp v57, v119, v57 row_newbcast:9 row_mask:0xf bank_mask:0xf
	v_mul_f32_dpp v58, v119, v58 row_newbcast:10 row_mask:0xf bank_mask:0xf
	v_mul_f32_dpp v59, v119, v59 row_newbcast:11 row_mask:0xf bank_mask:0xf
	v_mul_f32_dpp v60, v119, v60 row_newbcast:12 row_mask:0xf bank_mask:0xf
	v_mul_f32_dpp v61, v119, v61 row_newbcast:13 row_mask:0xf bank_mask:0xf
	v_mul_f32_dpp v62, v119, v62 row_newbcast:14 row_mask:0xf bank_mask:0xf
	v_mul_f32_dpp v63, v119, v63 row_newbcast:15 row_mask:0xf bank_mask:0xf
	s_waitcnt lgkmcnt(0)
	ds_read2st64_b32 v[104:105], v14 offset0:55 offset1:58
	ds_read2st64_b32 v[106:107], v17 offset0:55 offset1:58
	ds_read_b32 v138, v15 offset:13824
	ds_read_b32 v139, v15 offset:13952
	ds_read_b32 v109, v16 offset:13824
	v_mul_f32_dpp v120, v100, v32 row_newbcast:0 row_mask:0xf bank_mask:0xf
	v_mul_f32_dpp v121, v100, v33 row_newbcast:1 row_mask:0xf bank_mask:0xf
	v_fmac_f32_dpp v120, v100, v34 row_newbcast:2 row_mask:0xf bank_mask:0xf
	v_fmac_f32_dpp v121, v100, v35 row_newbcast:3 row_mask:0xf bank_mask:0xf
	v_fmac_f32_dpp v120, v100, v36 row_newbcast:4 row_mask:0xf bank_mask:0xf
	v_fmac_f32_dpp v121, v100, v37 row_newbcast:5 row_mask:0xf bank_mask:0xf
	v_fmac_f32_dpp v120, v100, v38 row_newbcast:6 row_mask:0xf bank_mask:0xf
	v_fmac_f32_dpp v121, v100, v39 row_newbcast:7 row_mask:0xf bank_mask:0xf
	v_fmac_f32_dpp v120, v100, v40 row_newbcast:8 row_mask:0xf bank_mask:0xf
	v_fmac_f32_dpp v121, v100, v41 row_newbcast:9 row_mask:0xf bank_mask:0xf
	v_fmac_f32_dpp v120, v100, v42 row_newbcast:10 row_mask:0xf bank_mask:0xf
	v_fmac_f32_dpp v121, v100, v43 row_newbcast:11 row_mask:0xf bank_mask:0xf
	v_fmac_f32_dpp v120, v100, v44 row_newbcast:12 row_mask:0xf bank_mask:0xf
	v_fmac_f32_dpp v121, v100, v45 row_newbcast:13 row_mask:0xf bank_mask:0xf
	v_fmac_f32_dpp v120, v100, v46 row_newbcast:14 row_mask:0xf bank_mask:0xf
	v_fmac_f32_dpp v121, v100, v47 row_newbcast:15 row_mask:0xf bank_mask:0xf
	v_fmac_f32_dpp v120, v102, v48 row_newbcast:0 row_mask:0xf bank_mask:0xf
	v_fmac_f32_dpp v121, v102, v49 row_newbcast:1 row_mask:0xf bank_mask:0xf
	v_fmac_f32_dpp v120, v102, v50 row_newbcast:2 row_mask:0xf bank_mask:0xf
	v_fmac_f32_dpp v121, v102, v51 row_newbcast:3 row_mask:0xf bank_mask:0xf
	v_fmac_f32_dpp v120, v102, v52 row_newbcast:4 row_mask:0xf bank_mask:0xf
	v_fmac_f32_dpp v121, v102, v53 row_newbcast:5 row_mask:0xf bank_mask:0xf
	v_fmac_f32_dpp v120, v102, v54 row_newbcast:6 row_mask:0xf bank_mask:0xf
	v_fmac_f32_dpp v121, v102, v55 row_newbcast:7 row_mask:0xf bank_mask:0xf
	v_fmac_f32_dpp v120, v102, v56 row_newbcast:8 row_mask:0xf bank_mask:0xf
	v_fmac_f32_dpp v121, v102, v57 row_newbcast:9 row_mask:0xf bank_mask:0xf
	v_fmac_f32_dpp v120, v102, v58 row_newbcast:10 row_mask:0xf bank_mask:0xf
	v_fmac_f32_dpp v121, v102, v59 row_newbcast:11 row_mask:0xf bank_mask:0xf
	v_fmac_f32_dpp v120, v102, v60 row_newbcast:12 row_mask:0xf bank_mask:0xf
	v_fmac_f32_dpp v121, v102, v61 row_newbcast:13 row_mask:0xf bank_mask:0xf
	v_fmac_f32_dpp v120, v102, v62 row_newbcast:14 row_mask:0xf bank_mask:0xf
	v_fmac_f32_dpp v121, v102, v63 row_newbcast:15 row_mask:0xf bank_mask:0xf
	v_add_f32_e32 v128, v120, v121
	s_nop 1
	v_permlane32_swap_b32 v129, v128
	s_nop 1
	v_add_f32_dpp v108, -v129, -v128 quad_perm:[0,1,2,3] row_mask:0xc bank_mask:0xf
	s_nop 1
	v_mfma_f32_32x32x2_f32 v[64:79], v136, v108, v[32:47]
	s_nop 15
	v_mfma_f32_32x32x2_f32 v[80:95], v137, v108, v[48:63]
	s_nop 1
	v_permlane32_swap_b32 v130, v131
	v_add_f32_e32 v133, v130, v131
	v_cvt_pk_bf16_f32 v133, v133, v133
	global_store_short v13, v133, s[16:17]
	s_add_u32 s16, s16, s20
	s_addc_u32 s17, s17, s21
	s_waitcnt lgkmcnt(0)
	ds_read2st64_b32 v[110:111], v14 offset0:61 offset1:64
	ds_read2st64_b32 v[112:113], v17 offset0:61 offset1:64
	ds_read_b32 v136, v15 offset:15360
	ds_read_b32 v137, v15 offset:15488
	ds_read_b32 v108, v16 offset:15360
	v_mul_f32_dpp v120, v104, v64 row_newbcast:0 row_mask:0xf bank_mask:0xf
	v_mul_f32_dpp v121, v104, v65 row_newbcast:1 row_mask:0xf bank_mask:0xf
	v_fmac_f32_dpp v120, v104, v66 row_newbcast:2 row_mask:0xf bank_mask:0xf
	v_fmac_f32_dpp v121, v104, v67 row_newbcast:3 row_mask:0xf bank_mask:0xf
	v_fmac_f32_dpp v120, v104, v68 row_newbcast:4 row_mask:0xf bank_mask:0xf
	v_fmac_f32_dpp v121, v104, v69 row_newbcast:5 row_mask:0xf bank_mask:0xf
	v_fmac_f32_dpp v120, v104, v70 row_newbcast:6 row_mask:0xf bank_mask:0xf
	v_fmac_f32_dpp v121, v104, v71 row_newbcast:7 row_mask:0xf bank_mask:0xf
	v_fmac_f32_dpp v120, v104, v72 row_newbcast:8 row_mask:0xf bank_mask:0xf
	v_fmac_f32_dpp v121, v104, v73 row_newbcast:9 row_mask:0xf bank_mask:0xf
	v_fmac_f32_dpp v120, v104, v74 row_newbcast:10 row_mask:0xf bank_mask:0xf
	v_fmac_f32_dpp v121, v104, v75 row_newbcast:11 row_mask:0xf bank_mask:0xf
	v_fmac_f32_dpp v120, v104, v76 row_newbcast:12 row_mask:0xf bank_mask:0xf
	v_fmac_f32_dpp v121, v104, v77 row_newbcast:13 row_mask:0xf bank_mask:0xf
	v_fmac_f32_dpp v120, v104, v78 row_newbcast:14 row_mask:0xf bank_mask:0xf
	v_fmac_f32_dpp v121, v104, v79 row_newbcast:15 row_mask:0xf bank_mask:0xf
	v_fmac_f32_dpp v120, v106, v80 row_newbcast:0 row_mask:0xf bank_mask:0xf
	v_fmac_f32_dpp v121, v106, v81 row_newbcast:1 row_mask:0xf bank_mask:0xf
	v_fmac_f32_dpp v120, v106, v82 row_newbcast:2 row_mask:0xf bank_mask:0xf
	v_fmac_f32_dpp v121, v106, v83 row_newbcast:3 row_mask:0xf bank_mask:0xf
	v_fmac_f32_dpp v120, v106, v84 row_newbcast:4 row_mask:0xf bank_mask:0xf
	v_fmac_f32_dpp v121, v106, v85 row_newbcast:5 row_mask:0xf bank_mask:0xf
	v_fmac_f32_dpp v120, v106, v86 row_newbcast:6 row_mask:0xf bank_mask:0xf
	v_fmac_f32_dpp v121, v106, v87 row_newbcast:7 row_mask:0xf bank_mask:0xf
	v_fmac_f32_dpp v120, v106, v88 row_newbcast:8 row_mask:0xf bank_mask:0xf
	v_fmac_f32_dpp v121, v106, v89 row_newbcast:9 row_mask:0xf bank_mask:0xf
	v_fmac_f32_dpp v120, v106, v90 row_newbcast:10 row_mask:0xf bank_mask:0xf
	v_fmac_f32_dpp v121, v106, v91 row_newbcast:11 row_mask:0xf bank_mask:0xf
	v_fmac_f32_dpp v120, v106, v92 row_newbcast:12 row_mask:0xf bank_mask:0xf
	v_fmac_f32_dpp v121, v106, v93 row_newbcast:13 row_mask:0xf bank_mask:0xf
	v_fmac_f32_dpp v120, v106, v94 row_newbcast:14 row_mask:0xf bank_mask:0xf
	v_fmac_f32_dpp v121, v106, v95 row_newbcast:15 row_mask:0xf bank_mask:0xf
	v_add_f32_e32 v128, v120, v121
	v_mul_f32_dpp v124, v101, v64 row_newbcast:0 row_mask:0xf bank_mask:0xf
	v_mul_f32_dpp v125, v101, v65 row_newbcast:1 row_mask:0xf bank_mask:0xf
	v_permlane32_swap_b32 v129, v128
	v_fmac_f32_dpp v124, v101, v66 row_newbcast:2 row_mask:0xf bank_mask:0xf
	v_fmac_f32_dpp v125, v101, v67 row_newbcast:3 row_mask:0xf bank_mask:0xf
	v_add_f32_dpp v109, -v129, -v128 quad_perm:[0,1,2,3] row_mask:0xc bank_mask:0xf
	v_fmac_f32_dpp v124, v101, v68 row_newbcast:4 row_mask:0xf bank_mask:0xf
	v_fmac_f32_dpp v125, v101, v69 row_newbcast:5 row_mask:0xf bank_mask:0xf
	v_mfma_f32_32x32x2_f32 v[32:47], v138, v109, v[64:79]
	v_fmac_f32_dpp v124, v101, v70 row_newbcast:6 row_mask:0xf bank_mask:0xf
	v_fmac_f32_dpp v125, v101, v71 row_newbcast:7 row_mask:0xf bank_mask:0xf
	v_fmac_f32_dpp v124, v101, v72 row_newbcast:8 row_mask:0xf bank_mask:0xf
	v_fmac_f32_dpp v125, v101, v73 row_newbcast:9 row_mask:0xf bank_mask:0xf
	v_fmac_f32_dpp v124, v101, v74 row_newbcast:10 row_mask:0xf bank_mask:0xf
	v_fmac_f32_dpp v125, v101, v75 row_newbcast:11 row_mask:0xf bank_mask:0xf
	v_fmac_f32_dpp v124, v101, v76 row_newbcast:12 row_mask:0xf bank_mask:0xf
	v_fmac_f32_dpp v125, v101, v77 row_newbcast:13 row_mask:0xf bank_mask:0xf
	v_fmac_f32_dpp v124, v101, v78 row_newbcast:14 row_mask:0xf bank_mask:0xf
	v_fmac_f32_dpp v125, v101, v79 row_newbcast:15 row_mask:0xf bank_mask:0xf
	v_fmac_f32_dpp v124, v103, v80 row_newbcast:0 row_mask:0xf bank_mask:0xf
	v_fmac_f32_dpp v125, v103, v81 row_newbcast:1 row_mask:0xf bank_mask:0xf
	v_fmac_f32_dpp v124, v103, v82 row_newbcast:2 row_mask:0xf bank_mask:0xf
	v_fmac_f32_dpp v125, v103, v83 row_newbcast:3 row_mask:0xf bank_mask:0xf
	v_mfma_f32_32x32x2_f32 v[48:63], v139, v109, v[80:95]
	v_fmac_f32_dpp v124, v103, v84 row_newbcast:4 row_mask:0xf bank_mask:0xf
	v_fmac_f32_dpp v125, v103, v85 row_newbcast:5 row_mask:0xf bank_mask:0xf
	v_fmac_f32_dpp v124, v103, v86 row_newbcast:6 row_mask:0xf bank_mask:0xf
	v_fmac_f32_dpp v125, v103, v87 row_newbcast:7 row_mask:0xf bank_mask:0xf
	v_fmac_f32_dpp v124, v103, v88 row_newbcast:8 row_mask:0xf bank_mask:0xf
	v_fmac_f32_dpp v125, v103, v89 row_newbcast:9 row_mask:0xf bank_mask:0xf
	v_fmac_f32_dpp v124, v103, v90 row_newbcast:10 row_mask:0xf bank_mask:0xf
	v_fmac_f32_dpp v125, v103, v91 row_newbcast:11 row_mask:0xf bank_mask:0xf
	v_fmac_f32_dpp v124, v103, v92 row_newbcast:12 row_mask:0xf bank_mask:0xf
	v_fmac_f32_dpp v125, v103, v93 row_newbcast:13 row_mask:0xf bank_mask:0xf
	v_fmac_f32_dpp v124, v103, v94 row_newbcast:14 row_mask:0xf bank_mask:0xf
	v_fmac_f32_dpp v125, v103, v95 row_newbcast:15 row_mask:0xf bank_mask:0xf
	v_add_f32_e32 v130, v124, v125
	s_waitcnt lgkmcnt(0)
	ds_read2st64_b32 v[114:115], v14 offset0:67 offset1:70
	ds_read2st64_b32 v[116:117], v17 offset0:67 offset1:70
	ds_read_b32 v138, v15 offset:16896
	ds_read_b32 v139, v15 offset:17024
	ds_read_b32 v109, v16 offset:16896
	v_mul_f32_dpp v120, v110, v32 row_newbcast:0 row_mask:0xf bank_mask:0xf
	v_mul_f32_dpp v121, v110, v33 row_newbcast:1 row_mask:0xf bank_mask:0xf
	v_fmac_f32_dpp v120, v110, v34 row_newbcast:2 row_mask:0xf bank_mask:0xf
	v_fmac_f32_dpp v121, v110, v35 row_newbcast:3 row_mask:0xf bank_mask:0xf
	v_fmac_f32_dpp v120, v110, v36 row_newbcast:4 row_mask:0xf bank_mask:0xf
	v_fmac_f32_dpp v121, v110, v37 row_newbcast:5 row_mask:0xf bank_mask:0xf
	v_fmac_f32_dpp v120, v110, v38 row_newbcast:6 row_mask:0xf bank_mask:0xf
	v_fmac_f32_dpp v121, v110, v39 row_newbcast:7 row_mask:0xf bank_mask:0xf
	v_fmac_f32_dpp v120, v110, v40 row_newbcast:8 row_mask:0xf bank_mask:0xf
	v_fmac_f32_dpp v121, v110, v41 row_newbcast:9 row_mask:0xf bank_mask:0xf
	v_fmac_f32_dpp v120, v110, v42 row_newbcast:10 row_mask:0xf bank_mask:0xf
	v_fmac_f32_dpp v121, v110, v43 row_newbcast:11 row_mask:0xf bank_mask:0xf
	v_fmac_f32_dpp v120, v110, v44 row_newbcast:12 row_mask:0xf bank_mask:0xf
	v_fmac_f32_dpp v121, v110, v45 row_newbcast:13 row_mask:0xf bank_mask:0xf
	v_fmac_f32_dpp v120, v110, v46 row_newbcast:14 row_mask:0xf bank_mask:0xf
	v_fmac_f32_dpp v121, v110, v47 row_newbcast:15 row_mask:0xf bank_mask:0xf
	v_fmac_f32_dpp v120, v112, v48 row_newbcast:0 row_mask:0xf bank_mask:0xf
	v_fmac_f32_dpp v121, v112, v49 row_newbcast:1 row_mask:0xf bank_mask:0xf
	v_fmac_f32_dpp v120, v112, v50 row_newbcast:2 row_mask:0xf bank_mask:0xf
	v_fmac_f32_dpp v121, v112, v51 row_newbcast:3 row_mask:0xf bank_mask:0xf
	v_fmac_f32_dpp v120, v112, v52 row_newbcast:4 row_mask:0xf bank_mask:0xf
	v_fmac_f32_dpp v121, v112, v53 row_newbcast:5 row_mask:0xf bank_mask:0xf
	v_fmac_f32_dpp v120, v112, v54 row_newbcast:6 row_mask:0xf bank_mask:0xf
	v_fmac_f32_dpp v121, v112, v55 row_newbcast:7 row_mask:0xf bank_mask:0xf
	v_fmac_f32_dpp v120, v112, v56 row_newbcast:8 row_mask:0xf bank_mask:0xf
	v_fmac_f32_dpp v121, v112, v57 row_newbcast:9 row_mask:0xf bank_mask:0xf
	v_fmac_f32_dpp v120, v112, v58 row_newbcast:10 row_mask:0xf bank_mask:0xf
	v_fmac_f32_dpp v121, v112, v59 row_newbcast:11 row_mask:0xf bank_mask:0xf
	v_fmac_f32_dpp v120, v112, v60 row_newbcast:12 row_mask:0xf bank_mask:0xf
	v_fmac_f32_dpp v121, v112, v61 row_newbcast:13 row_mask:0xf bank_mask:0xf
	v_fmac_f32_dpp v120, v112, v62 row_newbcast:14 row_mask:0xf bank_mask:0xf
	v_fmac_f32_dpp v121, v112, v63 row_newbcast:15 row_mask:0xf bank_mask:0xf
	v_add_f32_e32 v128, v120, v121
	v_mul_f32_dpp v124, v105, v32 row_newbcast:0 row_mask:0xf bank_mask:0xf
	v_mul_f32_dpp v125, v105, v33 row_newbcast:1 row_mask:0xf bank_mask:0xf
	v_permlane32_swap_b32 v129, v128
	v_fmac_f32_dpp v124, v105, v34 row_newbcast:2 row_mask:0xf bank_mask:0xf
	v_fmac_f32_dpp v125, v105, v35 row_newbcast:3 row_mask:0xf bank_mask:0xf
	v_add_f32_dpp v108, -v129, -v128 quad_perm:[0,1,2,3] row_mask:0xc bank_mask:0xf
	v_fmac_f32_dpp v124, v105, v36 row_newbcast:4 row_mask:0xf bank_mask:0xf
	v_fmac_f32_dpp v125, v105, v37 row_newbcast:5 row_mask:0xf bank_mask:0xf
	v_mfma_f32_32x32x2_f32 v[64:79], v136, v108, v[32:47]
	v_fmac_f32_dpp v124, v105, v38 row_newbcast:6 row_mask:0xf bank_mask:0xf
	v_fmac_f32_dpp v125, v105, v39 row_newbcast:7 row_mask:0xf bank_mask:0xf
	v_fmac_f32_dpp v124, v105, v40 row_newbcast:8 row_mask:0xf bank_mask:0xf
	v_fmac_f32_dpp v125, v105, v41 row_newbcast:9 row_mask:0xf bank_mask:0xf
	v_fmac_f32_dpp v124, v105, v42 row_newbcast:10 row_mask:0xf bank_mask:0xf
	v_fmac_f32_dpp v125, v105, v43 row_newbcast:11 row_mask:0xf bank_mask:0xf
	v_fmac_f32_dpp v124, v105, v44 row_newbcast:12 row_mask:0xf bank_mask:0xf
	v_fmac_f32_dpp v125, v105, v45 row_newbcast:13 row_mask:0xf bank_mask:0xf
	v_fmac_f32_dpp v124, v105, v46 row_newbcast:14 row_mask:0xf bank_mask:0xf
	v_fmac_f32_dpp v125, v105, v47 row_newbcast:15 row_mask:0xf bank_mask:0xf
	v_fmac_f32_dpp v124, v107, v48 row_newbcast:0 row_mask:0xf bank_mask:0xf
	v_fmac_f32_dpp v125, v107, v49 row_newbcast:1 row_mask:0xf bank_mask:0xf
	v_fmac_f32_dpp v124, v107, v50 row_newbcast:2 row_mask:0xf bank_mask:0xf
	v_fmac_f32_dpp v125, v107, v51 row_newbcast:3 row_mask:0xf bank_mask:0xf
	v_mfma_f32_32x32x2_f32 v[80:95], v137, v108, v[48:63]
	v_fmac_f32_dpp v124, v107, v52 row_newbcast:4 row_mask:0xf bank_mask:0xf
	v_fmac_f32_dpp v125, v107, v53 row_newbcast:5 row_mask:0xf bank_mask:0xf
	v_fmac_f32_dpp v124, v107, v54 row_newbcast:6 row_mask:0xf bank_mask:0xf
	v_fmac_f32_dpp v125, v107, v55 row_newbcast:7 row_mask:0xf bank_mask:0xf
	v_fmac_f32_dpp v124, v107, v56 row_newbcast:8 row_mask:0xf bank_mask:0xf
	v_fmac_f32_dpp v125, v107, v57 row_newbcast:9 row_mask:0xf bank_mask:0xf
	v_fmac_f32_dpp v124, v107, v58 row_newbcast:10 row_mask:0xf bank_mask:0xf
	v_fmac_f32_dpp v125, v107, v59 row_newbcast:11 row_mask:0xf bank_mask:0xf
	v_fmac_f32_dpp v124, v107, v60 row_newbcast:12 row_mask:0xf bank_mask:0xf
	v_fmac_f32_dpp v125, v107, v61 row_newbcast:13 row_mask:0xf bank_mask:0xf
	v_fmac_f32_dpp v124, v107, v62 row_newbcast:14 row_mask:0xf bank_mask:0xf
	v_fmac_f32_dpp v125, v107, v63 row_newbcast:15 row_mask:0xf bank_mask:0xf
	v_add_f32_e32 v131, v124, v125
	s_nop 1
	v_permlane32_swap_b32 v130, v131
	v_add_f32_e32 v133, v130, v131
	v_cvt_pk_bf16_f32 v133, v133, v133
	global_store_short v13, v133, s[16:17]
	s_add_u32 s16, s16, s20
	s_addc_u32 s17, s17, s21
	s_waitcnt lgkmcnt(0)
	ds_read2st64_b32 v[100:101], v14 offset0:73 offset1:76
	ds_read2st64_b32 v[102:103], v17 offset0:73 offset1:76
	ds_read_b32 v136, v15 offset:18432
	ds_read_b32 v137, v15 offset:18560
	ds_read_b32 v108, v16 offset:18432
	v_mul_f32_dpp v120, v114, v64 row_newbcast:0 row_mask:0xf bank_mask:0xf
	v_mul_f32_dpp v121, v114, v65 row_newbcast:1 row_mask:0xf bank_mask:0xf
	v_fmac_f32_dpp v120, v114, v66 row_newbcast:2 row_mask:0xf bank_mask:0xf
	v_fmac_f32_dpp v121, v114, v67 row_newbcast:3 row_mask:0xf bank_mask:0xf
	v_fmac_f32_dpp v120, v114, v68 row_newbcast:4 row_mask:0xf bank_mask:0xf
	v_fmac_f32_dpp v121, v114, v69 row_newbcast:5 row_mask:0xf bank_mask:0xf
	v_fmac_f32_dpp v120, v114, v70 row_newbcast:6 row_mask:0xf bank_mask:0xf
	v_fmac_f32_dpp v121, v114, v71 row_newbcast:7 row_mask:0xf bank_mask:0xf
	v_fmac_f32_dpp v120, v114, v72 row_newbcast:8 row_mask:0xf bank_mask:0xf
	v_fmac_f32_dpp v121, v114, v73 row_newbcast:9 row_mask:0xf bank_mask:0xf
	v_fmac_f32_dpp v120, v114, v74 row_newbcast:10 row_mask:0xf bank_mask:0xf
	v_fmac_f32_dpp v121, v114, v75 row_newbcast:11 row_mask:0xf bank_mask:0xf
	v_fmac_f32_dpp v120, v114, v76 row_newbcast:12 row_mask:0xf bank_mask:0xf
	v_fmac_f32_dpp v121, v114, v77 row_newbcast:13 row_mask:0xf bank_mask:0xf
	v_fmac_f32_dpp v120, v114, v78 row_newbcast:14 row_mask:0xf bank_mask:0xf
	v_fmac_f32_dpp v121, v114, v79 row_newbcast:15 row_mask:0xf bank_mask:0xf
	v_fmac_f32_dpp v120, v116, v80 row_newbcast:0 row_mask:0xf bank_mask:0xf
	v_fmac_f32_dpp v121, v116, v81 row_newbcast:1 row_mask:0xf bank_mask:0xf
	v_fmac_f32_dpp v120, v116, v82 row_newbcast:2 row_mask:0xf bank_mask:0xf
	v_fmac_f32_dpp v121, v116, v83 row_newbcast:3 row_mask:0xf bank_mask:0xf
	v_fmac_f32_dpp v120, v116, v84 row_newbcast:4 row_mask:0xf bank_mask:0xf
	v_fmac_f32_dpp v121, v116, v85 row_newbcast:5 row_mask:0xf bank_mask:0xf
	v_fmac_f32_dpp v120, v116, v86 row_newbcast:6 row_mask:0xf bank_mask:0xf
	v_fmac_f32_dpp v121, v116, v87 row_newbcast:7 row_mask:0xf bank_mask:0xf
	v_fmac_f32_dpp v120, v116, v88 row_newbcast:8 row_mask:0xf bank_mask:0xf
	v_fmac_f32_dpp v121, v116, v89 row_newbcast:9 row_mask:0xf bank_mask:0xf
	v_fmac_f32_dpp v120, v116, v90 row_newbcast:10 row_mask:0xf bank_mask:0xf
	v_fmac_f32_dpp v121, v116, v91 row_newbcast:11 row_mask:0xf bank_mask:0xf
	v_fmac_f32_dpp v120, v116, v92 row_newbcast:12 row_mask:0xf bank_mask:0xf
	v_fmac_f32_dpp v121, v116, v93 row_newbcast:13 row_mask:0xf bank_mask:0xf
	v_fmac_f32_dpp v120, v116, v94 row_newbcast:14 row_mask:0xf bank_mask:0xf
	v_fmac_f32_dpp v121, v116, v95 row_newbcast:15 row_mask:0xf bank_mask:0xf
	v_add_f32_e32 v128, v120, v121
	v_mul_f32_dpp v124, v111, v64 row_newbcast:0 row_mask:0xf bank_mask:0xf
	v_mul_f32_dpp v125, v111, v65 row_newbcast:1 row_mask:0xf bank_mask:0xf
	v_permlane32_swap_b32 v129, v128
	v_fmac_f32_dpp v124, v111, v66 row_newbcast:2 row_mask:0xf bank_mask:0xf
	v_fmac_f32_dpp v125, v111, v67 row_newbcast:3 row_mask:0xf bank_mask:0xf
	v_add_f32_dpp v109, -v129, -v128 quad_perm:[0,1,2,3] row_mask:0xc bank_mask:0xf
	v_fmac_f32_dpp v124, v111, v68 row_newbcast:4 row_mask:0xf bank_mask:0xf
	v_fmac_f32_dpp v125, v111, v69 row_newbcast:5 row_mask:0xf bank_mask:0xf
	v_mfma_f32_32x32x2_f32 v[32:47], v138, v109, v[64:79]
	v_fmac_f32_dpp v124, v111, v70 row_newbcast:6 row_mask:0xf bank_mask:0xf
	v_fmac_f32_dpp v125, v111, v71 row_newbcast:7 row_mask:0xf bank_mask:0xf
	v_fmac_f32_dpp v124, v111, v72 row_newbcast:8 row_mask:0xf bank_mask:0xf
	v_fmac_f32_dpp v125, v111, v73 row_newbcast:9 row_mask:0xf bank_mask:0xf
	v_fmac_f32_dpp v124, v111, v74 row_newbcast:10 row_mask:0xf bank_mask:0xf
	v_fmac_f32_dpp v125, v111, v75 row_newbcast:11 row_mask:0xf bank_mask:0xf
	v_fmac_f32_dpp v124, v111, v76 row_newbcast:12 row_mask:0xf bank_mask:0xf
	v_fmac_f32_dpp v125, v111, v77 row_newbcast:13 row_mask:0xf bank_mask:0xf
	v_fmac_f32_dpp v124, v111, v78 row_newbcast:14 row_mask:0xf bank_mask:0xf
	v_fmac_f32_dpp v125, v111, v79 row_newbcast:15 row_mask:0xf bank_mask:0xf
	v_fmac_f32_dpp v124, v113, v80 row_newbcast:0 row_mask:0xf bank_mask:0xf
	v_fmac_f32_dpp v125, v113, v81 row_newbcast:1 row_mask:0xf bank_mask:0xf
	v_fmac_f32_dpp v124, v113, v82 row_newbcast:2 row_mask:0xf bank_mask:0xf
	v_fmac_f32_dpp v125, v113, v83 row_newbcast:3 row_mask:0xf bank_mask:0xf
	v_mfma_f32_32x32x2_f32 v[48:63], v139, v109, v[80:95]
	v_fmac_f32_dpp v124, v113, v84 row_newbcast:4 row_mask:0xf bank_mask:0xf
	v_fmac_f32_dpp v125, v113, v85 row_newbcast:5 row_mask:0xf bank_mask:0xf
	v_fmac_f32_dpp v124, v113, v86 row_newbcast:6 row_mask:0xf bank_mask:0xf
	v_fmac_f32_dpp v125, v113, v87 row_newbcast:7 row_mask:0xf bank_mask:0xf
	v_fmac_f32_dpp v124, v113, v88 row_newbcast:8 row_mask:0xf bank_mask:0xf
	v_fmac_f32_dpp v125, v113, v89 row_newbcast:9 row_mask:0xf bank_mask:0xf
	v_fmac_f32_dpp v124, v113, v90 row_newbcast:10 row_mask:0xf bank_mask:0xf
	v_fmac_f32_dpp v125, v113, v91 row_newbcast:11 row_mask:0xf bank_mask:0xf
	v_fmac_f32_dpp v124, v113, v92 row_newbcast:12 row_mask:0xf bank_mask:0xf
	v_fmac_f32_dpp v125, v113, v93 row_newbcast:13 row_mask:0xf bank_mask:0xf
	v_fmac_f32_dpp v124, v113, v94 row_newbcast:14 row_mask:0xf bank_mask:0xf
	v_fmac_f32_dpp v125, v113, v95 row_newbcast:15 row_mask:0xf bank_mask:0xf
	v_add_f32_e32 v130, v124, v125
	s_waitcnt lgkmcnt(0)
	ds_read2st64_b32 v[104:105], v14 offset0:79 offset1:82
	ds_read2st64_b32 v[106:107], v17 offset0:79 offset1:82
	ds_read_b32 v138, v15 offset:19968
	ds_read_b32 v139, v15 offset:20096
	ds_read_b32 v109, v16 offset:19968
	v_mul_f32_dpp v120, v100, v32 row_newbcast:0 row_mask:0xf bank_mask:0xf
	v_mul_f32_dpp v121, v100, v33 row_newbcast:1 row_mask:0xf bank_mask:0xf
	v_fmac_f32_dpp v120, v100, v34 row_newbcast:2 row_mask:0xf bank_mask:0xf
	v_fmac_f32_dpp v121, v100, v35 row_newbcast:3 row_mask:0xf bank_mask:0xf
	v_fmac_f32_dpp v120, v100, v36 row_newbcast:4 row_mask:0xf bank_mask:0xf
	v_fmac_f32_dpp v121, v100, v37 row_newbcast:5 row_mask:0xf bank_mask:0xf
	v_fmac_f32_dpp v120, v100, v38 row_newbcast:6 row_mask:0xf bank_mask:0xf
	v_fmac_f32_dpp v121, v100, v39 row_newbcast:7 row_mask:0xf bank_mask:0xf
	v_fmac_f32_dpp v120, v100, v40 row_newbcast:8 row_mask:0xf bank_mask:0xf
	v_fmac_f32_dpp v121, v100, v41 row_newbcast:9 row_mask:0xf bank_mask:0xf
	v_fmac_f32_dpp v120, v100, v42 row_newbcast:10 row_mask:0xf bank_mask:0xf
	v_fmac_f32_dpp v121, v100, v43 row_newbcast:11 row_mask:0xf bank_mask:0xf
	v_fmac_f32_dpp v120, v100, v44 row_newbcast:12 row_mask:0xf bank_mask:0xf
	v_fmac_f32_dpp v121, v100, v45 row_newbcast:13 row_mask:0xf bank_mask:0xf
	v_fmac_f32_dpp v120, v100, v46 row_newbcast:14 row_mask:0xf bank_mask:0xf
	v_fmac_f32_dpp v121, v100, v47 row_newbcast:15 row_mask:0xf bank_mask:0xf
	v_fmac_f32_dpp v120, v102, v48 row_newbcast:0 row_mask:0xf bank_mask:0xf
	v_fmac_f32_dpp v121, v102, v49 row_newbcast:1 row_mask:0xf bank_mask:0xf
	v_fmac_f32_dpp v120, v102, v50 row_newbcast:2 row_mask:0xf bank_mask:0xf
	v_fmac_f32_dpp v121, v102, v51 row_newbcast:3 row_mask:0xf bank_mask:0xf
	v_fmac_f32_dpp v120, v102, v52 row_newbcast:4 row_mask:0xf bank_mask:0xf
	v_fmac_f32_dpp v121, v102, v53 row_newbcast:5 row_mask:0xf bank_mask:0xf
	v_fmac_f32_dpp v120, v102, v54 row_newbcast:6 row_mask:0xf bank_mask:0xf
	v_fmac_f32_dpp v121, v102, v55 row_newbcast:7 row_mask:0xf bank_mask:0xf
	v_fmac_f32_dpp v120, v102, v56 row_newbcast:8 row_mask:0xf bank_mask:0xf
	v_fmac_f32_dpp v121, v102, v57 row_newbcast:9 row_mask:0xf bank_mask:0xf
	v_fmac_f32_dpp v120, v102, v58 row_newbcast:10 row_mask:0xf bank_mask:0xf
	v_fmac_f32_dpp v121, v102, v59 row_newbcast:11 row_mask:0xf bank_mask:0xf
	v_fmac_f32_dpp v120, v102, v60 row_newbcast:12 row_mask:0xf bank_mask:0xf
	v_fmac_f32_dpp v121, v102, v61 row_newbcast:13 row_mask:0xf bank_mask:0xf
	v_fmac_f32_dpp v120, v102, v62 row_newbcast:14 row_mask:0xf bank_mask:0xf
	v_fmac_f32_dpp v121, v102, v63 row_newbcast:15 row_mask:0xf bank_mask:0xf
	v_add_f32_e32 v128, v120, v121
	v_mul_f32_dpp v124, v115, v32 row_newbcast:0 row_mask:0xf bank_mask:0xf
	v_mul_f32_dpp v125, v115, v33 row_newbcast:1 row_mask:0xf bank_mask:0xf
	v_permlane32_swap_b32 v129, v128
	v_fmac_f32_dpp v124, v115, v34 row_newbcast:2 row_mask:0xf bank_mask:0xf
	v_fmac_f32_dpp v125, v115, v35 row_newbcast:3 row_mask:0xf bank_mask:0xf
	v_add_f32_dpp v108, -v129, -v128 quad_perm:[0,1,2,3] row_mask:0xc bank_mask:0xf
	v_fmac_f32_dpp v124, v115, v36 row_newbcast:4 row_mask:0xf bank_mask:0xf
	v_fmac_f32_dpp v125, v115, v37 row_newbcast:5 row_mask:0xf bank_mask:0xf
	v_mfma_f32_32x32x2_f32 v[64:79], v136, v108, v[32:47]
	v_fmac_f32_dpp v124, v115, v38 row_newbcast:6 row_mask:0xf bank_mask:0xf
	v_fmac_f32_dpp v125, v115, v39 row_newbcast:7 row_mask:0xf bank_mask:0xf
	v_fmac_f32_dpp v124, v115, v40 row_newbcast:8 row_mask:0xf bank_mask:0xf
	v_fmac_f32_dpp v125, v115, v41 row_newbcast:9 row_mask:0xf bank_mask:0xf
	v_fmac_f32_dpp v124, v115, v42 row_newbcast:10 row_mask:0xf bank_mask:0xf
	v_fmac_f32_dpp v125, v115, v43 row_newbcast:11 row_mask:0xf bank_mask:0xf
	v_fmac_f32_dpp v124, v115, v44 row_newbcast:12 row_mask:0xf bank_mask:0xf
	v_fmac_f32_dpp v125, v115, v45 row_newbcast:13 row_mask:0xf bank_mask:0xf
	v_fmac_f32_dpp v124, v115, v46 row_newbcast:14 row_mask:0xf bank_mask:0xf
	v_fmac_f32_dpp v125, v115, v47 row_newbcast:15 row_mask:0xf bank_mask:0xf
	v_fmac_f32_dpp v124, v117, v48 row_newbcast:0 row_mask:0xf bank_mask:0xf
	v_fmac_f32_dpp v125, v117, v49 row_newbcast:1 row_mask:0xf bank_mask:0xf
	v_fmac_f32_dpp v124, v117, v50 row_newbcast:2 row_mask:0xf bank_mask:0xf
	v_fmac_f32_dpp v125, v117, v51 row_newbcast:3 row_mask:0xf bank_mask:0xf
	v_mfma_f32_32x32x2_f32 v[80:95], v137, v108, v[48:63]
	v_fmac_f32_dpp v124, v117, v52 row_newbcast:4 row_mask:0xf bank_mask:0xf
	v_fmac_f32_dpp v125, v117, v53 row_newbcast:5 row_mask:0xf bank_mask:0xf
	v_fmac_f32_dpp v124, v117, v54 row_newbcast:6 row_mask:0xf bank_mask:0xf
	v_fmac_f32_dpp v125, v117, v55 row_newbcast:7 row_mask:0xf bank_mask:0xf
	v_fmac_f32_dpp v124, v117, v56 row_newbcast:8 row_mask:0xf bank_mask:0xf
	v_fmac_f32_dpp v125, v117, v57 row_newbcast:9 row_mask:0xf bank_mask:0xf
	v_fmac_f32_dpp v124, v117, v58 row_newbcast:10 row_mask:0xf bank_mask:0xf
	v_fmac_f32_dpp v125, v117, v59 row_newbcast:11 row_mask:0xf bank_mask:0xf
	v_fmac_f32_dpp v124, v117, v60 row_newbcast:12 row_mask:0xf bank_mask:0xf
	v_fmac_f32_dpp v125, v117, v61 row_newbcast:13 row_mask:0xf bank_mask:0xf
	v_fmac_f32_dpp v124, v117, v62 row_newbcast:14 row_mask:0xf bank_mask:0xf
	v_fmac_f32_dpp v125, v117, v63 row_newbcast:15 row_mask:0xf bank_mask:0xf
	v_add_f32_e32 v131, v124, v125
	s_nop 1
	v_permlane32_swap_b32 v130, v131
	v_add_f32_e32 v133, v130, v131
	v_cvt_pk_bf16_f32 v133, v133, v133
	global_store_short v13, v133, s[16:17]
	s_add_u32 s16, s16, s20
	s_addc_u32 s17, s17, s21
	s_waitcnt lgkmcnt(0)
	ds_read2st64_b32 v[110:111], v14 offset0:85 offset1:88
	ds_read2st64_b32 v[112:113], v17 offset0:85 offset1:88
	ds_read_b32 v136, v15 offset:21504
	ds_read_b32 v137, v15 offset:21632
	ds_read_b32 v108, v16 offset:21504
	v_mul_f32_dpp v120, v104, v64 row_newbcast:0 row_mask:0xf bank_mask:0xf
	v_mul_f32_dpp v121, v104, v65 row_newbcast:1 row_mask:0xf bank_mask:0xf
	v_fmac_f32_dpp v120, v104, v66 row_newbcast:2 row_mask:0xf bank_mask:0xf
	v_fmac_f32_dpp v121, v104, v67 row_newbcast:3 row_mask:0xf bank_mask:0xf
	v_fmac_f32_dpp v120, v104, v68 row_newbcast:4 row_mask:0xf bank_mask:0xf
	v_fmac_f32_dpp v121, v104, v69 row_newbcast:5 row_mask:0xf bank_mask:0xf
	v_fmac_f32_dpp v120, v104, v70 row_newbcast:6 row_mask:0xf bank_mask:0xf
	v_fmac_f32_dpp v121, v104, v71 row_newbcast:7 row_mask:0xf bank_mask:0xf
	v_fmac_f32_dpp v120, v104, v72 row_newbcast:8 row_mask:0xf bank_mask:0xf
	v_fmac_f32_dpp v121, v104, v73 row_newbcast:9 row_mask:0xf bank_mask:0xf
	v_fmac_f32_dpp v120, v104, v74 row_newbcast:10 row_mask:0xf bank_mask:0xf
	v_fmac_f32_dpp v121, v104, v75 row_newbcast:11 row_mask:0xf bank_mask:0xf
	v_fmac_f32_dpp v120, v104, v76 row_newbcast:12 row_mask:0xf bank_mask:0xf
	v_fmac_f32_dpp v121, v104, v77 row_newbcast:13 row_mask:0xf bank_mask:0xf
	v_fmac_f32_dpp v120, v104, v78 row_newbcast:14 row_mask:0xf bank_mask:0xf
	v_fmac_f32_dpp v121, v104, v79 row_newbcast:15 row_mask:0xf bank_mask:0xf
	v_fmac_f32_dpp v120, v106, v80 row_newbcast:0 row_mask:0xf bank_mask:0xf
	v_fmac_f32_dpp v121, v106, v81 row_newbcast:1 row_mask:0xf bank_mask:0xf
	v_fmac_f32_dpp v120, v106, v82 row_newbcast:2 row_mask:0xf bank_mask:0xf
	v_fmac_f32_dpp v121, v106, v83 row_newbcast:3 row_mask:0xf bank_mask:0xf
	v_fmac_f32_dpp v120, v106, v84 row_newbcast:4 row_mask:0xf bank_mask:0xf
	v_fmac_f32_dpp v121, v106, v85 row_newbcast:5 row_mask:0xf bank_mask:0xf
	v_fmac_f32_dpp v120, v106, v86 row_newbcast:6 row_mask:0xf bank_mask:0xf
	v_fmac_f32_dpp v121, v106, v87 row_newbcast:7 row_mask:0xf bank_mask:0xf
	v_fmac_f32_dpp v120, v106, v88 row_newbcast:8 row_mask:0xf bank_mask:0xf
	v_fmac_f32_dpp v121, v106, v89 row_newbcast:9 row_mask:0xf bank_mask:0xf
	v_fmac_f32_dpp v120, v106, v90 row_newbcast:10 row_mask:0xf bank_mask:0xf
	v_fmac_f32_dpp v121, v106, v91 row_newbcast:11 row_mask:0xf bank_mask:0xf
	v_fmac_f32_dpp v120, v106, v92 row_newbcast:12 row_mask:0xf bank_mask:0xf
	v_fmac_f32_dpp v121, v106, v93 row_newbcast:13 row_mask:0xf bank_mask:0xf
	v_fmac_f32_dpp v120, v106, v94 row_newbcast:14 row_mask:0xf bank_mask:0xf
	v_fmac_f32_dpp v121, v106, v95 row_newbcast:15 row_mask:0xf bank_mask:0xf
	v_add_f32_e32 v128, v120, v121
	v_mul_f32_dpp v124, v101, v64 row_newbcast:0 row_mask:0xf bank_mask:0xf
	v_mul_f32_dpp v125, v101, v65 row_newbcast:1 row_mask:0xf bank_mask:0xf
	v_permlane32_swap_b32 v129, v128
	v_fmac_f32_dpp v124, v101, v66 row_newbcast:2 row_mask:0xf bank_mask:0xf
	v_fmac_f32_dpp v125, v101, v67 row_newbcast:3 row_mask:0xf bank_mask:0xf
	v_add_f32_dpp v109, -v129, -v128 quad_perm:[0,1,2,3] row_mask:0xc bank_mask:0xf
	v_fmac_f32_dpp v124, v101, v68 row_newbcast:4 row_mask:0xf bank_mask:0xf
	v_fmac_f32_dpp v125, v101, v69 row_newbcast:5 row_mask:0xf bank_mask:0xf
	v_mfma_f32_32x32x2_f32 v[32:47], v138, v109, v[64:79]
	v_fmac_f32_dpp v124, v101, v70 row_newbcast:6 row_mask:0xf bank_mask:0xf
	v_fmac_f32_dpp v125, v101, v71 row_newbcast:7 row_mask:0xf bank_mask:0xf
	v_fmac_f32_dpp v124, v101, v72 row_newbcast:8 row_mask:0xf bank_mask:0xf
	v_fmac_f32_dpp v125, v101, v73 row_newbcast:9 row_mask:0xf bank_mask:0xf
	v_fmac_f32_dpp v124, v101, v74 row_newbcast:10 row_mask:0xf bank_mask:0xf
	v_fmac_f32_dpp v125, v101, v75 row_newbcast:11 row_mask:0xf bank_mask:0xf
	v_fmac_f32_dpp v124, v101, v76 row_newbcast:12 row_mask:0xf bank_mask:0xf
	v_fmac_f32_dpp v125, v101, v77 row_newbcast:13 row_mask:0xf bank_mask:0xf
	v_fmac_f32_dpp v124, v101, v78 row_newbcast:14 row_mask:0xf bank_mask:0xf
	v_fmac_f32_dpp v125, v101, v79 row_newbcast:15 row_mask:0xf bank_mask:0xf
	v_fmac_f32_dpp v124, v103, v80 row_newbcast:0 row_mask:0xf bank_mask:0xf
	v_fmac_f32_dpp v125, v103, v81 row_newbcast:1 row_mask:0xf bank_mask:0xf
	v_fmac_f32_dpp v124, v103, v82 row_newbcast:2 row_mask:0xf bank_mask:0xf
	v_fmac_f32_dpp v125, v103, v83 row_newbcast:3 row_mask:0xf bank_mask:0xf
	v_mfma_f32_32x32x2_f32 v[48:63], v139, v109, v[80:95]
	v_fmac_f32_dpp v124, v103, v84 row_newbcast:4 row_mask:0xf bank_mask:0xf
	v_fmac_f32_dpp v125, v103, v85 row_newbcast:5 row_mask:0xf bank_mask:0xf
	v_fmac_f32_dpp v124, v103, v86 row_newbcast:6 row_mask:0xf bank_mask:0xf
	v_fmac_f32_dpp v125, v103, v87 row_newbcast:7 row_mask:0xf bank_mask:0xf
	v_fmac_f32_dpp v124, v103, v88 row_newbcast:8 row_mask:0xf bank_mask:0xf
	v_fmac_f32_dpp v125, v103, v89 row_newbcast:9 row_mask:0xf bank_mask:0xf
	v_fmac_f32_dpp v124, v103, v90 row_newbcast:10 row_mask:0xf bank_mask:0xf
	v_fmac_f32_dpp v125, v103, v91 row_newbcast:11 row_mask:0xf bank_mask:0xf
	v_fmac_f32_dpp v124, v103, v92 row_newbcast:12 row_mask:0xf bank_mask:0xf
	v_fmac_f32_dpp v125, v103, v93 row_newbcast:13 row_mask:0xf bank_mask:0xf
	v_fmac_f32_dpp v124, v103, v94 row_newbcast:14 row_mask:0xf bank_mask:0xf
	v_fmac_f32_dpp v125, v103, v95 row_newbcast:15 row_mask:0xf bank_mask:0xf
	v_add_f32_e32 v130, v124, v125
	s_waitcnt lgkmcnt(0)
	ds_read2st64_b32 v[114:115], v14 offset0:91 offset1:94
	ds_read2st64_b32 v[116:117], v17 offset0:91 offset1:94
	ds_read_b32 v138, v15 offset:23040
	ds_read_b32 v139, v15 offset:23168
	ds_read_b32 v109, v16 offset:23040
	ds_read_b32 v118, v14 offset:23040
	ds_read_b32 v119, v14 offset:23168
	v_mul_f32_dpp v120, v110, v32 row_newbcast:0 row_mask:0xf bank_mask:0xf
	v_mul_f32_dpp v121, v110, v33 row_newbcast:1 row_mask:0xf bank_mask:0xf
	v_fmac_f32_dpp v120, v110, v34 row_newbcast:2 row_mask:0xf bank_mask:0xf
	v_fmac_f32_dpp v121, v110, v35 row_newbcast:3 row_mask:0xf bank_mask:0xf
	v_fmac_f32_dpp v120, v110, v36 row_newbcast:4 row_mask:0xf bank_mask:0xf
	v_fmac_f32_dpp v121, v110, v37 row_newbcast:5 row_mask:0xf bank_mask:0xf
	v_fmac_f32_dpp v120, v110, v38 row_newbcast:6 row_mask:0xf bank_mask:0xf
	v_fmac_f32_dpp v121, v110, v39 row_newbcast:7 row_mask:0xf bank_mask:0xf
	v_fmac_f32_dpp v120, v110, v40 row_newbcast:8 row_mask:0xf bank_mask:0xf
	v_fmac_f32_dpp v121, v110, v41 row_newbcast:9 row_mask:0xf bank_mask:0xf
	v_fmac_f32_dpp v120, v110, v42 row_newbcast:10 row_mask:0xf bank_mask:0xf
	v_fmac_f32_dpp v121, v110, v43 row_newbcast:11 row_mask:0xf bank_mask:0xf
	v_fmac_f32_dpp v120, v110, v44 row_newbcast:12 row_mask:0xf bank_mask:0xf
	v_fmac_f32_dpp v121, v110, v45 row_newbcast:13 row_mask:0xf bank_mask:0xf
	v_fmac_f32_dpp v120, v110, v46 row_newbcast:14 row_mask:0xf bank_mask:0xf
	v_fmac_f32_dpp v121, v110, v47 row_newbcast:15 row_mask:0xf bank_mask:0xf
	v_fmac_f32_dpp v120, v112, v48 row_newbcast:0 row_mask:0xf bank_mask:0xf
	v_fmac_f32_dpp v121, v112, v49 row_newbcast:1 row_mask:0xf bank_mask:0xf
	v_fmac_f32_dpp v120, v112, v50 row_newbcast:2 row_mask:0xf bank_mask:0xf
	v_fmac_f32_dpp v121, v112, v51 row_newbcast:3 row_mask:0xf bank_mask:0xf
	v_fmac_f32_dpp v120, v112, v52 row_newbcast:4 row_mask:0xf bank_mask:0xf
	v_fmac_f32_dpp v121, v112, v53 row_newbcast:5 row_mask:0xf bank_mask:0xf
	v_fmac_f32_dpp v120, v112, v54 row_newbcast:6 row_mask:0xf bank_mask:0xf
	v_fmac_f32_dpp v121, v112, v55 row_newbcast:7 row_mask:0xf bank_mask:0xf
	v_fmac_f32_dpp v120, v112, v56 row_newbcast:8 row_mask:0xf bank_mask:0xf
	v_fmac_f32_dpp v121, v112, v57 row_newbcast:9 row_mask:0xf bank_mask:0xf
	v_fmac_f32_dpp v120, v112, v58 row_newbcast:10 row_mask:0xf bank_mask:0xf
	v_fmac_f32_dpp v121, v112, v59 row_newbcast:11 row_mask:0xf bank_mask:0xf
	v_fmac_f32_dpp v120, v112, v60 row_newbcast:12 row_mask:0xf bank_mask:0xf
	v_fmac_f32_dpp v121, v112, v61 row_newbcast:13 row_mask:0xf bank_mask:0xf
	v_fmac_f32_dpp v120, v112, v62 row_newbcast:14 row_mask:0xf bank_mask:0xf
	v_fmac_f32_dpp v121, v112, v63 row_newbcast:15 row_mask:0xf bank_mask:0xf
	v_add_f32_e32 v128, v120, v121
	v_mul_f32_dpp v124, v105, v32 row_newbcast:0 row_mask:0xf bank_mask:0xf
	v_mul_f32_dpp v125, v105, v33 row_newbcast:1 row_mask:0xf bank_mask:0xf
	v_permlane32_swap_b32 v129, v128
	v_fmac_f32_dpp v124, v105, v34 row_newbcast:2 row_mask:0xf bank_mask:0xf
	v_fmac_f32_dpp v125, v105, v35 row_newbcast:3 row_mask:0xf bank_mask:0xf
	v_add_f32_dpp v108, -v129, -v128 quad_perm:[0,1,2,3] row_mask:0xc bank_mask:0xf
	v_fmac_f32_dpp v124, v105, v36 row_newbcast:4 row_mask:0xf bank_mask:0xf
	v_fmac_f32_dpp v125, v105, v37 row_newbcast:5 row_mask:0xf bank_mask:0xf
	v_mfma_f32_32x32x2_f32 v[64:79], v136, v108, v[32:47]
	v_fmac_f32_dpp v124, v105, v38 row_newbcast:6 row_mask:0xf bank_mask:0xf
	v_fmac_f32_dpp v125, v105, v39 row_newbcast:7 row_mask:0xf bank_mask:0xf
	v_fmac_f32_dpp v124, v105, v40 row_newbcast:8 row_mask:0xf bank_mask:0xf
	v_fmac_f32_dpp v125, v105, v41 row_newbcast:9 row_mask:0xf bank_mask:0xf
	v_fmac_f32_dpp v124, v105, v42 row_newbcast:10 row_mask:0xf bank_mask:0xf
	v_fmac_f32_dpp v125, v105, v43 row_newbcast:11 row_mask:0xf bank_mask:0xf
	v_fmac_f32_dpp v124, v105, v44 row_newbcast:12 row_mask:0xf bank_mask:0xf
	v_fmac_f32_dpp v125, v105, v45 row_newbcast:13 row_mask:0xf bank_mask:0xf
	v_fmac_f32_dpp v124, v105, v46 row_newbcast:14 row_mask:0xf bank_mask:0xf
	v_fmac_f32_dpp v125, v105, v47 row_newbcast:15 row_mask:0xf bank_mask:0xf
	v_fmac_f32_dpp v124, v107, v48 row_newbcast:0 row_mask:0xf bank_mask:0xf
	v_fmac_f32_dpp v125, v107, v49 row_newbcast:1 row_mask:0xf bank_mask:0xf
	v_fmac_f32_dpp v124, v107, v50 row_newbcast:2 row_mask:0xf bank_mask:0xf
	v_fmac_f32_dpp v125, v107, v51 row_newbcast:3 row_mask:0xf bank_mask:0xf
	v_mfma_f32_32x32x2_f32 v[80:95], v137, v108, v[48:63]
	v_fmac_f32_dpp v124, v107, v52 row_newbcast:4 row_mask:0xf bank_mask:0xf
	v_fmac_f32_dpp v125, v107, v53 row_newbcast:5 row_mask:0xf bank_mask:0xf
	v_fmac_f32_dpp v124, v107, v54 row_newbcast:6 row_mask:0xf bank_mask:0xf
	v_fmac_f32_dpp v125, v107, v55 row_newbcast:7 row_mask:0xf bank_mask:0xf
	v_fmac_f32_dpp v124, v107, v56 row_newbcast:8 row_mask:0xf bank_mask:0xf
	v_fmac_f32_dpp v125, v107, v57 row_newbcast:9 row_mask:0xf bank_mask:0xf
	v_fmac_f32_dpp v124, v107, v58 row_newbcast:10 row_mask:0xf bank_mask:0xf
	v_fmac_f32_dpp v125, v107, v59 row_newbcast:11 row_mask:0xf bank_mask:0xf
	v_fmac_f32_dpp v124, v107, v60 row_newbcast:12 row_mask:0xf bank_mask:0xf
	v_fmac_f32_dpp v125, v107, v61 row_newbcast:13 row_mask:0xf bank_mask:0xf
	v_fmac_f32_dpp v124, v107, v62 row_newbcast:14 row_mask:0xf bank_mask:0xf
	v_fmac_f32_dpp v125, v107, v63 row_newbcast:15 row_mask:0xf bank_mask:0xf
	v_add_f32_e32 v131, v124, v125
	s_nop 1
	v_permlane32_swap_b32 v130, v131
	v_add_f32_e32 v133, v130, v131
	v_cvt_pk_bf16_f32 v133, v133, v133
	global_store_short v13, v133, s[16:17]
	s_add_u32 s16, s16, s20
	s_addc_u32 s17, s17, s21
	s_waitcnt lgkmcnt(0)
	v_mul_f32_dpp v120, v114, v64 row_newbcast:0 row_mask:0xf bank_mask:0xf
	v_mul_f32_dpp v121, v114, v65 row_newbcast:1 row_mask:0xf bank_mask:0xf
	v_fmac_f32_dpp v120, v114, v66 row_newbcast:2 row_mask:0xf bank_mask:0xf
	v_fmac_f32_dpp v121, v114, v67 row_newbcast:3 row_mask:0xf bank_mask:0xf
	v_fmac_f32_dpp v120, v114, v68 row_newbcast:4 row_mask:0xf bank_mask:0xf
	v_fmac_f32_dpp v121, v114, v69 row_newbcast:5 row_mask:0xf bank_mask:0xf
	v_fmac_f32_dpp v120, v114, v70 row_newbcast:6 row_mask:0xf bank_mask:0xf
	v_fmac_f32_dpp v121, v114, v71 row_newbcast:7 row_mask:0xf bank_mask:0xf
	v_fmac_f32_dpp v120, v114, v72 row_newbcast:8 row_mask:0xf bank_mask:0xf
	v_fmac_f32_dpp v121, v114, v73 row_newbcast:9 row_mask:0xf bank_mask:0xf
	v_fmac_f32_dpp v120, v114, v74 row_newbcast:10 row_mask:0xf bank_mask:0xf
	v_fmac_f32_dpp v121, v114, v75 row_newbcast:11 row_mask:0xf bank_mask:0xf
	v_fmac_f32_dpp v120, v114, v76 row_newbcast:12 row_mask:0xf bank_mask:0xf
	v_fmac_f32_dpp v121, v114, v77 row_newbcast:13 row_mask:0xf bank_mask:0xf
	v_fmac_f32_dpp v120, v114, v78 row_newbcast:14 row_mask:0xf bank_mask:0xf
	v_fmac_f32_dpp v121, v114, v79 row_newbcast:15 row_mask:0xf bank_mask:0xf
	v_fmac_f32_dpp v120, v116, v80 row_newbcast:0 row_mask:0xf bank_mask:0xf
	v_fmac_f32_dpp v121, v116, v81 row_newbcast:1 row_mask:0xf bank_mask:0xf
	v_fmac_f32_dpp v120, v116, v82 row_newbcast:2 row_mask:0xf bank_mask:0xf
	v_fmac_f32_dpp v121, v116, v83 row_newbcast:3 row_mask:0xf bank_mask:0xf
	v_fmac_f32_dpp v120, v116, v84 row_newbcast:4 row_mask:0xf bank_mask:0xf
	v_fmac_f32_dpp v121, v116, v85 row_newbcast:5 row_mask:0xf bank_mask:0xf
	v_fmac_f32_dpp v120, v116, v86 row_newbcast:6 row_mask:0xf bank_mask:0xf
	v_fmac_f32_dpp v121, v116, v87 row_newbcast:7 row_mask:0xf bank_mask:0xf
	v_fmac_f32_dpp v120, v116, v88 row_newbcast:8 row_mask:0xf bank_mask:0xf
	v_fmac_f32_dpp v121, v116, v89 row_newbcast:9 row_mask:0xf bank_mask:0xf
	v_fmac_f32_dpp v120, v116, v90 row_newbcast:10 row_mask:0xf bank_mask:0xf
	v_fmac_f32_dpp v121, v116, v91 row_newbcast:11 row_mask:0xf bank_mask:0xf
	v_fmac_f32_dpp v120, v116, v92 row_newbcast:12 row_mask:0xf bank_mask:0xf
	v_fmac_f32_dpp v121, v116, v93 row_newbcast:13 row_mask:0xf bank_mask:0xf
	v_fmac_f32_dpp v120, v116, v94 row_newbcast:14 row_mask:0xf bank_mask:0xf
	v_fmac_f32_dpp v121, v116, v95 row_newbcast:15 row_mask:0xf bank_mask:0xf
	v_add_f32_e32 v128, v120, v121
	v_mul_f32_dpp v124, v111, v64 row_newbcast:0 row_mask:0xf bank_mask:0xf
	v_mul_f32_dpp v125, v111, v65 row_newbcast:1 row_mask:0xf bank_mask:0xf
	v_permlane32_swap_b32 v129, v128
	v_fmac_f32_dpp v124, v111, v66 row_newbcast:2 row_mask:0xf bank_mask:0xf
	v_fmac_f32_dpp v125, v111, v67 row_newbcast:3 row_mask:0xf bank_mask:0xf
	v_add_f32_dpp v109, -v129, -v128 quad_perm:[0,1,2,3] row_mask:0xc bank_mask:0xf
	v_fmac_f32_dpp v124, v111, v68 row_newbcast:4 row_mask:0xf bank_mask:0xf
	v_fmac_f32_dpp v125, v111, v69 row_newbcast:5 row_mask:0xf bank_mask:0xf
	v_mfma_f32_32x32x2_f32 v[32:47], v138, v109, v[64:79]
	v_fmac_f32_dpp v124, v111, v70 row_newbcast:6 row_mask:0xf bank_mask:0xf
	v_fmac_f32_dpp v125, v111, v71 row_newbcast:7 row_mask:0xf bank_mask:0xf
	v_fmac_f32_dpp v124, v111, v72 row_newbcast:8 row_mask:0xf bank_mask:0xf
	v_fmac_f32_dpp v125, v111, v73 row_newbcast:9 row_mask:0xf bank_mask:0xf
	v_fmac_f32_dpp v124, v111, v74 row_newbcast:10 row_mask:0xf bank_mask:0xf
	v_fmac_f32_dpp v125, v111, v75 row_newbcast:11 row_mask:0xf bank_mask:0xf
	v_fmac_f32_dpp v124, v111, v76 row_newbcast:12 row_mask:0xf bank_mask:0xf
	v_fmac_f32_dpp v125, v111, v77 row_newbcast:13 row_mask:0xf bank_mask:0xf
	v_fmac_f32_dpp v124, v111, v78 row_newbcast:14 row_mask:0xf bank_mask:0xf
	v_fmac_f32_dpp v125, v111, v79 row_newbcast:15 row_mask:0xf bank_mask:0xf
	v_fmac_f32_dpp v124, v113, v80 row_newbcast:0 row_mask:0xf bank_mask:0xf
	v_fmac_f32_dpp v125, v113, v81 row_newbcast:1 row_mask:0xf bank_mask:0xf
	v_fmac_f32_dpp v124, v113, v82 row_newbcast:2 row_mask:0xf bank_mask:0xf
; __device__ void scan_chain(PRef p, int l, int chain, ScanSm* sm) {
;     ...
; #pragma unroll 1
;     for (int c = 0; c < 144; c++) {
;       __syncthreads();
;       const ScanRec* rc0 = &sm->rec[c & 1][0];
;       LDSET(A, rc0)
; #pragma unroll 1
;       for (int i2 = 0; i2 < 8; i2++) {
;         const ScanRec* rcA = rc0 + 2 * i2;
;         const ScanRec* rcC = (i2 < 7) ? rcA + 2 : rcA + 1;
;         LDSET(B, rcA + 1)
;         SCAN_STEP(A, c * 16 + 2 * i2)
;         LDSET(A, rcC)
;         SCAN_STEP(B, c * 16 + 2 * i2 + 1)
;       }
;     }
	v_fmac_f32_dpp v125, v113, v83 row_newbcast:3 row_mask:0xf bank_mask:0xf
	v_mfma_f32_32x32x2_f32 v[48:63], v139, v109, v[80:95]
	v_fmac_f32_dpp v124, v113, v84 row_newbcast:4 row_mask:0xf bank_mask:0xf
	v_fmac_f32_dpp v125, v113, v85 row_newbcast:5 row_mask:0xf bank_mask:0xf
	v_fmac_f32_dpp v124, v113, v86 row_newbcast:6 row_mask:0xf bank_mask:0xf
	v_fmac_f32_dpp v125, v113, v87 row_newbcast:7 row_mask:0xf bank_mask:0xf
	v_fmac_f32_dpp v124, v113, v88 row_newbcast:8 row_mask:0xf bank_mask:0xf
	v_fmac_f32_dpp v125, v113, v89 row_newbcast:9 row_mask:0xf bank_mask:0xf
	v_fmac_f32_dpp v124, v113, v90 row_newbcast:10 row_mask:0xf bank_mask:0xf
	v_fmac_f32_dpp v125, v113, v91 row_newbcast:11 row_mask:0xf bank_mask:0xf
	v_fmac_f32_dpp v124, v113, v92 row_newbcast:12 row_mask:0xf bank_mask:0xf
	v_fmac_f32_dpp v125, v113, v93 row_newbcast:13 row_mask:0xf bank_mask:0xf
	v_fmac_f32_dpp v124, v113, v94 row_newbcast:14 row_mask:0xf bank_mask:0xf
	v_fmac_f32_dpp v125, v113, v95 row_newbcast:15 row_mask:0xf bank_mask:0xf
	v_add_f32_e32 v130, v124, v125
	v_mul_f32_dpp v124, v115, v32 row_newbcast:0 row_mask:0xf bank_mask:0xf
	v_mul_f32_dpp v125, v115, v33 row_newbcast:1 row_mask:0xf bank_mask:0xf
	v_fmac_f32_dpp v124, v115, v34 row_newbcast:2 row_mask:0xf bank_mask:0xf
	v_fmac_f32_dpp v125, v115, v35 row_newbcast:3 row_mask:0xf bank_mask:0xf
	v_fmac_f32_dpp v124, v115, v36 row_newbcast:4 row_mask:0xf bank_mask:0xf
	v_fmac_f32_dpp v125, v115, v37 row_newbcast:5 row_mask:0xf bank_mask:0xf
	v_fmac_f32_dpp v124, v115, v38 row_newbcast:6 row_mask:0xf bank_mask:0xf
	v_fmac_f32_dpp v125, v115, v39 row_newbcast:7 row_mask:0xf bank_mask:0xf
	v_fmac_f32_dpp v124, v115, v40 row_newbcast:8 row_mask:0xf bank_mask:0xf
	v_fmac_f32_dpp v125, v115, v41 row_newbcast:9 row_mask:0xf bank_mask:0xf
	v_fmac_f32_dpp v124, v115, v42 row_newbcast:10 row_mask:0xf bank_mask:0xf
	v_fmac_f32_dpp v125, v115, v43 row_newbcast:11 row_mask:0xf bank_mask:0xf
	v_fmac_f32_dpp v124, v115, v44 row_newbcast:12 row_mask:0xf bank_mask:0xf
	v_fmac_f32_dpp v125, v115, v45 row_newbcast:13 row_mask:0xf bank_mask:0xf
	v_fmac_f32_dpp v124, v115, v46 row_newbcast:14 row_mask:0xf bank_mask:0xf
	v_fmac_f32_dpp v125, v115, v47 row_newbcast:15 row_mask:0xf bank_mask:0xf
	v_fmac_f32_dpp v124, v117, v48 row_newbcast:0 row_mask:0xf bank_mask:0xf
	v_fmac_f32_dpp v125, v117, v49 row_newbcast:1 row_mask:0xf bank_mask:0xf
	v_fmac_f32_dpp v124, v117, v50 row_newbcast:2 row_mask:0xf bank_mask:0xf
	v_fmac_f32_dpp v125, v117, v51 row_newbcast:3 row_mask:0xf bank_mask:0xf
	v_fmac_f32_dpp v124, v117, v52 row_newbcast:4 row_mask:0xf bank_mask:0xf
	v_fmac_f32_dpp v125, v117, v53 row_newbcast:5 row_mask:0xf bank_mask:0xf
	v_fmac_f32_dpp v124, v117, v54 row_newbcast:6 row_mask:0xf bank_mask:0xf
	v_fmac_f32_dpp v125, v117, v55 row_newbcast:7 row_mask:0xf bank_mask:0xf
	v_fmac_f32_dpp v124, v117, v56 row_newbcast:8 row_mask:0xf bank_mask:0xf
	v_fmac_f32_dpp v125, v117, v57 row_newbcast:9 row_mask:0xf bank_mask:0xf
	v_fmac_f32_dpp v124, v117, v58 row_newbcast:10 row_mask:0xf bank_mask:0xf
	v_fmac_f32_dpp v125, v117, v59 row_newbcast:11 row_mask:0xf bank_mask:0xf
	v_fmac_f32_dpp v124, v117, v60 row_newbcast:12 row_mask:0xf bank_mask:0xf
	v_fmac_f32_dpp v125, v117, v61 row_newbcast:13 row_mask:0xf bank_mask:0xf
	v_fmac_f32_dpp v124, v117, v62 row_newbcast:14 row_mask:0xf bank_mask:0xf
	v_fmac_f32_dpp v125, v117, v63 row_newbcast:15 row_mask:0xf bank_mask:0xf
	v_add_f32_e32 v131, v124, v125
	s_nop 1
	v_permlane32_swap_b32 v130, v131
	v_add_f32_e32 v133, v130, v131
	v_cvt_pk_bf16_f32 v133, v133, v133
	global_store_short v13, v133, s[16:17]
	s_add_u32 s16, s16, s20
	s_addc_u32 s17, s17, s21
	v_mul_f32_dpp v32, v118, v32 row_newbcast:0 row_mask:0xf bank_mask:0xf
	v_mul_f32_dpp v33, v118, v33 row_newbcast:1 row_mask:0xf bank_mask:0xf
	v_mul_f32_dpp v34, v118, v34 row_newbcast:2 row_mask:0xf bank_mask:0xf
	v_mul_f32_dpp v35, v118, v35 row_newbcast:3 row_mask:0xf bank_mask:0xf
	v_mul_f32_dpp v36, v118, v36 row_newbcast:4 row_mask:0xf bank_mask:0xf
	v_mul_f32_dpp v37, v118, v37 row_newbcast:5 row_mask:0xf bank_mask:0xf
	v_mul_f32_dpp v38, v118, v38 row_newbcast:6 row_mask:0xf bank_mask:0xf
	v_mul_f32_dpp v39, v118, v39 row_newbcast:7 row_mask:0xf bank_mask:0xf
	v_mul_f32_dpp v40, v118, v40 row_newbcast:8 row_mask:0xf bank_mask:0xf
	v_mul_f32_dpp v41, v118, v41 row_newbcast:9 row_mask:0xf bank_mask:0xf
	v_mul_f32_dpp v42, v118, v42 row_newbcast:10 row_mask:0xf bank_mask:0xf
	v_mul_f32_dpp v43, v118, v43 row_newbcast:11 row_mask:0xf bank_mask:0xf
	v_mul_f32_dpp v44, v118, v44 row_newbcast:12 row_mask:0xf bank_mask:0xf
	v_mul_f32_dpp v45, v118, v45 row_newbcast:13 row_mask:0xf bank_mask:0xf
	v_mul_f32_dpp v46, v118, v46 row_newbcast:14 row_mask:0xf bank_mask:0xf
	v_mul_f32_dpp v47, v118, v47 row_newbcast:15 row_mask:0xf bank_mask:0xf
	v_mul_f32_dpp v48, v119, v48 row_newbcast:0 row_mask:0xf bank_mask:0xf
	v_mul_f32_dpp v49, v119, v49 row_newbcast:1 row_mask:0xf bank_mask:0xf
	v_mul_f32_dpp v50, v119, v50 row_newbcast:2 row_mask:0xf bank_mask:0xf
	v_mul_f32_dpp v51, v119, v51 row_newbcast:3 row_mask:0xf bank_mask:0xf
	v_mul_f32_dpp v52, v119, v52 row_newbcast:4 row_mask:0xf bank_mask:0xf
	v_mul_f32_dpp v53, v119, v53 row_newbcast:5 row_mask:0xf bank_mask:0xf
	v_mul_f32_dpp v54, v119, v54 row_newbcast:6 row_mask:0xf bank_mask:0xf
	v_mul_f32_dpp v55, v119, v55 row_newbcast:7 row_mask:0xf bank_mask:0xf
	v_mul_f32_dpp v56, v119, v56 row_newbcast:8 row_mask:0xf bank_mask:0xf
	v_mul_f32_dpp v57, v119, v57 row_newbcast:9 row_mask:0xf bank_mask:0xf
	v_mul_f32_dpp v58, v119, v58 row_newbcast:10 row_mask:0xf bank_mask:0xf
	v_mul_f32_dpp v59, v119, v59 row_newbcast:11 row_mask:0xf bank_mask:0xf
	v_mul_f32_dpp v60, v119, v60 row_newbcast:12 row_mask:0xf bank_mask:0xf
	v_mul_f32_dpp v61, v119, v61 row_newbcast:13 row_mask:0xf bank_mask:0xf
	v_mul_f32_dpp v62, v119, v62 row_newbcast:14 row_mask:0xf bank_mask:0xf
	v_mul_f32_dpp v63, v119, v63 row_newbcast:15 row_mask:0xf bank_mask:0xf
.Lscan_tail:
	s_add_i32 s15, s15, 1
	s_cmpk_lg_i32 s15, 0x90
	s_cbranch_scc1 .Lscan_chunk
	s_branch .LBB0_564
